# lever 4: GEMM K-loops - one static priority raise for the younger wave half (waves 4-7) per unit instead of hipcc's per-MFMA-block s_setprio toggling
# speedup vs baseline: 1.0043x; 1.0043x over previous
;     __host__ __device__ bool next(int i, Unit& u) const { Unit m; if (!S.next(i >> 1, m)) return false; u.pm = m.pm; u.pn = m.pn + 4 * (i & 1); return true; }
;     __host__ __device__ bool next(int i, Unit& u) const { Unit m; if (!S.next(i >> 1, m)) return false; u.pm = m.pm + (i & 1) * dpm; u.pn = m.pn + (i & 1) * dpn; return true; }
; #define PG8_STAGE(bufoff, gbase, voff) do { _Pragma("unroll") for (int _i = 0; _i < 2; ++_i) \
;         __builtin_amdgcn_global_load_lds((const unsigned*)((const char*)(gbase) + (voff)[_i]), (PG8_LAS unsigned*)(lds + (bufoff) + ldsw + _i * 8192), 16, 0, 0); } while (0)
; #define PG8_LDA(dst, b, h) do { _Pragma("unroll") for (int m = 0; m < 4; ++m) _Pragma("unroll") for (int k = 0; k < 2; ++k) dst[m][k] = *(const PG8_LAS bf16x8*)(lds + PG8_SA(b, h) + aoff + m * 2048 + k * 1024); } while (0)
; #define PG8_WAIT_V(n) asm volatile("s_waitcnt vmcnt(" #n ")" ::: "memory")
; #define PG8_WAIT_L(n) asm volatile("s_waitcnt lgkmcnt(" #n ")" ::: "memory")
; template <class Epi, class Sched, bool ALIGN_EPI = false, bool SP2 = false>
; __device__ __forceinline__ void gemm_phase(PG8_LAS unsigned char* lds, const Gemm g, const Sched& S, const Epi& E) {
;     ...
;         const bool has_next = S.next(ui + 1, nxt);
;         const char* nA = has_next ? (const char*)g.A + (size_t)nxt.pm * tstep : cA; const char* nB = has_next ? (const char*)g.Bt + (size_t)nxt.pn * tstep : cB;
;         for (int t = 0; t < nt; t += 2) {
;             const bool last = (t == nt - 2);
;             const char* a1 = cA + (size_t)(t + 1) * kstep;
;             const char* a2 = last ? nA : cA + (size_t)(t + 2) * kstep; const char* b2 = last ? nB : cB + (size_t)(t + 2) * kstep;
;             const char* a3 = a2 + kstep; const char* b3 = b2 + kstep;
;             if (last && has_next) S.a_ready(nxt);
;             if constexpr (SP2) {
;             PG8_LDB(B0, 0, 0); PG8_LDB(B1, 0, 1); PG8_SCHED; PG8_LDA(At, 0, 0); PG8_STAGE(PG8_SA(1, 1), a1 + hstep, voffA);
;             PG8_WAIT_V(8); PG8_WAIT_L(0); PG8_BAR; PG8_MMA(0, 0, At, B0); PG8_MMA(0, 1, At, B1); PG8_BAR; PG8_SCHED;
;             PG8_LDA(At, 0, 1); PG8_STAGE(PG8_SB(0, 0), b2, voffB); PG8_STAGE(PG8_SB(0, 1), b2 + hstep, voffB); PG8_STAGE(PG8_SA(0, 0), a2, voffA);
;             PG8_WAIT_V(8); PG8_WAIT_L(0); PG8_BAR; PG8_MMA(1, 0, At, B0); PG8_MMA(1, 1, At, B1); PG8_BAR; PG8_SCHED;
.LBB0_152:
	s_ashr_i32 s21, s20, 31
	s_lshl_b64 s[22:23], s[20:21], 19
	s_add_u32 s22, s38, s22
	s_addc_u32 s23, s39, s23
	s_and_b64 s[24:25], s[4:5], exec
	s_cselect_b32 s7, s23, s37
	s_cselect_b32 s21, s22, s36
	s_ashr_i32 s19, s18, 31
	s_lshl_b64 s[24:25], s[18:19], 19
	v_readlane_b32 s19, v255, 42
	s_add_u32 s24, s19, s24
	v_readlane_b32 s19, v255, 43
	s_addc_u32 s25, s19, s25
	s_and_b64 s[28:29], s[4:5], exec
	s_cselect_b32 s19, s25, s43
	s_cselect_b32 s28, s24, s42
	s_add_u32 s36, s36, 0x40080
	s_addc_u32 s37, s37, 0
	s_add_u32 s29, s42, 0x100
	s_addc_u32 s60, s43, 0
	s_mov_b32 s68, -2
	v_cmp_lt_u32_e32 vcc, 0xff, v212
	s_cbranch_vccz .Lgprio0
	s_setprio 1
.Lgprio0:
	s_add_u32 s42, s36, 0xfffc0080
	s_addc_u32 s43, s37, -1
	s_add_i32 s86, 0, 0x10000
	s_cmp_eq_u32 s68, 12
	s_cselect_b32 s45, s7, s43
	s_cselect_b32 s44, s21, s42
	s_cselect_b32 s43, s19, s60
	s_cselect_b32 s42, s28, s29
	s_add_i32 s90, 0, 0x14000
	v_add_u32_e32 v140, s86, v182
	v_add_u32_e32 v176, s90, v182
	ds_read_b128 v[128:131], v140
	ds_read_b128 v[132:135], v140 offset:1024
	ds_read_b128 v[136:139], v140 offset:2048
	ds_read_b128 v[140:143], v140 offset:3072
	ds_read_b128 v[144:147], v176
	ds_read_b128 v[148:151], v176 offset:1024
	ds_read_b128 v[172:175], v176 offset:2048
	ds_read_b128 v[176:179], v176 offset:3072
	v_lshl_add_u64 v[236:237], s[36:37], 0, v[166:167]
	s_add_i32 m0, s69, 0xc000
	ds_read_b128 v[192:195], v157
	ds_read_b128 v[196:199], v157 offset:1024
	ds_read_b128 v[200:203], v157 offset:2048
	ds_read_b128 v[204:207], v157 offset:3072
	ds_read_b128 v[208:211], v157 offset:4096
	ds_read_b128 v[224:227], v157 offset:5120
	ds_read_b128 v[228:231], v157 offset:6144
	ds_read_b128 v[232:235], v157 offset:7168
	global_load_lds_dwordx4 v[236:237], off
	v_lshl_add_u64 v[236:237], s[36:37], 0, v[168:169]
	s_add_i32 m0, s69, 0xe000
	s_nop 0
	global_load_lds_dwordx4 v[236:237], off
	s_waitcnt vmcnt(8)
	s_waitcnt lgkmcnt(0)
	s_barrier
	s_waitcnt lgkmcnt(0)
	v_mfma_f32_16x16x32_bf16 v[124:127], v[128:131], v[192:195], 0
	v_mfma_f32_16x16x32_bf16 v[120:123], v[136:139], v[192:195], 0
	v_mfma_f32_16x16x32_bf16 v[116:119], v[128:131], v[200:203], 0
	v_mfma_f32_16x16x32_bf16 v[108:111], v[136:139], v[200:203], 0
	v_mfma_f32_16x16x32_bf16 v[100:103], v[128:131], v[208:211], 0
	v_mfma_f32_16x16x32_bf16 v[92:95], v[136:139], v[208:211], 0
	v_mfma_f32_16x16x32_bf16 v[84:87], v[128:131], v[228:231], 0
	v_mfma_f32_16x16x32_bf16 v[76:79], v[136:139], v[228:231], 0
	v_mfma_f32_16x16x32_bf16 v[124:127], v[132:135], v[196:199], v[124:127]
	v_mfma_f32_16x16x32_bf16 v[120:123], v[140:143], v[196:199], v[120:123]
	v_mfma_f32_16x16x32_bf16 v[116:119], v[132:135], v[204:207], v[116:119]
	v_mfma_f32_16x16x32_bf16 v[108:111], v[140:143], v[204:207], v[108:111]
	v_mfma_f32_16x16x32_bf16 v[100:103], v[132:135], v[224:227], v[100:103]
	v_mfma_f32_16x16x32_bf16 v[92:95], v[140:143], v[224:227], v[92:95]
	v_mfma_f32_16x16x32_bf16 v[84:87], v[132:135], v[232:235], v[84:87]
	v_mfma_f32_16x16x32_bf16 v[76:79], v[140:143], v[232:235], v[76:79]
	v_mfma_f32_16x16x32_bf16 v[112:115], v[144:147], v[192:195], 0
	v_mfma_f32_16x16x32_bf16 v[104:107], v[172:175], v[192:195], 0
	v_mfma_f32_16x16x32_bf16 v[96:99], v[144:147], v[200:203], 0
	v_mfma_f32_16x16x32_bf16 v[88:91], v[172:175], v[200:203], 0
	v_mfma_f32_16x16x32_bf16 v[80:83], v[144:147], v[208:211], 0
	v_mfma_f32_16x16x32_bf16 v[72:75], v[172:175], v[208:211], 0
	v_mfma_f32_16x16x32_bf16 v[68:71], v[144:147], v[228:231], 0
	v_mfma_f32_16x16x32_bf16 v[64:67], v[172:175], v[228:231], 0
	v_mfma_f32_16x16x32_bf16 v[112:115], v[148:151], v[196:199], v[112:115]
	v_mfma_f32_16x16x32_bf16 v[104:107], v[176:179], v[196:199], v[104:107]
	v_mfma_f32_16x16x32_bf16 v[96:99], v[148:151], v[204:207], v[96:99]
	v_mfma_f32_16x16x32_bf16 v[88:91], v[176:179], v[204:207], v[88:91]
	v_mfma_f32_16x16x32_bf16 v[80:83], v[148:151], v[224:227], v[80:83]
	v_mfma_f32_16x16x32_bf16 v[72:75], v[176:179], v[224:227], v[72:75]
	v_mfma_f32_16x16x32_bf16 v[68:71], v[148:151], v[232:235], v[68:71]
	v_mfma_f32_16x16x32_bf16 v[64:67], v[176:179], v[232:235], v[64:67]
	s_barrier
	s_add_i32 s86, s86, s46
	v_lshl_add_u64 v[236:237], s[42:43], 0, v[154:155]
	s_mov_b32 m0, s86
	ds_read_b128 v[192:195], v157 offset:16384
	ds_read_b128 v[196:199], v157 offset:17408
	ds_read_b128 v[200:203], v157 offset:18432
	ds_read_b128 v[204:207], v157 offset:19456
	ds_read_b128 v[208:211], v157 offset:20480
	ds_read_b128 v[224:227], v157 offset:21504
	ds_read_b128 v[228:231], v157 offset:22528
	ds_read_b128 v[232:235], v157 offset:23552
	global_load_lds_dwordx4 v[236:237], off
	s_add_i32 m0, s86, 0x2000
	s_add_u32 s86, s42, 0x40000
	v_lshl_add_u64 v[238:239], s[42:43], 0, v[152:153]
	s_addc_u32 s87, s43, 0
	s_add_i32 s90, s90, s46
	global_load_lds_dwordx4 v[238:239], off
	v_lshl_add_u64 v[240:241], s[86:87], 0, v[154:155]
	s_mov_b32 m0, s90
	v_lshl_add_u64 v[242:243], s[44:45], 0, v[152:153]
	global_load_lds_dwordx4 v[240:241], off
	v_lshl_add_u64 v[240:241], s[86:87], 0, v[152:153]
	s_add_i32 m0, s90, 0x2000
	s_nop 0
	global_load_lds_dwordx4 v[240:241], off
	v_lshl_add_u64 v[240:241], s[44:45], 0, v[154:155]
	s_mov_b32 m0, s69
	s_nop 0
	global_load_lds_dwordx4 v[240:241], off
	s_mov_b32 m0, s70
	s_nop 0
	global_load_lds_dwordx4 v[242:243], off
	s_waitcnt vmcnt(8)
	s_waitcnt lgkmcnt(0)
	s_barrier
; #define PG8_STAGE(bufoff, gbase, voff) do { _Pragma("unroll") for (int _i = 0; _i < 2; ++_i) \
;         __builtin_amdgcn_global_load_lds((const unsigned*)((const char*)(gbase) + (voff)[_i]), (PG8_LAS unsigned*)(lds + (bufoff) + ldsw + _i * 8192), 16, 0, 0); } while (0)
; #define PG8_LDA(dst, b, h) do { _Pragma("unroll") for (int m = 0; m < 4; ++m) _Pragma("unroll") for (int k = 0; k < 2; ++k) dst[m][k] = *(const PG8_LAS bf16x8*)(lds + PG8_SA(b, h) + aoff + m * 2048 + k * 1024); } while (0)
; #define PG8_LDB(dst, b, h) do { _Pragma("unroll") for (int n = 0; n < 2; ++n) _Pragma("unroll") for (int k = 0; k < 2; ++k) dst[n][k] = *(const PG8_LAS bf16x8*)(lds + PG8_SB(b, h) + boff + n * 2048 + k * 1024); } while (0)
; #define PG8_MMA(ai, bj, At, Bt) do { __builtin_amdgcn_s_setprio(1); _Pragma("unroll") for (int m = 0; m < 4; ++m) _Pragma("unroll") for (int n = 0; n < 2; ++n) _Pragma("unroll") for (int k = 0; k < 2; ++k) \
;         acc[ai][bj][m][n] = __builtin_amdgcn_mfma_f32_16x16x32_bf16(Bt[n][k], At[m][k], acc[ai][bj][m][n], 0, 0, 0); __builtin_amdgcn_s_setprio(0); } while (0)
; #define PG8_WAIT_V(n) asm volatile("s_waitcnt vmcnt(" #n ")" ::: "memory")
; #define PG8_WAIT_L(n) asm volatile("s_waitcnt lgkmcnt(" #n ")" ::: "memory")
; #define PG8_BAR __builtin_amdgcn_s_barrier()
; #define PG8_SCHED __builtin_amdgcn_sched_barrier(0)
; template <class Epi, class Sched, bool ALIGN_EPI = false, bool SP2 = false>
; __device__ __forceinline__ void gemm_phase(PG8_LAS unsigned char* lds, const Gemm g, const Sched& S, const Epi& E) {
;     ...
;             PG8_WAIT_V(8); PG8_WAIT_L(0); PG8_BAR; PG8_MMA(1, 0, At, B0); PG8_MMA(1, 1, At, B1); PG8_BAR; PG8_SCHED;
;             PG8_LDB(B0, 1, 0); PG8_LDB(B1, 1, 1); PG8_SCHED; PG8_LDA(At, 1, 0); PG8_STAGE(PG8_SA(0, 1), a2 + hstep, voffA);
;             PG8_WAIT_V(8); PG8_WAIT_L(0); PG8_BAR; PG8_MMA(0, 0, At, B0); PG8_MMA(0, 1, At, B1); PG8_BAR; PG8_SCHED;
	s_waitcnt lgkmcnt(0)
	v_mfma_f32_16x16x32_bf16 v[60:63], v[128:131], v[192:195], 0
	v_mfma_f32_16x16x32_bf16 v[56:59], v[136:139], v[192:195], 0
	v_mfma_f32_16x16x32_bf16 v[52:55], v[128:131], v[200:203], 0
	v_mfma_f32_16x16x32_bf16 v[44:47], v[136:139], v[200:203], 0
	v_mfma_f32_16x16x32_bf16 v[36:39], v[128:131], v[208:211], 0
	v_mfma_f32_16x16x32_bf16 v[28:31], v[136:139], v[208:211], 0
	v_mfma_f32_16x16x32_bf16 v[20:23], v[128:131], v[228:231], 0
	v_mfma_f32_16x16x32_bf16 v[12:15], v[136:139], v[228:231], 0
	v_mfma_f32_16x16x32_bf16 v[60:63], v[132:135], v[196:199], v[60:63]
	v_mfma_f32_16x16x32_bf16 v[56:59], v[140:143], v[196:199], v[56:59]
	v_mfma_f32_16x16x32_bf16 v[52:55], v[132:135], v[204:207], v[52:55]
	v_mfma_f32_16x16x32_bf16 v[44:47], v[140:143], v[204:207], v[44:47]
	v_mfma_f32_16x16x32_bf16 v[36:39], v[132:135], v[224:227], v[36:39]
	v_mfma_f32_16x16x32_bf16 v[28:31], v[140:143], v[224:227], v[28:31]
	v_mfma_f32_16x16x32_bf16 v[20:23], v[132:135], v[232:235], v[20:23]
	v_mfma_f32_16x16x32_bf16 v[12:15], v[140:143], v[232:235], v[12:15]
	v_mfma_f32_16x16x32_bf16 v[48:51], v[144:147], v[192:195], 0
	v_mfma_f32_16x16x32_bf16 v[40:43], v[172:175], v[192:195], 0
	v_mfma_f32_16x16x32_bf16 v[32:35], v[144:147], v[200:203], 0
	v_mfma_f32_16x16x32_bf16 v[24:27], v[172:175], v[200:203], 0
	v_mfma_f32_16x16x32_bf16 v[16:19], v[144:147], v[208:211], 0
	v_mfma_f32_16x16x32_bf16 v[8:11], v[172:175], v[208:211], 0
	v_mfma_f32_16x16x32_bf16 v[4:7], v[144:147], v[228:231], 0
	v_mfma_f32_16x16x32_bf16 v[0:3], v[172:175], v[228:231], 0
	v_mfma_f32_16x16x32_bf16 v[48:51], v[148:151], v[196:199], v[48:51]
	v_mfma_f32_16x16x32_bf16 v[40:43], v[176:179], v[196:199], v[40:43]
	v_mfma_f32_16x16x32_bf16 v[32:35], v[148:151], v[204:207], v[32:35]
	v_mfma_f32_16x16x32_bf16 v[24:27], v[176:179], v[204:207], v[24:27]
	v_mfma_f32_16x16x32_bf16 v[16:19], v[148:151], v[224:227], v[16:19]
	v_mfma_f32_16x16x32_bf16 v[8:11], v[176:179], v[224:227], v[8:11]
	v_mfma_f32_16x16x32_bf16 v[4:7], v[148:151], v[232:235], v[4:7]
	v_mfma_f32_16x16x32_bf16 v[0:3], v[176:179], v[232:235], v[0:3]
	s_barrier
	s_add_i32 s86, 0, 0x18000
	s_add_i32 s87, 0, 0x1c000
	v_add_u32_e32 v140, s86, v182
	v_add_u32_e32 v176, s87, v182
	ds_read_b128 v[128:131], v140
	ds_read_b128 v[132:135], v140 offset:1024
	ds_read_b128 v[136:139], v140 offset:2048
	ds_read_b128 v[140:143], v140 offset:3072
	ds_read_b128 v[144:147], v176
	ds_read_b128 v[148:151], v176 offset:1024
	ds_read_b128 v[172:175], v176 offset:2048
	ds_read_b128 v[176:179], v176 offset:3072
	s_add_u32 s44, s44, 0x40000
	s_addc_u32 s45, s45, 0
	s_mov_b32 m0, s71
	v_lshl_add_u64 v[244:245], s[44:45], 0, v[154:155]
	ds_read_b128 v[192:195], v157 offset:32768
	ds_read_b128 v[196:199], v157 offset:33792
	ds_read_b128 v[200:203], v157 offset:34816
	ds_read_b128 v[204:207], v157 offset:35840
	ds_read_b128 v[208:211], v157 offset:36864
	ds_read_b128 v[224:227], v157 offset:37888
	ds_read_b128 v[228:231], v157 offset:38912
	ds_read_b128 v[232:235], v157 offset:39936
	global_load_lds_dwordx4 v[244:245], off
	v_lshl_add_u64 v[244:245], s[44:45], 0, v[152:153]
	s_mov_b32 m0, s72
	s_nop 0
	global_load_lds_dwordx4 v[244:245], off
	s_waitcnt vmcnt(8)
	s_waitcnt lgkmcnt(0)
	s_barrier
	s_waitcnt lgkmcnt(0)
	v_mfma_f32_16x16x32_bf16 v[124:127], v[128:131], v[192:195], v[124:127]
	v_mfma_f32_16x16x32_bf16 v[120:123], v[136:139], v[192:195], v[120:123]
	v_mfma_f32_16x16x32_bf16 v[116:119], v[128:131], v[200:203], v[116:119]
	v_mfma_f32_16x16x32_bf16 v[108:111], v[136:139], v[200:203], v[108:111]
	v_mfma_f32_16x16x32_bf16 v[100:103], v[128:131], v[208:211], v[100:103]
	v_mfma_f32_16x16x32_bf16 v[92:95], v[136:139], v[208:211], v[92:95]
	v_mfma_f32_16x16x32_bf16 v[84:87], v[128:131], v[228:231], v[84:87]
	v_mfma_f32_16x16x32_bf16 v[76:79], v[136:139], v[228:231], v[76:79]
	v_mfma_f32_16x16x32_bf16 v[124:127], v[132:135], v[196:199], v[124:127]
	v_mfma_f32_16x16x32_bf16 v[120:123], v[140:143], v[196:199], v[120:123]
	v_mfma_f32_16x16x32_bf16 v[116:119], v[132:135], v[204:207], v[116:119]
	v_mfma_f32_16x16x32_bf16 v[108:111], v[140:143], v[204:207], v[108:111]
	v_mfma_f32_16x16x32_bf16 v[100:103], v[132:135], v[224:227], v[100:103]
	v_mfma_f32_16x16x32_bf16 v[92:95], v[140:143], v[224:227], v[92:95]
	v_mfma_f32_16x16x32_bf16 v[84:87], v[132:135], v[232:235], v[84:87]
	v_mfma_f32_16x16x32_bf16 v[76:79], v[140:143], v[232:235], v[76:79]
	v_mfma_f32_16x16x32_bf16 v[112:115], v[144:147], v[192:195], v[112:115]
	v_mfma_f32_16x16x32_bf16 v[104:107], v[172:175], v[192:195], v[104:107]
	v_mfma_f32_16x16x32_bf16 v[96:99], v[144:147], v[200:203], v[96:99]
	v_mfma_f32_16x16x32_bf16 v[88:91], v[172:175], v[200:203], v[88:91]
	v_mfma_f32_16x16x32_bf16 v[80:83], v[144:147], v[208:211], v[80:83]
	v_mfma_f32_16x16x32_bf16 v[72:75], v[172:175], v[208:211], v[72:75]
	v_mfma_f32_16x16x32_bf16 v[68:71], v[144:147], v[228:231], v[68:71]
	v_mfma_f32_16x16x32_bf16 v[64:67], v[172:175], v[228:231], v[64:67]
	v_mfma_f32_16x16x32_bf16 v[112:115], v[148:151], v[196:199], v[112:115]
	v_mfma_f32_16x16x32_bf16 v[104:107], v[176:179], v[196:199], v[104:107]
	v_mfma_f32_16x16x32_bf16 v[96:99], v[148:151], v[204:207], v[96:99]
	v_mfma_f32_16x16x32_bf16 v[88:91], v[176:179], v[204:207], v[88:91]
	v_mfma_f32_16x16x32_bf16 v[80:83], v[148:151], v[224:227], v[80:83]
	v_mfma_f32_16x16x32_bf16 v[72:75], v[176:179], v[224:227], v[72:75]
	v_mfma_f32_16x16x32_bf16 v[68:71], v[148:151], v[232:235], v[68:71]
	v_mfma_f32_16x16x32_bf16 v[64:67], v[176:179], v[232:235], v[64:67]
	s_barrier
; #define PG8_STAGE(bufoff, gbase, voff) do { _Pragma("unroll") for (int _i = 0; _i < 2; ++_i) \
;         __builtin_amdgcn_global_load_lds((const unsigned*)((const char*)(gbase) + (voff)[_i]), (PG8_LAS unsigned*)(lds + (bufoff) + ldsw + _i * 8192), 16, 0, 0); } while (0)
; #define PG8_LDA(dst, b, h) do { _Pragma("unroll") for (int m = 0; m < 4; ++m) _Pragma("unroll") for (int k = 0; k < 2; ++k) dst[m][k] = *(const PG8_LAS bf16x8*)(lds + PG8_SA(b, h) + aoff + m * 2048 + k * 1024); } while (0)
; #define PG8_LDB(dst, b, h) do { _Pragma("unroll") for (int n = 0; n < 2; ++n) _Pragma("unroll") for (int k = 0; k < 2; ++k) dst[n][k] = *(const PG8_LAS bf16x8*)(lds + PG8_SB(b, h) + boff + n * 2048 + k * 1024); } while (0)
; #define PG8_MMA(ai, bj, At, Bt) do { __builtin_amdgcn_s_setprio(1); _Pragma("unroll") for (int m = 0; m < 4; ++m) _Pragma("unroll") for (int n = 0; n < 2; ++n) _Pragma("unroll") for (int k = 0; k < 2; ++k) \
;         acc[ai][bj][m][n] = __builtin_amdgcn_mfma_f32_16x16x32_bf16(Bt[n][k], At[m][k], acc[ai][bj][m][n], 0, 0, 0); __builtin_amdgcn_s_setprio(0); } while (0)
; #define PG8_WAIT_V(n) asm volatile("s_waitcnt vmcnt(" #n ")" ::: "memory")
; #define PG8_WAIT_L(n) asm volatile("s_waitcnt lgkmcnt(" #n ")" ::: "memory")
; #define PG8_BAR __builtin_amdgcn_s_barrier()
; #define PG8_SCHED __builtin_amdgcn_sched_barrier(0)
; template <class Epi, class Sched, bool ALIGN_EPI = false, bool SP2 = false>
; __device__ __forceinline__ void gemm_phase(PG8_LAS unsigned char* lds, const Gemm g, const Sched& S, const Epi& E) {
;     ...
;             PG8_LDB(B0, 0, 0); PG8_LDB(B1, 0, 1); PG8_SCHED; PG8_LDA(At, 0, 0); PG8_STAGE(PG8_SA(1, 1), a1 + hstep, voffA);
;             PG8_WAIT_V(8); PG8_WAIT_L(0); PG8_BAR; PG8_MMA(0, 0, At, B0); PG8_MMA(0, 1, At, B1); PG8_BAR; PG8_SCHED;
;     ...
;             PG8_LDA(At, 1, 1); PG8_STAGE(PG8_SB(1, 0), b3, voffB); PG8_STAGE(PG8_SB(1, 1), b3 + hstep, voffB); PG8_STAGE(PG8_SA(1, 0), a3, voffA);
;             PG8_WAIT_V(8); PG8_WAIT_L(0); PG8_BAR; PG8_MMA(1, 0, At, B0); PG8_MMA(1, 1, At, B1); PG8_BAR; PG8_SCHED;
	s_add_i32 s44, s86, s46
	v_lshl_add_u64 v[236:237], v[236:237], 0, s[30:31]
	s_mov_b32 m0, s44
	ds_read_b128 v[192:195], v157 offset:49152
	ds_read_b128 v[196:199], v157 offset:50176
	ds_read_b128 v[200:203], v157 offset:51200
	ds_read_b128 v[204:207], v157 offset:52224
	ds_read_b128 v[208:211], v157 offset:53248
	ds_read_b128 v[224:227], v157 offset:54272
	ds_read_b128 v[228:231], v157 offset:55296
	ds_read_b128 v[232:235], v157 offset:56320
	global_load_lds_dwordx4 v[236:237], off
	s_add_i32 m0, s44, 0x2000
	s_add_u32 s42, s42, 0x40080
	v_lshl_add_u64 v[236:237], v[238:239], 0, s[30:31]
	s_addc_u32 s43, s43, 0
	s_add_i32 s44, s87, s46
	global_load_lds_dwordx4 v[236:237], off
	v_lshl_add_u64 v[236:237], s[42:43], 0, v[154:155]
	s_mov_b32 m0, s44
	s_nop 0
	global_load_lds_dwordx4 v[236:237], off
	v_lshl_add_u64 v[236:237], s[42:43], 0, v[152:153]
	s_add_i32 m0, s44, 0x2000
	s_nop 0
	global_load_lds_dwordx4 v[236:237], off
	v_lshl_add_u64 v[236:237], v[240:241], 0, s[30:31]
	s_mov_b32 m0, s77
	s_nop 0
	global_load_lds_dwordx4 v[236:237], off
	v_lshl_add_u64 v[236:237], v[242:243], 0, s[30:31]
	s_mov_b32 m0, s78
	s_nop 0
	global_load_lds_dwordx4 v[236:237], off
	s_waitcnt vmcnt(8)
	s_waitcnt lgkmcnt(0)
	s_barrier
	s_waitcnt lgkmcnt(0)
	v_mfma_f32_16x16x32_bf16 v[60:63], v[128:131], v[192:195], v[60:63]
	v_mfma_f32_16x16x32_bf16 v[56:59], v[136:139], v[192:195], v[56:59]
	v_mfma_f32_16x16x32_bf16 v[52:55], v[128:131], v[200:203], v[52:55]
	v_mfma_f32_16x16x32_bf16 v[44:47], v[136:139], v[200:203], v[44:47]
	v_mfma_f32_16x16x32_bf16 v[36:39], v[128:131], v[208:211], v[36:39]
	v_mfma_f32_16x16x32_bf16 v[28:31], v[136:139], v[208:211], v[28:31]
	v_mfma_f32_16x16x32_bf16 v[20:23], v[128:131], v[228:231], v[20:23]
	v_mfma_f32_16x16x32_bf16 v[12:15], v[136:139], v[228:231], v[12:15]
	v_mfma_f32_16x16x32_bf16 v[60:63], v[132:135], v[196:199], v[60:63]
	v_mfma_f32_16x16x32_bf16 v[56:59], v[140:143], v[196:199], v[56:59]
	v_mfma_f32_16x16x32_bf16 v[52:55], v[132:135], v[204:207], v[52:55]
	v_mfma_f32_16x16x32_bf16 v[44:47], v[140:143], v[204:207], v[44:47]
	v_mfma_f32_16x16x32_bf16 v[36:39], v[132:135], v[224:227], v[36:39]
	v_mfma_f32_16x16x32_bf16 v[28:31], v[140:143], v[224:227], v[28:31]
	v_mfma_f32_16x16x32_bf16 v[20:23], v[132:135], v[232:235], v[20:23]
	v_mfma_f32_16x16x32_bf16 v[12:15], v[140:143], v[232:235], v[12:15]
	v_mfma_f32_16x16x32_bf16 v[48:51], v[144:147], v[192:195], v[48:51]
	v_mfma_f32_16x16x32_bf16 v[40:43], v[172:175], v[192:195], v[40:43]
	v_mfma_f32_16x16x32_bf16 v[32:35], v[144:147], v[200:203], v[32:35]
	v_mfma_f32_16x16x32_bf16 v[24:27], v[172:175], v[200:203], v[24:27]
	v_mfma_f32_16x16x32_bf16 v[16:19], v[144:147], v[208:211], v[16:19]
	v_mfma_f32_16x16x32_bf16 v[8:11], v[172:175], v[208:211], v[8:11]
	v_mfma_f32_16x16x32_bf16 v[4:7], v[144:147], v[228:231], v[4:7]
	v_mfma_f32_16x16x32_bf16 v[0:3], v[172:175], v[228:231], v[0:3]
	v_mfma_f32_16x16x32_bf16 v[48:51], v[148:151], v[196:199], v[48:51]
	v_mfma_f32_16x16x32_bf16 v[40:43], v[176:179], v[196:199], v[40:43]
	v_mfma_f32_16x16x32_bf16 v[32:35], v[148:151], v[204:207], v[32:35]
	v_mfma_f32_16x16x32_bf16 v[24:27], v[176:179], v[204:207], v[24:27]
	v_mfma_f32_16x16x32_bf16 v[16:19], v[148:151], v[224:227], v[16:19]
	v_mfma_f32_16x16x32_bf16 v[8:11], v[176:179], v[224:227], v[8:11]
	v_mfma_f32_16x16x32_bf16 v[4:7], v[148:151], v[232:235], v[4:7]
	v_mfma_f32_16x16x32_bf16 v[0:3], v[176:179], v[232:235], v[0:3]
	s_barrier
	s_add_i32 s68, s68, 2
	s_add_u32 s36, s36, 0x100
	s_addc_u32 s37, s37, 0
	s_add_u32 s29, s29, 0x100
	s_addc_u32 s60, s60, 0
	s_cmp_gt_u32 s68, 13
	s_cbranch_scc0 .LBB0_153
	s_branch .Lgzero0_done
.LBB0_153:
	s_add_u32 s42, s36, 0xfffc0080
	s_addc_u32 s43, s37, -1
	s_add_i32 s86, 0, 0x10000
	s_cmp_eq_u32 s68, 12
	s_cselect_b32 s45, s7, s43
	s_cselect_b32 s44, s21, s42
	s_cselect_b32 s43, s19, s60
	s_cselect_b32 s42, s28, s29
	s_add_i32 s90, 0, 0x14000
	v_add_u32_e32 v140, s86, v182
	v_add_u32_e32 v176, s90, v182
	ds_read_b128 v[128:131], v140
	ds_read_b128 v[132:135], v140 offset:1024
	ds_read_b128 v[136:139], v140 offset:2048
	ds_read_b128 v[140:143], v140 offset:3072
	ds_read_b128 v[144:147], v176
	ds_read_b128 v[148:151], v176 offset:1024
	ds_read_b128 v[172:175], v176 offset:2048
	ds_read_b128 v[176:179], v176 offset:3072
	v_lshl_add_u64 v[236:237], s[36:37], 0, v[166:167]
	s_add_i32 m0, s69, 0xc000
	ds_read_b128 v[192:195], v157
	ds_read_b128 v[196:199], v157 offset:1024
	ds_read_b128 v[200:203], v157 offset:2048
	ds_read_b128 v[204:207], v157 offset:3072
	ds_read_b128 v[208:211], v157 offset:4096
	ds_read_b128 v[224:227], v157 offset:5120
	ds_read_b128 v[228:231], v157 offset:6144
	ds_read_b128 v[232:235], v157 offset:7168
	global_load_lds_dwordx4 v[236:237], off
	v_lshl_add_u64 v[236:237], s[36:37], 0, v[168:169]
	s_add_i32 m0, s69, 0xe000
	s_nop 0
	global_load_lds_dwordx4 v[236:237], off
	s_waitcnt vmcnt(8)
	s_waitcnt lgkmcnt(0)
	s_barrier
; #define PG8_STAGE(bufoff, gbase, voff) do { _Pragma("unroll") for (int _i = 0; _i < 2; ++_i) \
;         __builtin_amdgcn_global_load_lds((const unsigned*)((const char*)(gbase) + (voff)[_i]), (PG8_LAS unsigned*)(lds + (bufoff) + ldsw + _i * 8192), 16, 0, 0); } while (0)
; #define PG8_LDA(dst, b, h) do { _Pragma("unroll") for (int m = 0; m < 4; ++m) _Pragma("unroll") for (int k = 0; k < 2; ++k) dst[m][k] = *(const PG8_LAS bf16x8*)(lds + PG8_SA(b, h) + aoff + m * 2048 + k * 1024); } while (0)
; #define PG8_MMA(ai, bj, At, Bt) do { __builtin_amdgcn_s_setprio(1); _Pragma("unroll") for (int m = 0; m < 4; ++m) _Pragma("unroll") for (int n = 0; n < 2; ++n) _Pragma("unroll") for (int k = 0; k < 2; ++k) \
;         acc[ai][bj][m][n] = __builtin_amdgcn_mfma_f32_16x16x32_bf16(Bt[n][k], At[m][k], acc[ai][bj][m][n], 0, 0, 0); __builtin_amdgcn_s_setprio(0); } while (0)
; #define PG8_WAIT_V(n) asm volatile("s_waitcnt vmcnt(" #n ")" ::: "memory")
; #define PG8_WAIT_L(n) asm volatile("s_waitcnt lgkmcnt(" #n ")" ::: "memory")
; #define PG8_BAR __builtin_amdgcn_s_barrier()
; #define PG8_SCHED __builtin_amdgcn_sched_barrier(0)
; template <class Epi, class Sched, bool ALIGN_EPI = false, bool SP2 = false>
; __device__ __forceinline__ void gemm_phase(PG8_LAS unsigned char* lds, const Gemm g, const Sched& S, const Epi& E) {
;     ...
;             PG8_WAIT_V(8); PG8_WAIT_L(0); PG8_BAR; PG8_MMA(0, 0, At, B0); PG8_MMA(0, 1, At, B1); PG8_BAR; PG8_SCHED;
;             PG8_LDA(At, 0, 1); PG8_STAGE(PG8_SB(0, 0), b2, voffB); PG8_STAGE(PG8_SB(0, 1), b2 + hstep, voffB); PG8_STAGE(PG8_SA(0, 0), a2, voffA);
;             PG8_WAIT_V(8); PG8_WAIT_L(0); PG8_BAR; PG8_MMA(1, 0, At, B0); PG8_MMA(1, 1, At, B1); PG8_BAR; PG8_SCHED;
	s_waitcnt lgkmcnt(0)
	v_mfma_f32_16x16x32_bf16 v[124:127], v[128:131], v[192:195], v[124:127]
	v_mfma_f32_16x16x32_bf16 v[120:123], v[136:139], v[192:195], v[120:123]
	v_mfma_f32_16x16x32_bf16 v[116:119], v[128:131], v[200:203], v[116:119]
	v_mfma_f32_16x16x32_bf16 v[108:111], v[136:139], v[200:203], v[108:111]
	v_mfma_f32_16x16x32_bf16 v[100:103], v[128:131], v[208:211], v[100:103]
	v_mfma_f32_16x16x32_bf16 v[92:95], v[136:139], v[208:211], v[92:95]
	v_mfma_f32_16x16x32_bf16 v[84:87], v[128:131], v[228:231], v[84:87]
	v_mfma_f32_16x16x32_bf16 v[76:79], v[136:139], v[228:231], v[76:79]
	v_mfma_f32_16x16x32_bf16 v[124:127], v[132:135], v[196:199], v[124:127]
	v_mfma_f32_16x16x32_bf16 v[120:123], v[140:143], v[196:199], v[120:123]
	v_mfma_f32_16x16x32_bf16 v[116:119], v[132:135], v[204:207], v[116:119]
	v_mfma_f32_16x16x32_bf16 v[108:111], v[140:143], v[204:207], v[108:111]
	v_mfma_f32_16x16x32_bf16 v[100:103], v[132:135], v[224:227], v[100:103]
	v_mfma_f32_16x16x32_bf16 v[92:95], v[140:143], v[224:227], v[92:95]
	v_mfma_f32_16x16x32_bf16 v[84:87], v[132:135], v[232:235], v[84:87]
	v_mfma_f32_16x16x32_bf16 v[76:79], v[140:143], v[232:235], v[76:79]
	v_mfma_f32_16x16x32_bf16 v[112:115], v[144:147], v[192:195], v[112:115]
	v_mfma_f32_16x16x32_bf16 v[104:107], v[172:175], v[192:195], v[104:107]
	v_mfma_f32_16x16x32_bf16 v[96:99], v[144:147], v[200:203], v[96:99]
	v_mfma_f32_16x16x32_bf16 v[88:91], v[172:175], v[200:203], v[88:91]
	v_mfma_f32_16x16x32_bf16 v[80:83], v[144:147], v[208:211], v[80:83]
	v_mfma_f32_16x16x32_bf16 v[72:75], v[172:175], v[208:211], v[72:75]
	v_mfma_f32_16x16x32_bf16 v[68:71], v[144:147], v[228:231], v[68:71]
	v_mfma_f32_16x16x32_bf16 v[64:67], v[172:175], v[228:231], v[64:67]
	v_mfma_f32_16x16x32_bf16 v[112:115], v[148:151], v[196:199], v[112:115]
	v_mfma_f32_16x16x32_bf16 v[104:107], v[176:179], v[196:199], v[104:107]
	v_mfma_f32_16x16x32_bf16 v[96:99], v[148:151], v[204:207], v[96:99]
	v_mfma_f32_16x16x32_bf16 v[88:91], v[176:179], v[204:207], v[88:91]
	v_mfma_f32_16x16x32_bf16 v[80:83], v[148:151], v[224:227], v[80:83]
	v_mfma_f32_16x16x32_bf16 v[72:75], v[176:179], v[224:227], v[72:75]
	v_mfma_f32_16x16x32_bf16 v[68:71], v[148:151], v[232:235], v[68:71]
	v_mfma_f32_16x16x32_bf16 v[64:67], v[176:179], v[232:235], v[64:67]
	s_barrier
	s_add_i32 s86, s86, s46
	v_lshl_add_u64 v[236:237], s[42:43], 0, v[154:155]
	s_mov_b32 m0, s86
	ds_read_b128 v[192:195], v157 offset:16384
	ds_read_b128 v[196:199], v157 offset:17408
	ds_read_b128 v[200:203], v157 offset:18432
	ds_read_b128 v[204:207], v157 offset:19456
	ds_read_b128 v[208:211], v157 offset:20480
	ds_read_b128 v[224:227], v157 offset:21504
	ds_read_b128 v[228:231], v157 offset:22528
	ds_read_b128 v[232:235], v157 offset:23552
	global_load_lds_dwordx4 v[236:237], off
	s_add_i32 m0, s86, 0x2000
	s_add_u32 s86, s42, 0x40000
	v_lshl_add_u64 v[238:239], s[42:43], 0, v[152:153]
	s_addc_u32 s87, s43, 0
	s_add_i32 s90, s90, s46
	global_load_lds_dwordx4 v[238:239], off
	v_lshl_add_u64 v[240:241], s[86:87], 0, v[154:155]
	s_mov_b32 m0, s90
	v_lshl_add_u64 v[242:243], s[44:45], 0, v[152:153]
	global_load_lds_dwordx4 v[240:241], off
	v_lshl_add_u64 v[240:241], s[86:87], 0, v[152:153]
	s_add_i32 m0, s90, 0x2000
	s_nop 0
	global_load_lds_dwordx4 v[240:241], off
	v_lshl_add_u64 v[240:241], s[44:45], 0, v[154:155]
	s_mov_b32 m0, s69
	s_nop 0
	global_load_lds_dwordx4 v[240:241], off
	s_mov_b32 m0, s70
	s_nop 0
	global_load_lds_dwordx4 v[242:243], off
	s_waitcnt vmcnt(8)
	s_waitcnt lgkmcnt(0)
	s_barrier
	s_waitcnt lgkmcnt(0)
	v_mfma_f32_16x16x32_bf16 v[60:63], v[128:131], v[192:195], v[60:63]
	v_mfma_f32_16x16x32_bf16 v[56:59], v[136:139], v[192:195], v[56:59]
	v_mfma_f32_16x16x32_bf16 v[52:55], v[128:131], v[200:203], v[52:55]
	v_mfma_f32_16x16x32_bf16 v[44:47], v[136:139], v[200:203], v[44:47]
	v_mfma_f32_16x16x32_bf16 v[36:39], v[128:131], v[208:211], v[36:39]
	v_mfma_f32_16x16x32_bf16 v[28:31], v[136:139], v[208:211], v[28:31]
	v_mfma_f32_16x16x32_bf16 v[20:23], v[128:131], v[228:231], v[20:23]
	v_mfma_f32_16x16x32_bf16 v[12:15], v[136:139], v[228:231], v[12:15]
	v_mfma_f32_16x16x32_bf16 v[60:63], v[132:135], v[196:199], v[60:63]
	v_mfma_f32_16x16x32_bf16 v[56:59], v[140:143], v[196:199], v[56:59]
	v_mfma_f32_16x16x32_bf16 v[52:55], v[132:135], v[204:207], v[52:55]
	v_mfma_f32_16x16x32_bf16 v[44:47], v[140:143], v[204:207], v[44:47]
	v_mfma_f32_16x16x32_bf16 v[36:39], v[132:135], v[224:227], v[36:39]
	v_mfma_f32_16x16x32_bf16 v[28:31], v[140:143], v[224:227], v[28:31]
	v_mfma_f32_16x16x32_bf16 v[20:23], v[132:135], v[232:235], v[20:23]
	v_mfma_f32_16x16x32_bf16 v[12:15], v[140:143], v[232:235], v[12:15]
	v_mfma_f32_16x16x32_bf16 v[48:51], v[144:147], v[192:195], v[48:51]
	v_mfma_f32_16x16x32_bf16 v[40:43], v[172:175], v[192:195], v[40:43]
	v_mfma_f32_16x16x32_bf16 v[32:35], v[144:147], v[200:203], v[32:35]
	v_mfma_f32_16x16x32_bf16 v[24:27], v[172:175], v[200:203], v[24:27]
	v_mfma_f32_16x16x32_bf16 v[16:19], v[144:147], v[208:211], v[16:19]
	v_mfma_f32_16x16x32_bf16 v[8:11], v[172:175], v[208:211], v[8:11]
	v_mfma_f32_16x16x32_bf16 v[4:7], v[144:147], v[228:231], v[4:7]
	v_mfma_f32_16x16x32_bf16 v[0:3], v[172:175], v[228:231], v[0:3]
	v_mfma_f32_16x16x32_bf16 v[48:51], v[148:151], v[196:199], v[48:51]
	v_mfma_f32_16x16x32_bf16 v[40:43], v[176:179], v[196:199], v[40:43]
	v_mfma_f32_16x16x32_bf16 v[32:35], v[148:151], v[204:207], v[32:35]
	v_mfma_f32_16x16x32_bf16 v[24:27], v[176:179], v[204:207], v[24:27]
	v_mfma_f32_16x16x32_bf16 v[16:19], v[148:151], v[224:227], v[16:19]
	v_mfma_f32_16x16x32_bf16 v[8:11], v[176:179], v[224:227], v[8:11]
	v_mfma_f32_16x16x32_bf16 v[4:7], v[148:151], v[232:235], v[4:7]
	v_mfma_f32_16x16x32_bf16 v[0:3], v[176:179], v[232:235], v[0:3]
	s_barrier
; #define PG8_STAGE(bufoff, gbase, voff) do { _Pragma("unroll") for (int _i = 0; _i < 2; ++_i) \
;         __builtin_amdgcn_global_load_lds((const unsigned*)((const char*)(gbase) + (voff)[_i]), (PG8_LAS unsigned*)(lds + (bufoff) + ldsw + _i * 8192), 16, 0, 0); } while (0)
; #define PG8_LDA(dst, b, h) do { _Pragma("unroll") for (int m = 0; m < 4; ++m) _Pragma("unroll") for (int k = 0; k < 2; ++k) dst[m][k] = *(const PG8_LAS bf16x8*)(lds + PG8_SA(b, h) + aoff + m * 2048 + k * 1024); } while (0)
; #define PG8_LDB(dst, b, h) do { _Pragma("unroll") for (int n = 0; n < 2; ++n) _Pragma("unroll") for (int k = 0; k < 2; ++k) dst[n][k] = *(const PG8_LAS bf16x8*)(lds + PG8_SB(b, h) + boff + n * 2048 + k * 1024); } while (0)
; #define PG8_MMA(ai, bj, At, Bt) do { __builtin_amdgcn_s_setprio(1); _Pragma("unroll") for (int m = 0; m < 4; ++m) _Pragma("unroll") for (int n = 0; n < 2; ++n) _Pragma("unroll") for (int k = 0; k < 2; ++k) \
;         acc[ai][bj][m][n] = __builtin_amdgcn_mfma_f32_16x16x32_bf16(Bt[n][k], At[m][k], acc[ai][bj][m][n], 0, 0, 0); __builtin_amdgcn_s_setprio(0); } while (0)
; #define PG8_WAIT_V(n) asm volatile("s_waitcnt vmcnt(" #n ")" ::: "memory")
; #define PG8_WAIT_L(n) asm volatile("s_waitcnt lgkmcnt(" #n ")" ::: "memory")
; #define PG8_BAR __builtin_amdgcn_s_barrier()
; #define PG8_SCHED __builtin_amdgcn_sched_barrier(0)
; template <class Epi, class Sched, bool ALIGN_EPI = false, bool SP2 = false>
; __device__ __forceinline__ void gemm_phase(PG8_LAS unsigned char* lds, const Gemm g, const Sched& S, const Epi& E) {
;     ...
;             PG8_LDB(B0, 1, 0); PG8_LDB(B1, 1, 1); PG8_SCHED; PG8_LDA(At, 1, 0); PG8_STAGE(PG8_SA(0, 1), a2 + hstep, voffA);
;             PG8_WAIT_V(8); PG8_WAIT_L(0); PG8_BAR; PG8_MMA(0, 0, At, B0); PG8_MMA(0, 1, At, B1); PG8_BAR; PG8_SCHED;
;             PG8_LDA(At, 1, 1); PG8_STAGE(PG8_SB(1, 0), b3, voffB); PG8_STAGE(PG8_SB(1, 1), b3 + hstep, voffB); PG8_STAGE(PG8_SA(1, 0), a3, voffA);
;             PG8_WAIT_V(8); PG8_WAIT_L(0); PG8_BAR; PG8_MMA(1, 0, At, B0); PG8_MMA(1, 1, At, B1); PG8_BAR; PG8_SCHED;
	s_add_i32 s86, 0, 0x18000
	s_add_i32 s87, 0, 0x1c000
	v_add_u32_e32 v140, s86, v182
	v_add_u32_e32 v176, s87, v182
	ds_read_b128 v[128:131], v140
	ds_read_b128 v[132:135], v140 offset:1024
	ds_read_b128 v[136:139], v140 offset:2048
	ds_read_b128 v[140:143], v140 offset:3072
	ds_read_b128 v[144:147], v176
	ds_read_b128 v[148:151], v176 offset:1024
	ds_read_b128 v[172:175], v176 offset:2048
	ds_read_b128 v[176:179], v176 offset:3072
	s_add_u32 s44, s44, 0x40000
	s_addc_u32 s45, s45, 0
	s_mov_b32 m0, s71
	v_lshl_add_u64 v[244:245], s[44:45], 0, v[154:155]
	ds_read_b128 v[192:195], v157 offset:32768
	ds_read_b128 v[196:199], v157 offset:33792
	ds_read_b128 v[200:203], v157 offset:34816
	ds_read_b128 v[204:207], v157 offset:35840
	ds_read_b128 v[208:211], v157 offset:36864
	ds_read_b128 v[224:227], v157 offset:37888
	ds_read_b128 v[228:231], v157 offset:38912
	ds_read_b128 v[232:235], v157 offset:39936
	global_load_lds_dwordx4 v[244:245], off
	v_lshl_add_u64 v[244:245], s[44:45], 0, v[152:153]
	s_mov_b32 m0, s72
	s_nop 0
	global_load_lds_dwordx4 v[244:245], off
	s_waitcnt vmcnt(8)
	s_waitcnt lgkmcnt(0)
	s_barrier
	s_waitcnt lgkmcnt(0)
	v_mfma_f32_16x16x32_bf16 v[124:127], v[128:131], v[192:195], v[124:127]
	v_mfma_f32_16x16x32_bf16 v[120:123], v[136:139], v[192:195], v[120:123]
	v_mfma_f32_16x16x32_bf16 v[116:119], v[128:131], v[200:203], v[116:119]
	v_mfma_f32_16x16x32_bf16 v[108:111], v[136:139], v[200:203], v[108:111]
	v_mfma_f32_16x16x32_bf16 v[100:103], v[128:131], v[208:211], v[100:103]
	v_mfma_f32_16x16x32_bf16 v[92:95], v[136:139], v[208:211], v[92:95]
	v_mfma_f32_16x16x32_bf16 v[84:87], v[128:131], v[228:231], v[84:87]
	v_mfma_f32_16x16x32_bf16 v[76:79], v[136:139], v[228:231], v[76:79]
	v_mfma_f32_16x16x32_bf16 v[124:127], v[132:135], v[196:199], v[124:127]
	v_mfma_f32_16x16x32_bf16 v[120:123], v[140:143], v[196:199], v[120:123]
	v_mfma_f32_16x16x32_bf16 v[116:119], v[132:135], v[204:207], v[116:119]
	v_mfma_f32_16x16x32_bf16 v[108:111], v[140:143], v[204:207], v[108:111]
	v_mfma_f32_16x16x32_bf16 v[100:103], v[132:135], v[224:227], v[100:103]
	v_mfma_f32_16x16x32_bf16 v[92:95], v[140:143], v[224:227], v[92:95]
	v_mfma_f32_16x16x32_bf16 v[84:87], v[132:135], v[232:235], v[84:87]
	v_mfma_f32_16x16x32_bf16 v[76:79], v[140:143], v[232:235], v[76:79]
	v_mfma_f32_16x16x32_bf16 v[112:115], v[144:147], v[192:195], v[112:115]
	v_mfma_f32_16x16x32_bf16 v[104:107], v[172:175], v[192:195], v[104:107]
	v_mfma_f32_16x16x32_bf16 v[96:99], v[144:147], v[200:203], v[96:99]
	v_mfma_f32_16x16x32_bf16 v[88:91], v[172:175], v[200:203], v[88:91]
	v_mfma_f32_16x16x32_bf16 v[80:83], v[144:147], v[208:211], v[80:83]
	v_mfma_f32_16x16x32_bf16 v[72:75], v[172:175], v[208:211], v[72:75]
	v_mfma_f32_16x16x32_bf16 v[68:71], v[144:147], v[228:231], v[68:71]
	v_mfma_f32_16x16x32_bf16 v[64:67], v[172:175], v[228:231], v[64:67]
	v_mfma_f32_16x16x32_bf16 v[112:115], v[148:151], v[196:199], v[112:115]
	v_mfma_f32_16x16x32_bf16 v[104:107], v[176:179], v[196:199], v[104:107]
	v_mfma_f32_16x16x32_bf16 v[96:99], v[148:151], v[204:207], v[96:99]
	v_mfma_f32_16x16x32_bf16 v[88:91], v[176:179], v[204:207], v[88:91]
	v_mfma_f32_16x16x32_bf16 v[80:83], v[148:151], v[224:227], v[80:83]
	v_mfma_f32_16x16x32_bf16 v[72:75], v[176:179], v[224:227], v[72:75]
	v_mfma_f32_16x16x32_bf16 v[68:71], v[148:151], v[232:235], v[68:71]
	v_mfma_f32_16x16x32_bf16 v[64:67], v[176:179], v[232:235], v[64:67]
	s_barrier
	s_add_i32 s44, s86, s46
	v_lshl_add_u64 v[236:237], v[236:237], 0, s[30:31]
	s_mov_b32 m0, s44
	ds_read_b128 v[192:195], v157 offset:49152
	ds_read_b128 v[196:199], v157 offset:50176
	ds_read_b128 v[200:203], v157 offset:51200
	ds_read_b128 v[204:207], v157 offset:52224
	ds_read_b128 v[208:211], v157 offset:53248
	ds_read_b128 v[224:227], v157 offset:54272
	ds_read_b128 v[228:231], v157 offset:55296
	ds_read_b128 v[232:235], v157 offset:56320
	global_load_lds_dwordx4 v[236:237], off
	s_add_i32 m0, s44, 0x2000
	s_add_u32 s42, s42, 0x40080
	v_lshl_add_u64 v[236:237], v[238:239], 0, s[30:31]
	s_addc_u32 s43, s43, 0
	s_add_i32 s44, s87, s46
	global_load_lds_dwordx4 v[236:237], off
	v_lshl_add_u64 v[236:237], s[42:43], 0, v[154:155]
	s_mov_b32 m0, s44
	s_nop 0
	global_load_lds_dwordx4 v[236:237], off
	v_lshl_add_u64 v[236:237], s[42:43], 0, v[152:153]
	s_add_i32 m0, s44, 0x2000
	s_nop 0
	global_load_lds_dwordx4 v[236:237], off
	v_lshl_add_u64 v[236:237], v[240:241], 0, s[30:31]
	s_mov_b32 m0, s77
	s_nop 0
	global_load_lds_dwordx4 v[236:237], off
	v_lshl_add_u64 v[236:237], v[242:243], 0, s[30:31]
	s_mov_b32 m0, s78
	s_nop 0
	global_load_lds_dwordx4 v[236:237], off
	s_waitcnt vmcnt(8)
	s_waitcnt lgkmcnt(0)
	s_barrier
	s_waitcnt lgkmcnt(0)
	v_mfma_f32_16x16x32_bf16 v[60:63], v[128:131], v[192:195], v[60:63]
	v_mfma_f32_16x16x32_bf16 v[56:59], v[136:139], v[192:195], v[56:59]
	v_mfma_f32_16x16x32_bf16 v[52:55], v[128:131], v[200:203], v[52:55]
	v_mfma_f32_16x16x32_bf16 v[44:47], v[136:139], v[200:203], v[44:47]
	v_mfma_f32_16x16x32_bf16 v[36:39], v[128:131], v[208:211], v[36:39]
	v_mfma_f32_16x16x32_bf16 v[28:31], v[136:139], v[208:211], v[28:31]
	v_mfma_f32_16x16x32_bf16 v[20:23], v[128:131], v[228:231], v[20:23]
	v_mfma_f32_16x16x32_bf16 v[12:15], v[136:139], v[228:231], v[12:15]
	v_mfma_f32_16x16x32_bf16 v[60:63], v[132:135], v[196:199], v[60:63]
	v_mfma_f32_16x16x32_bf16 v[56:59], v[140:143], v[196:199], v[56:59]
	v_mfma_f32_16x16x32_bf16 v[52:55], v[132:135], v[204:207], v[52:55]
	v_mfma_f32_16x16x32_bf16 v[44:47], v[140:143], v[204:207], v[44:47]
	v_mfma_f32_16x16x32_bf16 v[36:39], v[132:135], v[224:227], v[36:39]
	v_mfma_f32_16x16x32_bf16 v[28:31], v[140:143], v[224:227], v[28:31]
	v_mfma_f32_16x16x32_bf16 v[20:23], v[132:135], v[232:235], v[20:23]
	v_mfma_f32_16x16x32_bf16 v[12:15], v[140:143], v[232:235], v[12:15]
	v_mfma_f32_16x16x32_bf16 v[48:51], v[144:147], v[192:195], v[48:51]
	v_mfma_f32_16x16x32_bf16 v[40:43], v[172:175], v[192:195], v[40:43]
	v_mfma_f32_16x16x32_bf16 v[32:35], v[144:147], v[200:203], v[32:35]
	v_mfma_f32_16x16x32_bf16 v[24:27], v[172:175], v[200:203], v[24:27]
	v_mfma_f32_16x16x32_bf16 v[16:19], v[144:147], v[208:211], v[16:19]
	v_mfma_f32_16x16x32_bf16 v[8:11], v[172:175], v[208:211], v[8:11]
	v_mfma_f32_16x16x32_bf16 v[4:7], v[144:147], v[228:231], v[4:7]
	v_mfma_f32_16x16x32_bf16 v[0:3], v[172:175], v[228:231], v[0:3]
	v_mfma_f32_16x16x32_bf16 v[48:51], v[148:151], v[196:199], v[48:51]
	v_mfma_f32_16x16x32_bf16 v[40:43], v[176:179], v[196:199], v[40:43]
	v_mfma_f32_16x16x32_bf16 v[32:35], v[148:151], v[204:207], v[32:35]
	v_mfma_f32_16x16x32_bf16 v[24:27], v[176:179], v[204:207], v[24:27]
	v_mfma_f32_16x16x32_bf16 v[16:19], v[148:151], v[224:227], v[16:19]
	v_mfma_f32_16x16x32_bf16 v[8:11], v[176:179], v[224:227], v[8:11]
	v_mfma_f32_16x16x32_bf16 v[4:7], v[148:151], v[232:235], v[4:7]
	v_mfma_f32_16x16x32_bf16 v[0:3], v[176:179], v[232:235], v[0:3]
	s_barrier
	s_add_i32 s68, s68, 2
	s_add_u32 s36, s36, 0x100
	s_addc_u32 s37, s37, 0
	s_add_u32 s29, s29, 0x100
	s_addc_u32 s60, s60, 0
	s_cmp_gt_u32 s68, 13
	s_cbranch_scc0 .LBB0_153
; #define PG8_BAR __builtin_amdgcn_s_barrier()
; template <class Epi, class Sched, bool ALIGN_EPI = false, bool SP2 = false>
; __device__ __forceinline__ void gemm_phase(PG8_LAS unsigned char* lds, const Gemm g, const Sched& S, const Epi& E) {
;     ...
;         if constexpr (ALIGN_EPI) { if (wr == 0) PG8_BAR; }
;         if constexpr (!Epi::AFTER_DRAIN) { E(acc, cur, wr, wc, fr, fq); S.done(cur); }
.Lgzero0_done:
	s_setprio 0
	s_and_b64 vcc, exec, s[12:13]
	s_cbranch_vccz .LBB0_156
	s_barrier

;     __host__ __device__ bool next(int i, Unit& u) const { Unit m; if (!S.next(i >> 1, m)) return false; u.pm = m.pm; u.pn = m.pn + 4 * (i & 1); return true; }
;     __host__ __device__ bool next(int i, Unit& u) const { Unit m; if (!S.next(i >> 1, m)) return false; u.pm = m.pm + (i & 1) * dpm; u.pn = m.pn + (i & 1) * dpn; return true; }
; #define PG8_STAGE(bufoff, gbase, voff) do { _Pragma("unroll") for (int _i = 0; _i < 2; ++_i) \
;         __builtin_amdgcn_global_load_lds((const unsigned*)((const char*)(gbase) + (voff)[_i]), (PG8_LAS unsigned*)(lds + (bufoff) + ldsw + _i * 8192), 16, 0, 0); } while (0)
; #define PG8_LDA(dst, b, h) do { _Pragma("unroll") for (int m = 0; m < 4; ++m) _Pragma("unroll") for (int k = 0; k < 2; ++k) dst[m][k] = *(const PG8_LAS bf16x8*)(lds + PG8_SA(b, h) + aoff + m * 2048 + k * 1024); } while (0)
; #define PG8_WAIT_V(n) asm volatile("s_waitcnt vmcnt(" #n ")" ::: "memory")
; #define PG8_WAIT_L(n) asm volatile("s_waitcnt lgkmcnt(" #n ")" ::: "memory")
; template <class Epi, class Sched, bool ALIGN_EPI = false, bool SP2 = false>
; __device__ __forceinline__ void gemm_phase(PG8_LAS unsigned char* lds, const Gemm g, const Sched& S, const Epi& E) {
;     ...
;         const bool has_next = S.next(ui + 1, nxt);
;         const char* nA = has_next ? (const char*)g.A + (size_t)nxt.pm * tstep : cA; const char* nB = has_next ? (const char*)g.Bt + (size_t)nxt.pn * tstep : cB;
;         for (int t = 0; t < nt; t += 2) {
;             const bool last = (t == nt - 2);
;             const char* a1 = cA + (size_t)(t + 1) * kstep;
;             const char* a2 = last ? nA : cA + (size_t)(t + 2) * kstep; const char* b2 = last ? nB : cB + (size_t)(t + 2) * kstep;
;             const char* a3 = a2 + kstep; const char* b3 = b2 + kstep;
;             if (last && has_next) S.a_ready(nxt);
;             if constexpr (SP2) {
;             PG8_LDB(B0, 0, 0); PG8_LDB(B1, 0, 1); PG8_SCHED; PG8_LDA(At, 0, 0); PG8_STAGE(PG8_SA(1, 1), a1 + hstep, voffA);
;             PG8_WAIT_V(8); PG8_WAIT_L(0); PG8_BAR; PG8_MMA(0, 0, At, B0); PG8_MMA(0, 1, At, B1); PG8_BAR; PG8_SCHED;
;             PG8_LDA(At, 0, 1); PG8_STAGE(PG8_SB(0, 0), b2, voffB); PG8_STAGE(PG8_SB(0, 1), b2 + hstep, voffB); PG8_STAGE(PG8_SA(0, 0), a2, voffA);
;             PG8_WAIT_V(8); PG8_WAIT_L(0); PG8_BAR; PG8_MMA(1, 0, At, B0); PG8_MMA(1, 1, At, B1); PG8_BAR; PG8_SCHED;
.LBB0_373:
	s_ashr_i32 s19, s18, 31
	s_lshl_b64 s[20:21], s[18:19], 19
	s_add_u32 s20, s38, s20
	s_addc_u32 s21, s39, s21
	s_and_b64 s[22:23], s[6:7], exec
	s_cselect_b32 s19, s21, s25
	s_cselect_b32 s71, s20, s24
	s_ashr_i32 s17, s16, 31
	s_lshl_b64 s[22:23], s[16:17], 19
	s_add_u32 s22, s28, s22
	s_addc_u32 s23, s29, s23
	s_and_b64 s[42:43], s[6:7], exec
	s_cselect_b32 s17, s23, s37
	s_cselect_b32 s72, s22, s36
	s_add_u32 s24, s24, 0x40080
	s_addc_u32 s25, s25, 0
	s_add_u32 s73, s36, 0x100
	s_addc_u32 s76, s37, 0
	s_mov_b32 s77, -2
	v_cmp_lt_u32_e32 vcc, 0xff, v212
	s_cbranch_vccz .Lgprio1
	s_setprio 1
.Lgprio1:
	s_add_u32 s36, s24, 0xfffc0080
	s_addc_u32 s37, s25, -1
	s_add_i32 s78, 0, 0x10000
	s_cmp_eq_u32 s77, 12
	s_cselect_b32 s43, s19, s37
	s_cselect_b32 s42, s71, s36
	s_cselect_b32 s37, s17, s76
	s_cselect_b32 s36, s72, s73
	s_add_i32 s80, 0, 0x14000
	v_add_u32_e32 v68, s78, v153
	v_add_u32_e32 v150, s80, v153
	ds_read_b128 v[48:51], v68
	ds_read_b128 v[52:55], v68 offset:1024
	ds_read_b128 v[64:67], v68 offset:2048
	ds_read_b128 v[68:71], v68 offset:3072
	ds_read_b128 v[156:159], v150
	ds_read_b128 v[160:163], v150 offset:1024
	ds_read_b128 v[164:167], v150 offset:2048
	ds_read_b128 v[168:171], v150 offset:3072
	v_lshl_add_u64 v[150:151], s[24:25], 0, v[146:147]
	s_add_i32 m0, s45, 0xc000
	ds_read_b128 v[172:175], v155
	ds_read_b128 v[176:179], v155 offset:1024
	ds_read_b128 v[180:183], v155 offset:2048
	ds_read_b128 v[190:193], v155 offset:3072
	ds_read_b128 v[194:197], v155 offset:4096
	ds_read_b128 v[198:201], v155 offset:5120
	ds_read_b128 v[202:205], v155 offset:6144
	ds_read_b128 v[206:209], v155 offset:7168
	global_load_lds_dwordx4 v[150:151], off
	v_lshl_add_u64 v[150:151], s[24:25], 0, v[148:149]
	s_add_i32 m0, s45, 0xe000
	s_nop 0
	global_load_lds_dwordx4 v[150:151], off
	s_waitcnt vmcnt(8)
	s_waitcnt lgkmcnt(0)
	s_barrier
	s_waitcnt lgkmcnt(0)
	v_mfma_f32_16x16x32_bf16 v[140:143], v[48:51], v[172:175], 0
	v_mfma_f32_16x16x32_bf16 v[136:139], v[64:67], v[172:175], 0
	v_mfma_f32_16x16x32_bf16 v[124:127], v[48:51], v[180:183], 0
	v_mfma_f32_16x16x32_bf16 v[120:123], v[64:67], v[180:183], 0
	v_mfma_f32_16x16x32_bf16 v[108:111], v[48:51], v[194:197], 0
	v_mfma_f32_16x16x32_bf16 v[104:107], v[64:67], v[194:197], 0
	v_mfma_f32_16x16x32_bf16 v[92:95], v[48:51], v[202:205], 0
	v_mfma_f32_16x16x32_bf16 v[88:91], v[64:67], v[202:205], 0
	v_mfma_f32_16x16x32_bf16 v[140:143], v[52:55], v[176:179], v[140:143]
	v_mfma_f32_16x16x32_bf16 v[136:139], v[68:71], v[176:179], v[136:139]
	v_mfma_f32_16x16x32_bf16 v[124:127], v[52:55], v[190:193], v[124:127]
	v_mfma_f32_16x16x32_bf16 v[120:123], v[68:71], v[190:193], v[120:123]
	v_mfma_f32_16x16x32_bf16 v[108:111], v[52:55], v[198:201], v[108:111]
	v_mfma_f32_16x16x32_bf16 v[104:107], v[68:71], v[198:201], v[104:107]
	v_mfma_f32_16x16x32_bf16 v[92:95], v[52:55], v[206:209], v[92:95]
	v_mfma_f32_16x16x32_bf16 v[88:91], v[68:71], v[206:209], v[88:91]
	v_mfma_f32_16x16x32_bf16 v[132:135], v[156:159], v[172:175], 0
	v_mfma_f32_16x16x32_bf16 v[128:131], v[164:167], v[172:175], 0
	v_mfma_f32_16x16x32_bf16 v[116:119], v[156:159], v[180:183], 0
	v_mfma_f32_16x16x32_bf16 v[112:115], v[164:167], v[180:183], 0
	v_mfma_f32_16x16x32_bf16 v[100:103], v[156:159], v[194:197], 0
	v_mfma_f32_16x16x32_bf16 v[96:99], v[164:167], v[194:197], 0
	v_mfma_f32_16x16x32_bf16 v[84:87], v[156:159], v[202:205], 0
	v_mfma_f32_16x16x32_bf16 v[80:83], v[164:167], v[202:205], 0
	v_mfma_f32_16x16x32_bf16 v[132:135], v[160:163], v[176:179], v[132:135]
	v_mfma_f32_16x16x32_bf16 v[128:131], v[168:171], v[176:179], v[128:131]
	v_mfma_f32_16x16x32_bf16 v[116:119], v[160:163], v[190:193], v[116:119]
	v_mfma_f32_16x16x32_bf16 v[112:115], v[168:171], v[190:193], v[112:115]
	v_mfma_f32_16x16x32_bf16 v[100:103], v[160:163], v[198:201], v[100:103]
	v_mfma_f32_16x16x32_bf16 v[96:99], v[168:171], v[198:201], v[96:99]
	v_mfma_f32_16x16x32_bf16 v[84:87], v[160:163], v[206:209], v[84:87]
	v_mfma_f32_16x16x32_bf16 v[80:83], v[168:171], v[206:209], v[80:83]
	s_barrier
	s_add_i32 s78, s78, s44
	v_lshl_add_u64 v[150:151], s[36:37], 0, v[184:185]
	s_mov_b32 m0, s78
	ds_read_b128 v[172:175], v155 offset:16384
	ds_read_b128 v[176:179], v155 offset:17408
	ds_read_b128 v[180:183], v155 offset:18432
	ds_read_b128 v[190:193], v155 offset:19456
	ds_read_b128 v[194:197], v155 offset:20480
	ds_read_b128 v[198:201], v155 offset:21504
	ds_read_b128 v[202:205], v155 offset:22528
	ds_read_b128 v[206:209], v155 offset:23552
	global_load_lds_dwordx4 v[150:151], off
	s_add_i32 m0, s78, 0x2000
	s_add_u32 s78, s36, 0x40000
	v_lshl_add_u64 v[186:187], s[36:37], 0, v[144:145]
	s_addc_u32 s79, s37, 0
	s_add_i32 s80, s80, s44
	global_load_lds_dwordx4 v[186:187], off
	v_lshl_add_u64 v[188:189], s[78:79], 0, v[184:185]
	s_mov_b32 m0, s80
	v_lshl_add_u64 v[210:211], s[42:43], 0, v[144:145]
	global_load_lds_dwordx4 v[188:189], off
	v_lshl_add_u64 v[188:189], s[78:79], 0, v[144:145]
	s_add_i32 m0, s80, 0x2000
	s_nop 0
	global_load_lds_dwordx4 v[188:189], off
	v_lshl_add_u64 v[188:189], s[42:43], 0, v[184:185]
	s_mov_b32 m0, s45
	s_nop 0
	global_load_lds_dwordx4 v[188:189], off
	s_mov_b32 m0, s46
	s_nop 0
	global_load_lds_dwordx4 v[210:211], off
	s_waitcnt vmcnt(8)
	s_waitcnt lgkmcnt(0)
	s_barrier
; #define PG8_STAGE(bufoff, gbase, voff) do { _Pragma("unroll") for (int _i = 0; _i < 2; ++_i) \
;         __builtin_amdgcn_global_load_lds((const unsigned*)((const char*)(gbase) + (voff)[_i]), (PG8_LAS unsigned*)(lds + (bufoff) + ldsw + _i * 8192), 16, 0, 0); } while (0)
; #define PG8_LDA(dst, b, h) do { _Pragma("unroll") for (int m = 0; m < 4; ++m) _Pragma("unroll") for (int k = 0; k < 2; ++k) dst[m][k] = *(const PG8_LAS bf16x8*)(lds + PG8_SA(b, h) + aoff + m * 2048 + k * 1024); } while (0)
; #define PG8_LDB(dst, b, h) do { _Pragma("unroll") for (int n = 0; n < 2; ++n) _Pragma("unroll") for (int k = 0; k < 2; ++k) dst[n][k] = *(const PG8_LAS bf16x8*)(lds + PG8_SB(b, h) + boff + n * 2048 + k * 1024); } while (0)
; #define PG8_MMA(ai, bj, At, Bt) do { __builtin_amdgcn_s_setprio(1); _Pragma("unroll") for (int m = 0; m < 4; ++m) _Pragma("unroll") for (int n = 0; n < 2; ++n) _Pragma("unroll") for (int k = 0; k < 2; ++k) \
;         acc[ai][bj][m][n] = __builtin_amdgcn_mfma_f32_16x16x32_bf16(Bt[n][k], At[m][k], acc[ai][bj][m][n], 0, 0, 0); __builtin_amdgcn_s_setprio(0); } while (0)
; #define PG8_WAIT_V(n) asm volatile("s_waitcnt vmcnt(" #n ")" ::: "memory")
; #define PG8_WAIT_L(n) asm volatile("s_waitcnt lgkmcnt(" #n ")" ::: "memory")
; #define PG8_BAR __builtin_amdgcn_s_barrier()
; #define PG8_SCHED __builtin_amdgcn_sched_barrier(0)
; template <class Epi, class Sched, bool ALIGN_EPI = false, bool SP2 = false>
; __device__ __forceinline__ void gemm_phase(PG8_LAS unsigned char* lds, const Gemm g, const Sched& S, const Epi& E) {
;     ...
;             PG8_WAIT_V(8); PG8_WAIT_L(0); PG8_BAR; PG8_MMA(1, 0, At, B0); PG8_MMA(1, 1, At, B1); PG8_BAR; PG8_SCHED;
;             PG8_LDB(B0, 1, 0); PG8_LDB(B1, 1, 1); PG8_SCHED; PG8_LDA(At, 1, 0); PG8_STAGE(PG8_SA(0, 1), a2 + hstep, voffA);
;             PG8_WAIT_V(8); PG8_WAIT_L(0); PG8_BAR; PG8_MMA(0, 0, At, B0); PG8_MMA(0, 1, At, B1); PG8_BAR; PG8_SCHED;
	s_waitcnt lgkmcnt(0)
	v_mfma_f32_16x16x32_bf16 v[76:79], v[48:51], v[172:175], 0
	v_mfma_f32_16x16x32_bf16 v[72:75], v[64:67], v[172:175], 0
	v_mfma_f32_16x16x32_bf16 v[44:47], v[48:51], v[180:183], 0
	v_mfma_f32_16x16x32_bf16 v[40:43], v[64:67], v[180:183], 0
	v_mfma_f32_16x16x32_bf16 v[28:31], v[48:51], v[194:197], 0
	v_mfma_f32_16x16x32_bf16 v[24:27], v[64:67], v[194:197], 0
	v_mfma_f32_16x16x32_bf16 v[12:15], v[48:51], v[202:205], 0
	v_mfma_f32_16x16x32_bf16 v[8:11], v[64:67], v[202:205], 0
	v_mfma_f32_16x16x32_bf16 v[76:79], v[52:55], v[176:179], v[76:79]
	v_mfma_f32_16x16x32_bf16 v[72:75], v[68:71], v[176:179], v[72:75]
	v_mfma_f32_16x16x32_bf16 v[44:47], v[52:55], v[190:193], v[44:47]
	v_mfma_f32_16x16x32_bf16 v[40:43], v[68:71], v[190:193], v[40:43]
	v_mfma_f32_16x16x32_bf16 v[28:31], v[52:55], v[198:201], v[28:31]
	v_mfma_f32_16x16x32_bf16 v[24:27], v[68:71], v[198:201], v[24:27]
	v_mfma_f32_16x16x32_bf16 v[12:15], v[52:55], v[206:209], v[12:15]
	v_mfma_f32_16x16x32_bf16 v[8:11], v[68:71], v[206:209], v[8:11]
	v_mfma_f32_16x16x32_bf16 v[36:39], v[156:159], v[180:183], 0
	v_mfma_f32_16x16x32_bf16 v[32:35], v[164:167], v[180:183], 0
	v_mfma_f32_16x16x32_bf16 v[20:23], v[156:159], v[194:197], 0
	v_mfma_f32_16x16x32_bf16 v[16:19], v[164:167], v[194:197], 0
	v_mfma_f32_16x16x32_bf16 v[4:7], v[156:159], v[202:205], 0
	v_mfma_f32_16x16x32_bf16 v[0:3], v[164:167], v[202:205], 0
	v_mfma_f32_16x16x32_bf16 v[48:51], v[156:159], v[172:175], 0
	v_mfma_f32_16x16x32_bf16 v[52:55], v[164:167], v[172:175], 0
	v_mfma_f32_16x16x32_bf16 v[36:39], v[160:163], v[190:193], v[36:39]
	v_mfma_f32_16x16x32_bf16 v[32:35], v[168:171], v[190:193], v[32:35]
	v_mfma_f32_16x16x32_bf16 v[20:23], v[160:163], v[198:201], v[20:23]
	v_mfma_f32_16x16x32_bf16 v[16:19], v[168:171], v[198:201], v[16:19]
	v_mfma_f32_16x16x32_bf16 v[4:7], v[160:163], v[206:209], v[4:7]
	v_mfma_f32_16x16x32_bf16 v[0:3], v[168:171], v[206:209], v[0:3]
	v_mfma_f32_16x16x32_bf16 v[48:51], v[160:163], v[176:179], v[48:51]
	v_mfma_f32_16x16x32_bf16 v[52:55], v[168:171], v[176:179], v[52:55]
	s_barrier
	s_add_i32 s78, 0, 0x18000
	s_add_i32 s79, 0, 0x1c000
	v_add_u32_e32 v68, s78, v153
	v_add_u32_e32 v168, s79, v153
	ds_read_b128 v[56:59], v68
	ds_read_b128 v[60:63], v68 offset:1024
	ds_read_b128 v[64:67], v68 offset:2048
	ds_read_b128 v[68:71], v68 offset:3072
	ds_read_b128 v[156:159], v168
	ds_read_b128 v[160:163], v168 offset:1024
	ds_read_b128 v[164:167], v168 offset:2048
	ds_read_b128 v[168:171], v168 offset:3072
	s_add_u32 s42, s42, 0x40000
	s_addc_u32 s43, s43, 0
	s_mov_b32 m0, s47
	v_lshl_add_u64 v[214:215], s[42:43], 0, v[184:185]
	ds_read_b128 v[172:175], v155 offset:32768
	ds_read_b128 v[176:179], v155 offset:33792
	ds_read_b128 v[180:183], v155 offset:34816
	ds_read_b128 v[190:193], v155 offset:35840
	ds_read_b128 v[194:197], v155 offset:36864
	ds_read_b128 v[198:201], v155 offset:37888
	ds_read_b128 v[202:205], v155 offset:38912
	ds_read_b128 v[206:209], v155 offset:39936
	global_load_lds_dwordx4 v[214:215], off
	v_lshl_add_u64 v[214:215], s[42:43], 0, v[144:145]
	s_mov_b32 m0, s48
	s_nop 0
	global_load_lds_dwordx4 v[214:215], off
	s_waitcnt vmcnt(8)
	s_waitcnt lgkmcnt(0)
	s_barrier
	s_waitcnt lgkmcnt(0)
	v_mfma_f32_16x16x32_bf16 v[140:143], v[56:59], v[172:175], v[140:143]
	v_mfma_f32_16x16x32_bf16 v[136:139], v[64:67], v[172:175], v[136:139]
	v_mfma_f32_16x16x32_bf16 v[124:127], v[56:59], v[180:183], v[124:127]
	v_mfma_f32_16x16x32_bf16 v[120:123], v[64:67], v[180:183], v[120:123]
	v_mfma_f32_16x16x32_bf16 v[108:111], v[56:59], v[194:197], v[108:111]
	v_mfma_f32_16x16x32_bf16 v[104:107], v[64:67], v[194:197], v[104:107]
	v_mfma_f32_16x16x32_bf16 v[92:95], v[56:59], v[202:205], v[92:95]
	v_mfma_f32_16x16x32_bf16 v[88:91], v[64:67], v[202:205], v[88:91]
	v_mfma_f32_16x16x32_bf16 v[140:143], v[60:63], v[176:179], v[140:143]
	v_mfma_f32_16x16x32_bf16 v[136:139], v[68:71], v[176:179], v[136:139]
	v_mfma_f32_16x16x32_bf16 v[124:127], v[60:63], v[190:193], v[124:127]
	v_mfma_f32_16x16x32_bf16 v[120:123], v[68:71], v[190:193], v[120:123]
	v_mfma_f32_16x16x32_bf16 v[108:111], v[60:63], v[198:201], v[108:111]
	v_mfma_f32_16x16x32_bf16 v[104:107], v[68:71], v[198:201], v[104:107]
	v_mfma_f32_16x16x32_bf16 v[92:95], v[60:63], v[206:209], v[92:95]
	v_mfma_f32_16x16x32_bf16 v[88:91], v[68:71], v[206:209], v[88:91]
	v_mfma_f32_16x16x32_bf16 v[132:135], v[156:159], v[172:175], v[132:135]
	v_mfma_f32_16x16x32_bf16 v[128:131], v[164:167], v[172:175], v[128:131]
	v_mfma_f32_16x16x32_bf16 v[116:119], v[156:159], v[180:183], v[116:119]
	v_mfma_f32_16x16x32_bf16 v[112:115], v[164:167], v[180:183], v[112:115]
	v_mfma_f32_16x16x32_bf16 v[100:103], v[156:159], v[194:197], v[100:103]
	v_mfma_f32_16x16x32_bf16 v[96:99], v[164:167], v[194:197], v[96:99]
	v_mfma_f32_16x16x32_bf16 v[84:87], v[156:159], v[202:205], v[84:87]
	v_mfma_f32_16x16x32_bf16 v[80:83], v[164:167], v[202:205], v[80:83]
	v_mfma_f32_16x16x32_bf16 v[132:135], v[160:163], v[176:179], v[132:135]
	v_mfma_f32_16x16x32_bf16 v[128:131], v[168:171], v[176:179], v[128:131]
	v_mfma_f32_16x16x32_bf16 v[116:119], v[160:163], v[190:193], v[116:119]
	v_mfma_f32_16x16x32_bf16 v[112:115], v[168:171], v[190:193], v[112:115]
	v_mfma_f32_16x16x32_bf16 v[100:103], v[160:163], v[198:201], v[100:103]
	v_mfma_f32_16x16x32_bf16 v[96:99], v[168:171], v[198:201], v[96:99]
	v_mfma_f32_16x16x32_bf16 v[84:87], v[160:163], v[206:209], v[84:87]
	v_mfma_f32_16x16x32_bf16 v[80:83], v[168:171], v[206:209], v[80:83]
	s_barrier
; #define PG8_STAGE(bufoff, gbase, voff) do { _Pragma("unroll") for (int _i = 0; _i < 2; ++_i) \
;         __builtin_amdgcn_global_load_lds((const unsigned*)((const char*)(gbase) + (voff)[_i]), (PG8_LAS unsigned*)(lds + (bufoff) + ldsw + _i * 8192), 16, 0, 0); } while (0)
; #define PG8_LDA(dst, b, h) do { _Pragma("unroll") for (int m = 0; m < 4; ++m) _Pragma("unroll") for (int k = 0; k < 2; ++k) dst[m][k] = *(const PG8_LAS bf16x8*)(lds + PG8_SA(b, h) + aoff + m * 2048 + k * 1024); } while (0)
; #define PG8_LDB(dst, b, h) do { _Pragma("unroll") for (int n = 0; n < 2; ++n) _Pragma("unroll") for (int k = 0; k < 2; ++k) dst[n][k] = *(const PG8_LAS bf16x8*)(lds + PG8_SB(b, h) + boff + n * 2048 + k * 1024); } while (0)
; #define PG8_MMA(ai, bj, At, Bt) do { __builtin_amdgcn_s_setprio(1); _Pragma("unroll") for (int m = 0; m < 4; ++m) _Pragma("unroll") for (int n = 0; n < 2; ++n) _Pragma("unroll") for (int k = 0; k < 2; ++k) \
;         acc[ai][bj][m][n] = __builtin_amdgcn_mfma_f32_16x16x32_bf16(Bt[n][k], At[m][k], acc[ai][bj][m][n], 0, 0, 0); __builtin_amdgcn_s_setprio(0); } while (0)
; #define PG8_WAIT_V(n) asm volatile("s_waitcnt vmcnt(" #n ")" ::: "memory")
; #define PG8_WAIT_L(n) asm volatile("s_waitcnt lgkmcnt(" #n ")" ::: "memory")
; #define PG8_BAR __builtin_amdgcn_s_barrier()
; #define PG8_SCHED __builtin_amdgcn_sched_barrier(0)
; template <class Epi, class Sched, bool ALIGN_EPI = false, bool SP2 = false>
; __device__ __forceinline__ void gemm_phase(PG8_LAS unsigned char* lds, const Gemm g, const Sched& S, const Epi& E) {
;     ...
;             PG8_LDB(B0, 0, 0); PG8_LDB(B1, 0, 1); PG8_SCHED; PG8_LDA(At, 0, 0); PG8_STAGE(PG8_SA(1, 1), a1 + hstep, voffA);
;             PG8_WAIT_V(8); PG8_WAIT_L(0); PG8_BAR; PG8_MMA(0, 0, At, B0); PG8_MMA(0, 1, At, B1); PG8_BAR; PG8_SCHED;
;     ...
;             PG8_LDA(At, 1, 1); PG8_STAGE(PG8_SB(1, 0), b3, voffB); PG8_STAGE(PG8_SB(1, 1), b3 + hstep, voffB); PG8_STAGE(PG8_SA(1, 0), a3, voffA);
;             PG8_WAIT_V(8); PG8_WAIT_L(0); PG8_BAR; PG8_MMA(1, 0, At, B0); PG8_MMA(1, 1, At, B1); PG8_BAR; PG8_SCHED;
	s_add_i32 s42, s78, s44
	v_lshl_add_u64 v[150:151], v[150:151], 0, s[30:31]
	s_mov_b32 m0, s42
	ds_read_b128 v[172:175], v155 offset:49152
	ds_read_b128 v[176:179], v155 offset:50176
	ds_read_b128 v[180:183], v155 offset:51200
	ds_read_b128 v[190:193], v155 offset:52224
	ds_read_b128 v[194:197], v155 offset:53248
	ds_read_b128 v[198:201], v155 offset:54272
	ds_read_b128 v[202:205], v155 offset:55296
	ds_read_b128 v[206:209], v155 offset:56320
	global_load_lds_dwordx4 v[150:151], off
	s_add_i32 m0, s42, 0x2000
	s_add_u32 s36, s36, 0x40080
	v_lshl_add_u64 v[150:151], v[186:187], 0, s[30:31]
	s_addc_u32 s37, s37, 0
	s_add_i32 s42, s79, s44
	global_load_lds_dwordx4 v[150:151], off
	v_lshl_add_u64 v[150:151], s[36:37], 0, v[184:185]
	s_mov_b32 m0, s42
	s_nop 0
	global_load_lds_dwordx4 v[150:151], off
	v_lshl_add_u64 v[150:151], s[36:37], 0, v[144:145]
	s_add_i32 m0, s42, 0x2000
	s_nop 0
	global_load_lds_dwordx4 v[150:151], off
	v_lshl_add_u64 v[150:151], v[188:189], 0, s[30:31]
	s_mov_b32 m0, s49
	s_nop 0
	global_load_lds_dwordx4 v[150:151], off
	v_lshl_add_u64 v[150:151], v[210:211], 0, s[30:31]
	s_mov_b32 m0, s60
	s_nop 0
	global_load_lds_dwordx4 v[150:151], off
	s_waitcnt vmcnt(8)
	s_waitcnt lgkmcnt(0)
	s_barrier
	s_waitcnt lgkmcnt(0)
	v_mfma_f32_16x16x32_bf16 v[76:79], v[56:59], v[172:175], v[76:79]
	v_mfma_f32_16x16x32_bf16 v[72:75], v[64:67], v[172:175], v[72:75]
	v_mfma_f32_16x16x32_bf16 v[44:47], v[56:59], v[180:183], v[44:47]
	v_mfma_f32_16x16x32_bf16 v[40:43], v[64:67], v[180:183], v[40:43]
	v_mfma_f32_16x16x32_bf16 v[28:31], v[56:59], v[194:197], v[28:31]
	v_mfma_f32_16x16x32_bf16 v[24:27], v[64:67], v[194:197], v[24:27]
	v_mfma_f32_16x16x32_bf16 v[12:15], v[56:59], v[202:205], v[12:15]
	v_mfma_f32_16x16x32_bf16 v[8:11], v[64:67], v[202:205], v[8:11]
	v_mfma_f32_16x16x32_bf16 v[76:79], v[60:63], v[176:179], v[76:79]
	v_mfma_f32_16x16x32_bf16 v[72:75], v[68:71], v[176:179], v[72:75]
	v_mfma_f32_16x16x32_bf16 v[44:47], v[60:63], v[190:193], v[44:47]
	v_mfma_f32_16x16x32_bf16 v[40:43], v[68:71], v[190:193], v[40:43]
	v_mfma_f32_16x16x32_bf16 v[28:31], v[60:63], v[198:201], v[28:31]
	v_mfma_f32_16x16x32_bf16 v[24:27], v[68:71], v[198:201], v[24:27]
	v_mfma_f32_16x16x32_bf16 v[12:15], v[60:63], v[206:209], v[12:15]
	v_mfma_f32_16x16x32_bf16 v[8:11], v[68:71], v[206:209], v[8:11]
	v_mfma_f32_16x16x32_bf16 v[48:51], v[156:159], v[172:175], v[48:51]
	v_mfma_f32_16x16x32_bf16 v[60:63], v[160:163], v[176:179], v[48:51]
	v_mfma_f32_16x16x32_bf16 v[48:51], v[164:167], v[172:175], v[52:55]
	v_mfma_f32_16x16x32_bf16 v[36:39], v[156:159], v[180:183], v[36:39]
	v_mfma_f32_16x16x32_bf16 v[32:35], v[164:167], v[180:183], v[32:35]
	v_mfma_f32_16x16x32_bf16 v[20:23], v[156:159], v[194:197], v[20:23]
	v_mfma_f32_16x16x32_bf16 v[16:19], v[164:167], v[194:197], v[16:19]
	v_mfma_f32_16x16x32_bf16 v[4:7], v[156:159], v[202:205], v[4:7]
	v_mfma_f32_16x16x32_bf16 v[0:3], v[164:167], v[202:205], v[0:3]
	v_mfma_f32_16x16x32_bf16 v[56:59], v[168:171], v[176:179], v[48:51]
	v_mfma_f32_16x16x32_bf16 v[36:39], v[160:163], v[190:193], v[36:39]
	v_mfma_f32_16x16x32_bf16 v[32:35], v[168:171], v[190:193], v[32:35]
	v_mfma_f32_16x16x32_bf16 v[20:23], v[160:163], v[198:201], v[20:23]
	v_mfma_f32_16x16x32_bf16 v[16:19], v[168:171], v[198:201], v[16:19]
	v_mfma_f32_16x16x32_bf16 v[4:7], v[160:163], v[206:209], v[4:7]
	v_mfma_f32_16x16x32_bf16 v[0:3], v[168:171], v[206:209], v[0:3]
	s_barrier
	s_add_i32 s77, s77, 2
	s_add_u32 s24, s24, 0x100
	s_addc_u32 s25, s25, 0
	s_add_u32 s73, s73, 0x100
	s_addc_u32 s76, s76, 0
	s_cmp_gt_u32 s77, 13
	s_cbranch_scc0 .LBB0_374
	s_branch .Lgzero1_done
.LBB0_374:
	s_add_u32 s36, s24, 0xfffc0080
	s_addc_u32 s37, s25, -1
	s_add_i32 s78, 0, 0x10000
	s_cmp_eq_u32 s77, 12
	s_cselect_b32 s43, s19, s37
	s_cselect_b32 s42, s71, s36
	s_cselect_b32 s37, s17, s76
	s_cselect_b32 s36, s72, s73
	s_add_i32 s80, 0, 0x14000
	v_add_u32_e32 v68, s78, v153
	v_add_u32_e32 v150, s80, v153
	ds_read_b128 v[48:51], v68
	ds_read_b128 v[52:55], v68 offset:1024
	ds_read_b128 v[64:67], v68 offset:2048
	ds_read_b128 v[68:71], v68 offset:3072
	ds_read_b128 v[156:159], v150
	ds_read_b128 v[160:163], v150 offset:1024
	ds_read_b128 v[164:167], v150 offset:2048
	ds_read_b128 v[168:171], v150 offset:3072
	v_lshl_add_u64 v[150:151], s[24:25], 0, v[146:147]
	s_add_i32 m0, s45, 0xc000
	ds_read_b128 v[172:175], v155
	ds_read_b128 v[176:179], v155 offset:1024
	ds_read_b128 v[180:183], v155 offset:2048
	ds_read_b128 v[190:193], v155 offset:3072
	ds_read_b128 v[194:197], v155 offset:4096
	ds_read_b128 v[198:201], v155 offset:5120
	ds_read_b128 v[202:205], v155 offset:6144
	ds_read_b128 v[206:209], v155 offset:7168
	global_load_lds_dwordx4 v[150:151], off
	v_lshl_add_u64 v[150:151], s[24:25], 0, v[148:149]
	s_add_i32 m0, s45, 0xe000
	s_nop 0
	global_load_lds_dwordx4 v[150:151], off
	s_waitcnt vmcnt(8)
	s_waitcnt lgkmcnt(0)
	s_barrier
; #define PG8_STAGE(bufoff, gbase, voff) do { _Pragma("unroll") for (int _i = 0; _i < 2; ++_i) \
;         __builtin_amdgcn_global_load_lds((const unsigned*)((const char*)(gbase) + (voff)[_i]), (PG8_LAS unsigned*)(lds + (bufoff) + ldsw + _i * 8192), 16, 0, 0); } while (0)
; #define PG8_LDA(dst, b, h) do { _Pragma("unroll") for (int m = 0; m < 4; ++m) _Pragma("unroll") for (int k = 0; k < 2; ++k) dst[m][k] = *(const PG8_LAS bf16x8*)(lds + PG8_SA(b, h) + aoff + m * 2048 + k * 1024); } while (0)
; #define PG8_MMA(ai, bj, At, Bt) do { __builtin_amdgcn_s_setprio(1); _Pragma("unroll") for (int m = 0; m < 4; ++m) _Pragma("unroll") for (int n = 0; n < 2; ++n) _Pragma("unroll") for (int k = 0; k < 2; ++k) \
;         acc[ai][bj][m][n] = __builtin_amdgcn_mfma_f32_16x16x32_bf16(Bt[n][k], At[m][k], acc[ai][bj][m][n], 0, 0, 0); __builtin_amdgcn_s_setprio(0); } while (0)
; #define PG8_WAIT_V(n) asm volatile("s_waitcnt vmcnt(" #n ")" ::: "memory")
; #define PG8_WAIT_L(n) asm volatile("s_waitcnt lgkmcnt(" #n ")" ::: "memory")
; #define PG8_BAR __builtin_amdgcn_s_barrier()
; #define PG8_SCHED __builtin_amdgcn_sched_barrier(0)
; template <class Epi, class Sched, bool ALIGN_EPI = false, bool SP2 = false>
; __device__ __forceinline__ void gemm_phase(PG8_LAS unsigned char* lds, const Gemm g, const Sched& S, const Epi& E) {
;     ...
;             PG8_WAIT_V(8); PG8_WAIT_L(0); PG8_BAR; PG8_MMA(0, 0, At, B0); PG8_MMA(0, 1, At, B1); PG8_BAR; PG8_SCHED;
;             PG8_LDA(At, 0, 1); PG8_STAGE(PG8_SB(0, 0), b2, voffB); PG8_STAGE(PG8_SB(0, 1), b2 + hstep, voffB); PG8_STAGE(PG8_SA(0, 0), a2, voffA);
;             PG8_WAIT_V(8); PG8_WAIT_L(0); PG8_BAR; PG8_MMA(1, 0, At, B0); PG8_MMA(1, 1, At, B1); PG8_BAR; PG8_SCHED;
	s_waitcnt lgkmcnt(0)
	v_mfma_f32_16x16x32_bf16 v[140:143], v[48:51], v[172:175], v[140:143]
	v_mfma_f32_16x16x32_bf16 v[136:139], v[64:67], v[172:175], v[136:139]
	v_mfma_f32_16x16x32_bf16 v[124:127], v[48:51], v[180:183], v[124:127]
	v_mfma_f32_16x16x32_bf16 v[120:123], v[64:67], v[180:183], v[120:123]
	v_mfma_f32_16x16x32_bf16 v[108:111], v[48:51], v[194:197], v[108:111]
	v_mfma_f32_16x16x32_bf16 v[104:107], v[64:67], v[194:197], v[104:107]
	v_mfma_f32_16x16x32_bf16 v[92:95], v[48:51], v[202:205], v[92:95]
	v_mfma_f32_16x16x32_bf16 v[88:91], v[64:67], v[202:205], v[88:91]
	v_mfma_f32_16x16x32_bf16 v[140:143], v[52:55], v[176:179], v[140:143]
	v_mfma_f32_16x16x32_bf16 v[136:139], v[68:71], v[176:179], v[136:139]
	v_mfma_f32_16x16x32_bf16 v[124:127], v[52:55], v[190:193], v[124:127]
	v_mfma_f32_16x16x32_bf16 v[120:123], v[68:71], v[190:193], v[120:123]
	v_mfma_f32_16x16x32_bf16 v[108:111], v[52:55], v[198:201], v[108:111]
	v_mfma_f32_16x16x32_bf16 v[104:107], v[68:71], v[198:201], v[104:107]
	v_mfma_f32_16x16x32_bf16 v[92:95], v[52:55], v[206:209], v[92:95]
	v_mfma_f32_16x16x32_bf16 v[88:91], v[68:71], v[206:209], v[88:91]
	v_mfma_f32_16x16x32_bf16 v[132:135], v[156:159], v[172:175], v[132:135]
	v_mfma_f32_16x16x32_bf16 v[128:131], v[164:167], v[172:175], v[128:131]
	v_mfma_f32_16x16x32_bf16 v[116:119], v[156:159], v[180:183], v[116:119]
	v_mfma_f32_16x16x32_bf16 v[112:115], v[164:167], v[180:183], v[112:115]
	v_mfma_f32_16x16x32_bf16 v[100:103], v[156:159], v[194:197], v[100:103]
	v_mfma_f32_16x16x32_bf16 v[96:99], v[164:167], v[194:197], v[96:99]
	v_mfma_f32_16x16x32_bf16 v[84:87], v[156:159], v[202:205], v[84:87]
	v_mfma_f32_16x16x32_bf16 v[80:83], v[164:167], v[202:205], v[80:83]
	v_mfma_f32_16x16x32_bf16 v[132:135], v[160:163], v[176:179], v[132:135]
	v_mfma_f32_16x16x32_bf16 v[128:131], v[168:171], v[176:179], v[128:131]
	v_mfma_f32_16x16x32_bf16 v[116:119], v[160:163], v[190:193], v[116:119]
	v_mfma_f32_16x16x32_bf16 v[112:115], v[168:171], v[190:193], v[112:115]
	v_mfma_f32_16x16x32_bf16 v[100:103], v[160:163], v[198:201], v[100:103]
	v_mfma_f32_16x16x32_bf16 v[96:99], v[168:171], v[198:201], v[96:99]
	v_mfma_f32_16x16x32_bf16 v[84:87], v[160:163], v[206:209], v[84:87]
	v_mfma_f32_16x16x32_bf16 v[80:83], v[168:171], v[206:209], v[80:83]
	s_barrier
	s_add_i32 s78, s78, s44
	v_lshl_add_u64 v[150:151], s[36:37], 0, v[184:185]
	s_mov_b32 m0, s78
	ds_read_b128 v[172:175], v155 offset:16384
	ds_read_b128 v[176:179], v155 offset:17408
	ds_read_b128 v[180:183], v155 offset:18432
	ds_read_b128 v[190:193], v155 offset:19456
	ds_read_b128 v[194:197], v155 offset:20480
	ds_read_b128 v[198:201], v155 offset:21504
	ds_read_b128 v[202:205], v155 offset:22528
	ds_read_b128 v[206:209], v155 offset:23552
	global_load_lds_dwordx4 v[150:151], off
	s_add_i32 m0, s78, 0x2000
	s_add_u32 s78, s36, 0x40000
	v_lshl_add_u64 v[186:187], s[36:37], 0, v[144:145]
	s_addc_u32 s79, s37, 0
	s_add_i32 s80, s80, s44
	global_load_lds_dwordx4 v[186:187], off
	v_lshl_add_u64 v[188:189], s[78:79], 0, v[184:185]
	s_mov_b32 m0, s80
	v_lshl_add_u64 v[210:211], s[42:43], 0, v[144:145]
	global_load_lds_dwordx4 v[188:189], off
	v_lshl_add_u64 v[188:189], s[78:79], 0, v[144:145]
	s_add_i32 m0, s80, 0x2000
	s_nop 0
	global_load_lds_dwordx4 v[188:189], off
	v_lshl_add_u64 v[188:189], s[42:43], 0, v[184:185]
	s_mov_b32 m0, s45
	s_nop 0
	global_load_lds_dwordx4 v[188:189], off
	s_mov_b32 m0, s46
	s_nop 0
	global_load_lds_dwordx4 v[210:211], off
	s_waitcnt vmcnt(8)
	s_waitcnt lgkmcnt(0)
	s_barrier
	s_waitcnt lgkmcnt(0)
	v_mfma_f32_16x16x32_bf16 v[76:79], v[48:51], v[172:175], v[76:79]
	v_mfma_f32_16x16x32_bf16 v[72:75], v[64:67], v[172:175], v[72:75]
	v_mfma_f32_16x16x32_bf16 v[44:47], v[48:51], v[180:183], v[44:47]
	v_mfma_f32_16x16x32_bf16 v[40:43], v[64:67], v[180:183], v[40:43]
	v_mfma_f32_16x16x32_bf16 v[28:31], v[48:51], v[194:197], v[28:31]
	v_mfma_f32_16x16x32_bf16 v[24:27], v[64:67], v[194:197], v[24:27]
	v_mfma_f32_16x16x32_bf16 v[12:15], v[48:51], v[202:205], v[12:15]
	v_mfma_f32_16x16x32_bf16 v[8:11], v[64:67], v[202:205], v[8:11]
	v_mfma_f32_16x16x32_bf16 v[76:79], v[52:55], v[176:179], v[76:79]
	v_mfma_f32_16x16x32_bf16 v[72:75], v[68:71], v[176:179], v[72:75]
	v_mfma_f32_16x16x32_bf16 v[44:47], v[52:55], v[190:193], v[44:47]
	v_mfma_f32_16x16x32_bf16 v[40:43], v[68:71], v[190:193], v[40:43]
	v_mfma_f32_16x16x32_bf16 v[28:31], v[52:55], v[198:201], v[28:31]
	v_mfma_f32_16x16x32_bf16 v[24:27], v[68:71], v[198:201], v[24:27]
	v_mfma_f32_16x16x32_bf16 v[12:15], v[52:55], v[206:209], v[12:15]
	v_mfma_f32_16x16x32_bf16 v[8:11], v[68:71], v[206:209], v[8:11]
	v_mfma_f32_16x16x32_bf16 v[36:39], v[156:159], v[180:183], v[36:39]
	v_mfma_f32_16x16x32_bf16 v[32:35], v[164:167], v[180:183], v[32:35]
	v_mfma_f32_16x16x32_bf16 v[20:23], v[156:159], v[194:197], v[20:23]
	v_mfma_f32_16x16x32_bf16 v[16:19], v[164:167], v[194:197], v[16:19]
	v_mfma_f32_16x16x32_bf16 v[4:7], v[156:159], v[202:205], v[4:7]
	v_mfma_f32_16x16x32_bf16 v[0:3], v[164:167], v[202:205], v[0:3]
	v_mfma_f32_16x16x32_bf16 v[48:51], v[156:159], v[172:175], v[60:63]
	v_mfma_f32_16x16x32_bf16 v[52:55], v[164:167], v[172:175], v[56:59]
	v_mfma_f32_16x16x32_bf16 v[36:39], v[160:163], v[190:193], v[36:39]
	v_mfma_f32_16x16x32_bf16 v[32:35], v[168:171], v[190:193], v[32:35]
	v_mfma_f32_16x16x32_bf16 v[20:23], v[160:163], v[198:201], v[20:23]
	v_mfma_f32_16x16x32_bf16 v[16:19], v[168:171], v[198:201], v[16:19]
	v_mfma_f32_16x16x32_bf16 v[4:7], v[160:163], v[206:209], v[4:7]
	v_mfma_f32_16x16x32_bf16 v[0:3], v[168:171], v[206:209], v[0:3]
	v_mfma_f32_16x16x32_bf16 v[48:51], v[160:163], v[176:179], v[48:51]
	v_mfma_f32_16x16x32_bf16 v[52:55], v[168:171], v[176:179], v[52:55]
	s_barrier
; #define PG8_STAGE(bufoff, gbase, voff) do { _Pragma("unroll") for (int _i = 0; _i < 2; ++_i) \
;         __builtin_amdgcn_global_load_lds((const unsigned*)((const char*)(gbase) + (voff)[_i]), (PG8_LAS unsigned*)(lds + (bufoff) + ldsw + _i * 8192), 16, 0, 0); } while (0)
; #define PG8_LDA(dst, b, h) do { _Pragma("unroll") for (int m = 0; m < 4; ++m) _Pragma("unroll") for (int k = 0; k < 2; ++k) dst[m][k] = *(const PG8_LAS bf16x8*)(lds + PG8_SA(b, h) + aoff + m * 2048 + k * 1024); } while (0)
; #define PG8_LDB(dst, b, h) do { _Pragma("unroll") for (int n = 0; n < 2; ++n) _Pragma("unroll") for (int k = 0; k < 2; ++k) dst[n][k] = *(const PG8_LAS bf16x8*)(lds + PG8_SB(b, h) + boff + n * 2048 + k * 1024); } while (0)
; #define PG8_MMA(ai, bj, At, Bt) do { __builtin_amdgcn_s_setprio(1); _Pragma("unroll") for (int m = 0; m < 4; ++m) _Pragma("unroll") for (int n = 0; n < 2; ++n) _Pragma("unroll") for (int k = 0; k < 2; ++k) \
;         acc[ai][bj][m][n] = __builtin_amdgcn_mfma_f32_16x16x32_bf16(Bt[n][k], At[m][k], acc[ai][bj][m][n], 0, 0, 0); __builtin_amdgcn_s_setprio(0); } while (0)
; #define PG8_WAIT_V(n) asm volatile("s_waitcnt vmcnt(" #n ")" ::: "memory")
; #define PG8_WAIT_L(n) asm volatile("s_waitcnt lgkmcnt(" #n ")" ::: "memory")
; #define PG8_BAR __builtin_amdgcn_s_barrier()
; #define PG8_SCHED __builtin_amdgcn_sched_barrier(0)
; template <class Epi, class Sched, bool ALIGN_EPI = false, bool SP2 = false>
; __device__ __forceinline__ void gemm_phase(PG8_LAS unsigned char* lds, const Gemm g, const Sched& S, const Epi& E) {
;     ...
;             PG8_LDB(B0, 1, 0); PG8_LDB(B1, 1, 1); PG8_SCHED; PG8_LDA(At, 1, 0); PG8_STAGE(PG8_SA(0, 1), a2 + hstep, voffA);
;             PG8_WAIT_V(8); PG8_WAIT_L(0); PG8_BAR; PG8_MMA(0, 0, At, B0); PG8_MMA(0, 1, At, B1); PG8_BAR; PG8_SCHED;
;             PG8_LDA(At, 1, 1); PG8_STAGE(PG8_SB(1, 0), b3, voffB); PG8_STAGE(PG8_SB(1, 1), b3 + hstep, voffB); PG8_STAGE(PG8_SA(1, 0), a3, voffA);
;             PG8_WAIT_V(8); PG8_WAIT_L(0); PG8_BAR; PG8_MMA(1, 0, At, B0); PG8_MMA(1, 1, At, B1); PG8_BAR; PG8_SCHED;
	s_add_i32 s78, 0, 0x18000
	s_add_i32 s79, 0, 0x1c000
	v_add_u32_e32 v68, s78, v153
	v_add_u32_e32 v168, s79, v153
	ds_read_b128 v[56:59], v68
	ds_read_b128 v[60:63], v68 offset:1024
	ds_read_b128 v[64:67], v68 offset:2048
	ds_read_b128 v[68:71], v68 offset:3072
	ds_read_b128 v[156:159], v168
	ds_read_b128 v[160:163], v168 offset:1024
	ds_read_b128 v[164:167], v168 offset:2048
	ds_read_b128 v[168:171], v168 offset:3072
	s_add_u32 s42, s42, 0x40000
	s_addc_u32 s43, s43, 0
	s_mov_b32 m0, s47
	v_lshl_add_u64 v[214:215], s[42:43], 0, v[184:185]
	ds_read_b128 v[172:175], v155 offset:32768
	ds_read_b128 v[176:179], v155 offset:33792
	ds_read_b128 v[180:183], v155 offset:34816
	ds_read_b128 v[190:193], v155 offset:35840
	ds_read_b128 v[194:197], v155 offset:36864
	ds_read_b128 v[198:201], v155 offset:37888
	ds_read_b128 v[202:205], v155 offset:38912
	ds_read_b128 v[206:209], v155 offset:39936
	global_load_lds_dwordx4 v[214:215], off
	v_lshl_add_u64 v[214:215], s[42:43], 0, v[144:145]
	s_mov_b32 m0, s48
	s_nop 0
	global_load_lds_dwordx4 v[214:215], off
	s_waitcnt vmcnt(8)
	s_waitcnt lgkmcnt(0)
	s_barrier
	s_waitcnt lgkmcnt(0)
	v_mfma_f32_16x16x32_bf16 v[140:143], v[56:59], v[172:175], v[140:143]
	v_mfma_f32_16x16x32_bf16 v[136:139], v[64:67], v[172:175], v[136:139]
	v_mfma_f32_16x16x32_bf16 v[124:127], v[56:59], v[180:183], v[124:127]
	v_mfma_f32_16x16x32_bf16 v[120:123], v[64:67], v[180:183], v[120:123]
	v_mfma_f32_16x16x32_bf16 v[108:111], v[56:59], v[194:197], v[108:111]
	v_mfma_f32_16x16x32_bf16 v[104:107], v[64:67], v[194:197], v[104:107]
	v_mfma_f32_16x16x32_bf16 v[92:95], v[56:59], v[202:205], v[92:95]
	v_mfma_f32_16x16x32_bf16 v[88:91], v[64:67], v[202:205], v[88:91]
	v_mfma_f32_16x16x32_bf16 v[140:143], v[60:63], v[176:179], v[140:143]
	v_mfma_f32_16x16x32_bf16 v[136:139], v[68:71], v[176:179], v[136:139]
	v_mfma_f32_16x16x32_bf16 v[124:127], v[60:63], v[190:193], v[124:127]
	v_mfma_f32_16x16x32_bf16 v[120:123], v[68:71], v[190:193], v[120:123]
	v_mfma_f32_16x16x32_bf16 v[108:111], v[60:63], v[198:201], v[108:111]
	v_mfma_f32_16x16x32_bf16 v[104:107], v[68:71], v[198:201], v[104:107]
	v_mfma_f32_16x16x32_bf16 v[92:95], v[60:63], v[206:209], v[92:95]
	v_mfma_f32_16x16x32_bf16 v[88:91], v[68:71], v[206:209], v[88:91]
	v_mfma_f32_16x16x32_bf16 v[132:135], v[156:159], v[172:175], v[132:135]
	v_mfma_f32_16x16x32_bf16 v[128:131], v[164:167], v[172:175], v[128:131]
	v_mfma_f32_16x16x32_bf16 v[116:119], v[156:159], v[180:183], v[116:119]
	v_mfma_f32_16x16x32_bf16 v[112:115], v[164:167], v[180:183], v[112:115]
	v_mfma_f32_16x16x32_bf16 v[100:103], v[156:159], v[194:197], v[100:103]
	v_mfma_f32_16x16x32_bf16 v[96:99], v[164:167], v[194:197], v[96:99]
	v_mfma_f32_16x16x32_bf16 v[84:87], v[156:159], v[202:205], v[84:87]
	v_mfma_f32_16x16x32_bf16 v[80:83], v[164:167], v[202:205], v[80:83]
	v_mfma_f32_16x16x32_bf16 v[132:135], v[160:163], v[176:179], v[132:135]
	v_mfma_f32_16x16x32_bf16 v[128:131], v[168:171], v[176:179], v[128:131]
	v_mfma_f32_16x16x32_bf16 v[116:119], v[160:163], v[190:193], v[116:119]
	v_mfma_f32_16x16x32_bf16 v[112:115], v[168:171], v[190:193], v[112:115]
	v_mfma_f32_16x16x32_bf16 v[100:103], v[160:163], v[198:201], v[100:103]
	v_mfma_f32_16x16x32_bf16 v[96:99], v[168:171], v[198:201], v[96:99]
	v_mfma_f32_16x16x32_bf16 v[84:87], v[160:163], v[206:209], v[84:87]
	v_mfma_f32_16x16x32_bf16 v[80:83], v[168:171], v[206:209], v[80:83]
	s_barrier
	s_add_i32 s42, s78, s44
	v_lshl_add_u64 v[150:151], v[150:151], 0, s[30:31]
	s_mov_b32 m0, s42
	ds_read_b128 v[172:175], v155 offset:49152
	ds_read_b128 v[176:179], v155 offset:50176
	ds_read_b128 v[180:183], v155 offset:51200
	ds_read_b128 v[190:193], v155 offset:52224
	ds_read_b128 v[194:197], v155 offset:53248
	ds_read_b128 v[198:201], v155 offset:54272
	ds_read_b128 v[202:205], v155 offset:55296
	ds_read_b128 v[206:209], v155 offset:56320
	global_load_lds_dwordx4 v[150:151], off
	s_add_i32 m0, s42, 0x2000
	s_add_u32 s36, s36, 0x40080
	v_lshl_add_u64 v[150:151], v[186:187], 0, s[30:31]
	s_addc_u32 s37, s37, 0
	s_add_i32 s42, s79, s44
	global_load_lds_dwordx4 v[150:151], off
	v_lshl_add_u64 v[150:151], s[36:37], 0, v[184:185]
	s_mov_b32 m0, s42
	s_nop 0
	global_load_lds_dwordx4 v[150:151], off
	v_lshl_add_u64 v[150:151], s[36:37], 0, v[144:145]
	s_add_i32 m0, s42, 0x2000
	s_nop 0
	global_load_lds_dwordx4 v[150:151], off
	v_lshl_add_u64 v[150:151], v[188:189], 0, s[30:31]
	s_mov_b32 m0, s49
	s_nop 0
	global_load_lds_dwordx4 v[150:151], off
	v_lshl_add_u64 v[150:151], v[210:211], 0, s[30:31]
	s_mov_b32 m0, s60
	s_nop 0
	global_load_lds_dwordx4 v[150:151], off
	s_waitcnt vmcnt(8)
	s_waitcnt lgkmcnt(0)
	s_barrier
	s_waitcnt lgkmcnt(0)
	v_mfma_f32_16x16x32_bf16 v[76:79], v[56:59], v[172:175], v[76:79]
	v_mfma_f32_16x16x32_bf16 v[72:75], v[64:67], v[172:175], v[72:75]
	v_mfma_f32_16x16x32_bf16 v[44:47], v[56:59], v[180:183], v[44:47]
	v_mfma_f32_16x16x32_bf16 v[40:43], v[64:67], v[180:183], v[40:43]
	v_mfma_f32_16x16x32_bf16 v[28:31], v[56:59], v[194:197], v[28:31]
	v_mfma_f32_16x16x32_bf16 v[24:27], v[64:67], v[194:197], v[24:27]
	v_mfma_f32_16x16x32_bf16 v[12:15], v[56:59], v[202:205], v[12:15]
	v_mfma_f32_16x16x32_bf16 v[8:11], v[64:67], v[202:205], v[8:11]
	v_mfma_f32_16x16x32_bf16 v[76:79], v[60:63], v[176:179], v[76:79]
	v_mfma_f32_16x16x32_bf16 v[72:75], v[68:71], v[176:179], v[72:75]
	v_mfma_f32_16x16x32_bf16 v[44:47], v[60:63], v[190:193], v[44:47]
	v_mfma_f32_16x16x32_bf16 v[40:43], v[68:71], v[190:193], v[40:43]
	v_mfma_f32_16x16x32_bf16 v[28:31], v[60:63], v[198:201], v[28:31]
	v_mfma_f32_16x16x32_bf16 v[24:27], v[68:71], v[198:201], v[24:27]
	v_mfma_f32_16x16x32_bf16 v[12:15], v[60:63], v[206:209], v[12:15]
	v_mfma_f32_16x16x32_bf16 v[8:11], v[68:71], v[206:209], v[8:11]
	v_mfma_f32_16x16x32_bf16 v[48:51], v[156:159], v[172:175], v[48:51]
	v_mfma_f32_16x16x32_bf16 v[60:63], v[160:163], v[176:179], v[48:51]
	v_mfma_f32_16x16x32_bf16 v[48:51], v[164:167], v[172:175], v[52:55]
	v_mfma_f32_16x16x32_bf16 v[36:39], v[156:159], v[180:183], v[36:39]
	v_mfma_f32_16x16x32_bf16 v[32:35], v[164:167], v[180:183], v[32:35]
	v_mfma_f32_16x16x32_bf16 v[20:23], v[156:159], v[194:197], v[20:23]
	v_mfma_f32_16x16x32_bf16 v[16:19], v[164:167], v[194:197], v[16:19]
	v_mfma_f32_16x16x32_bf16 v[4:7], v[156:159], v[202:205], v[4:7]
	v_mfma_f32_16x16x32_bf16 v[0:3], v[164:167], v[202:205], v[0:3]
	v_mfma_f32_16x16x32_bf16 v[56:59], v[168:171], v[176:179], v[48:51]
	v_mfma_f32_16x16x32_bf16 v[36:39], v[160:163], v[190:193], v[36:39]
	v_mfma_f32_16x16x32_bf16 v[32:35], v[168:171], v[190:193], v[32:35]
	v_mfma_f32_16x16x32_bf16 v[20:23], v[160:163], v[198:201], v[20:23]
	v_mfma_f32_16x16x32_bf16 v[16:19], v[168:171], v[198:201], v[16:19]
	v_mfma_f32_16x16x32_bf16 v[4:7], v[160:163], v[206:209], v[4:7]
	v_mfma_f32_16x16x32_bf16 v[0:3], v[168:171], v[206:209], v[0:3]
	s_barrier
	s_add_i32 s77, s77, 2
	s_add_u32 s24, s24, 0x100
	s_addc_u32 s25, s25, 0
	s_add_u32 s73, s73, 0x100
	s_addc_u32 s76, s76, 0
	s_cmp_gt_u32 s77, 13
	s_cbranch_scc0 .LBB0_374
; #define PG8_BAR __builtin_amdgcn_s_barrier()
; template <class Epi, class Sched, bool ALIGN_EPI = false, bool SP2 = false>
; __device__ __forceinline__ void gemm_phase(PG8_LAS unsigned char* lds, const Gemm g, const Sched& S, const Epi& E) {
;     ...
;         if constexpr (ALIGN_EPI) { if (wr == 0) PG8_BAR; }
;         if constexpr (!Epi::AFTER_DRAIN) { E(acc, cur, wr, wc, fr, fq); S.done(cur); }
.Lgzero1_done:
	s_setprio 0
	s_and_b64 vcc, exec, s[14:15]
	s_cbranch_vccz .LBB0_377
	s_barrier

;     __host__ __device__ bool next(int i, Unit& u) const { Unit m; if (!S.next(i >> 1, m)) return false; u.pm = m.pm; u.pn = m.pn + 4 * (i & 1); return true; }
;     __host__ __device__ bool next(int i, Unit& u) const { Unit m; if (!S.next(i >> 1, m)) return false; u.pm = m.pm + (i & 1) * dpm; u.pn = m.pn + (i & 1) * dpn; return true; }
; #define PG8_STAGE(bufoff, gbase, voff) do { _Pragma("unroll") for (int _i = 0; _i < 2; ++_i) \
;         __builtin_amdgcn_global_load_lds((const unsigned*)((const char*)(gbase) + (voff)[_i]), (PG8_LAS unsigned*)(lds + (bufoff) + ldsw + _i * 8192), 16, 0, 0); } while (0)
; #define PG8_LDA(dst, b, h) do { _Pragma("unroll") for (int m = 0; m < 4; ++m) _Pragma("unroll") for (int k = 0; k < 2; ++k) dst[m][k] = *(const PG8_LAS bf16x8*)(lds + PG8_SA(b, h) + aoff + m * 2048 + k * 1024); } while (0)
; #define PG8_WAIT_V(n) asm volatile("s_waitcnt vmcnt(" #n ")" ::: "memory")
; #define PG8_WAIT_L(n) asm volatile("s_waitcnt lgkmcnt(" #n ")" ::: "memory")
; template <class Epi, class Sched, bool ALIGN_EPI = false, bool SP2 = false>
; __device__ __forceinline__ void gemm_phase(PG8_LAS unsigned char* lds, const Gemm g, const Sched& S, const Epi& E) {
;     ...
;         const bool has_next = S.next(ui + 1, nxt);
;         const char* nA = has_next ? (const char*)g.A + (size_t)nxt.pm * tstep : cA; const char* nB = has_next ? (const char*)g.Bt + (size_t)nxt.pn * tstep : cB;
;         for (int t = 0; t < nt; t += 2) {
;             const bool last = (t == nt - 2);
;             const char* a1 = cA + (size_t)(t + 1) * kstep;
;             const char* a2 = last ? nA : cA + (size_t)(t + 2) * kstep; const char* b2 = last ? nB : cB + (size_t)(t + 2) * kstep;
;             const char* a3 = a2 + kstep; const char* b3 = b2 + kstep;
;             if (last && has_next) S.a_ready(nxt);
;             if constexpr (SP2) {
;             PG8_LDB(B0, 0, 0); PG8_LDB(B1, 0, 1); PG8_SCHED; PG8_LDA(At, 0, 0); PG8_STAGE(PG8_SA(1, 1), a1 + hstep, voffA);
;             PG8_WAIT_V(8); PG8_WAIT_L(0); PG8_BAR; PG8_MMA(0, 0, At, B0); PG8_MMA(0, 1, At, B1); PG8_BAR; PG8_SCHED;
;             PG8_LDA(At, 0, 1); PG8_STAGE(PG8_SB(0, 0), b2, voffB); PG8_STAGE(PG8_SB(0, 1), b2 + hstep, voffB); PG8_STAGE(PG8_SA(0, 0), a2, voffA);
;             PG8_WAIT_V(8); PG8_WAIT_L(0); PG8_BAR; PG8_MMA(1, 0, At, B0); PG8_MMA(1, 1, At, B1); PG8_BAR; PG8_SCHED;
.LBB0_394:
	s_ashr_i32 s15, s14, 31
	s_lshl_b64 s[18:19], s[14:15], 18
	s_add_u32 s18, s91, s18
	s_addc_u32 s19, s81, s19
	s_and_b64 s[20:21], s[6:7], exec
	s_cselect_b32 s15, s19, s23
	s_cselect_b32 s69, s18, s22
	s_ashr_i32 s17, s16, 31
	s_lshl_b64 s[20:21], s[16:17], 18
	s_add_u32 s20, s28, s20
	s_addc_u32 s21, s29, s21
	s_and_b64 s[36:37], s[6:7], exec
	s_cselect_b32 s17, s21, s25
	s_cselect_b32 s70, s20, s24
	s_add_u32 s22, s22, 0x20080
	s_addc_u32 s23, s23, 0
	s_add_u32 s71, s24, 0x100
	s_addc_u32 s72, s25, 0
	s_mov_b32 s73, -2
	v_cmp_lt_u32_e32 vcc, 0xff, v212
	s_cbranch_vccz .Lgprio2
	s_setprio 1
.Lgprio2:
	s_add_u32 s24, s22, 0xfffe0080
	s_addc_u32 s25, s23, -1
	s_add_i32 s76, 0, 0x10000
	s_cmp_eq_u32 s73, 4
	s_cselect_b32 s37, s15, s25
	s_cselect_b32 s36, s69, s24
	s_cselect_b32 s25, s17, s72
	s_cselect_b32 s24, s70, s71
	s_add_i32 s78, 0, 0x14000
	v_add_u32_e32 v140, s76, v224
	v_add_u32_e32 v156, s78, v224
	ds_read_b128 v[128:131], v140
	ds_read_b128 v[132:135], v140 offset:1024
	ds_read_b128 v[136:139], v140 offset:2048
	ds_read_b128 v[140:143], v140 offset:3072
	ds_read_b128 v[144:147], v156
	ds_read_b128 v[148:151], v156 offset:1024
	ds_read_b128 v[152:155], v156 offset:2048
	ds_read_b128 v[156:159], v156 offset:3072
	v_lshl_add_u64 v[186:187], s[22:23], 0, v[192:193]
	s_add_i32 m0, s43, 0xc000
	ds_read_b128 v[160:163], v228
	ds_read_b128 v[164:167], v228 offset:1024
	ds_read_b128 v[168:171], v228 offset:2048
	ds_read_b128 v[172:175], v228 offset:3072
	ds_read_b128 v[176:179], v228 offset:4096
	ds_read_b128 v[180:183], v228 offset:5120
	ds_read_b128 v[196:199], v228 offset:6144
	ds_read_b128 v[200:203], v228 offset:7168
	global_load_lds_dwordx4 v[186:187], off
	v_lshl_add_u64 v[186:187], s[22:23], 0, v[194:195]
	s_add_i32 m0, s43, 0xe000
	s_nop 0
	global_load_lds_dwordx4 v[186:187], off
	s_waitcnt vmcnt(8)
	s_waitcnt lgkmcnt(0)
	s_barrier
	s_waitcnt lgkmcnt(0)
	v_mfma_f32_16x16x32_bf16 v[124:127], v[128:131], v[160:163], 0
	v_mfma_f32_16x16x32_bf16 v[120:123], v[136:139], v[160:163], 0
	v_mfma_f32_16x16x32_bf16 v[108:111], v[128:131], v[168:171], 0
	v_mfma_f32_16x16x32_bf16 v[104:107], v[136:139], v[168:171], 0
	v_mfma_f32_16x16x32_bf16 v[96:99], v[128:131], v[176:179], 0
	v_mfma_f32_16x16x32_bf16 v[88:91], v[136:139], v[176:179], 0
	v_mfma_f32_16x16x32_bf16 v[80:83], v[128:131], v[196:199], 0
	v_mfma_f32_16x16x32_bf16 v[72:75], v[136:139], v[196:199], 0
	v_mfma_f32_16x16x32_bf16 v[124:127], v[132:135], v[164:167], v[124:127]
	v_mfma_f32_16x16x32_bf16 v[120:123], v[140:143], v[164:167], v[120:123]
	v_mfma_f32_16x16x32_bf16 v[108:111], v[132:135], v[172:175], v[108:111]
	v_mfma_f32_16x16x32_bf16 v[104:107], v[140:143], v[172:175], v[104:107]
	v_mfma_f32_16x16x32_bf16 v[96:99], v[132:135], v[180:183], v[96:99]
	v_mfma_f32_16x16x32_bf16 v[88:91], v[140:143], v[180:183], v[88:91]
	v_mfma_f32_16x16x32_bf16 v[80:83], v[132:135], v[200:203], v[80:83]
	v_mfma_f32_16x16x32_bf16 v[72:75], v[140:143], v[200:203], v[72:75]
	v_mfma_f32_16x16x32_bf16 v[116:119], v[144:147], v[160:163], 0
	v_mfma_f32_16x16x32_bf16 v[112:115], v[152:155], v[160:163], 0
	v_mfma_f32_16x16x32_bf16 v[100:103], v[144:147], v[168:171], 0
	v_mfma_f32_16x16x32_bf16 v[92:95], v[152:155], v[168:171], 0
	v_mfma_f32_16x16x32_bf16 v[84:87], v[144:147], v[176:179], 0
	v_mfma_f32_16x16x32_bf16 v[76:79], v[152:155], v[176:179], 0
	v_mfma_f32_16x16x32_bf16 v[68:71], v[144:147], v[196:199], 0
	v_mfma_f32_16x16x32_bf16 v[64:67], v[152:155], v[196:199], 0
	v_mfma_f32_16x16x32_bf16 v[116:119], v[148:151], v[164:167], v[116:119]
	v_mfma_f32_16x16x32_bf16 v[112:115], v[156:159], v[164:167], v[112:115]
	v_mfma_f32_16x16x32_bf16 v[100:103], v[148:151], v[172:175], v[100:103]
	v_mfma_f32_16x16x32_bf16 v[92:95], v[156:159], v[172:175], v[92:95]
	v_mfma_f32_16x16x32_bf16 v[84:87], v[148:151], v[180:183], v[84:87]
	v_mfma_f32_16x16x32_bf16 v[76:79], v[156:159], v[180:183], v[76:79]
	v_mfma_f32_16x16x32_bf16 v[68:71], v[148:151], v[200:203], v[68:71]
	v_mfma_f32_16x16x32_bf16 v[64:67], v[156:159], v[200:203], v[64:67]
	s_barrier
	s_add_i32 s76, s76, s42
	v_lshl_add_u64 v[186:187], s[24:25], 0, v[184:185]
	s_mov_b32 m0, s76
	ds_read_b128 v[160:163], v228 offset:16384
	ds_read_b128 v[164:167], v228 offset:17408
	ds_read_b128 v[168:171], v228 offset:18432
	ds_read_b128 v[172:175], v228 offset:19456
	ds_read_b128 v[176:179], v228 offset:20480
	ds_read_b128 v[180:183], v228 offset:21504
	ds_read_b128 v[196:199], v228 offset:22528
	ds_read_b128 v[200:203], v228 offset:23552
	global_load_lds_dwordx4 v[186:187], off
	s_add_i32 m0, s76, 0x2000
	s_add_u32 s76, s24, 0x20000
	v_lshl_add_u64 v[188:189], s[24:25], 0, v[190:191]
	s_addc_u32 s77, s25, 0
	s_add_i32 s78, s78, s42
	global_load_lds_dwordx4 v[188:189], off
	v_lshl_add_u64 v[204:205], s[76:77], 0, v[184:185]
	s_mov_b32 m0, s78
	v_lshl_add_u64 v[206:207], s[36:37], 0, v[190:191]
	global_load_lds_dwordx4 v[204:205], off
	v_lshl_add_u64 v[204:205], s[76:77], 0, v[190:191]
	s_add_i32 m0, s78, 0x2000
	s_nop 0
	global_load_lds_dwordx4 v[204:205], off
	v_lshl_add_u64 v[204:205], s[36:37], 0, v[184:185]
	s_mov_b32 m0, s43
	s_nop 0
	global_load_lds_dwordx4 v[204:205], off
	s_mov_b32 m0, s44
	s_nop 0
	global_load_lds_dwordx4 v[206:207], off
	s_waitcnt vmcnt(8)
	s_waitcnt lgkmcnt(0)
	s_barrier
; #define PG8_STAGE(bufoff, gbase, voff) do { _Pragma("unroll") for (int _i = 0; _i < 2; ++_i) \
;         __builtin_amdgcn_global_load_lds((const unsigned*)((const char*)(gbase) + (voff)[_i]), (PG8_LAS unsigned*)(lds + (bufoff) + ldsw + _i * 8192), 16, 0, 0); } while (0)
; #define PG8_LDA(dst, b, h) do { _Pragma("unroll") for (int m = 0; m < 4; ++m) _Pragma("unroll") for (int k = 0; k < 2; ++k) dst[m][k] = *(const PG8_LAS bf16x8*)(lds + PG8_SA(b, h) + aoff + m * 2048 + k * 1024); } while (0)
; #define PG8_LDB(dst, b, h) do { _Pragma("unroll") for (int n = 0; n < 2; ++n) _Pragma("unroll") for (int k = 0; k < 2; ++k) dst[n][k] = *(const PG8_LAS bf16x8*)(lds + PG8_SB(b, h) + boff + n * 2048 + k * 1024); } while (0)
; #define PG8_MMA(ai, bj, At, Bt) do { __builtin_amdgcn_s_setprio(1); _Pragma("unroll") for (int m = 0; m < 4; ++m) _Pragma("unroll") for (int n = 0; n < 2; ++n) _Pragma("unroll") for (int k = 0; k < 2; ++k) \
;         acc[ai][bj][m][n] = __builtin_amdgcn_mfma_f32_16x16x32_bf16(Bt[n][k], At[m][k], acc[ai][bj][m][n], 0, 0, 0); __builtin_amdgcn_s_setprio(0); } while (0)
; #define PG8_WAIT_V(n) asm volatile("s_waitcnt vmcnt(" #n ")" ::: "memory")
; #define PG8_WAIT_L(n) asm volatile("s_waitcnt lgkmcnt(" #n ")" ::: "memory")
; #define PG8_BAR __builtin_amdgcn_s_barrier()
; #define PG8_SCHED __builtin_amdgcn_sched_barrier(0)
; template <class Epi, class Sched, bool ALIGN_EPI = false, bool SP2 = false>
; __device__ __forceinline__ void gemm_phase(PG8_LAS unsigned char* lds, const Gemm g, const Sched& S, const Epi& E) {
;     ...
;             PG8_WAIT_V(8); PG8_WAIT_L(0); PG8_BAR; PG8_MMA(1, 0, At, B0); PG8_MMA(1, 1, At, B1); PG8_BAR; PG8_SCHED;
;             PG8_LDB(B0, 1, 0); PG8_LDB(B1, 1, 1); PG8_SCHED; PG8_LDA(At, 1, 0); PG8_STAGE(PG8_SA(0, 1), a2 + hstep, voffA);
;             PG8_WAIT_V(8); PG8_WAIT_L(0); PG8_BAR; PG8_MMA(0, 0, At, B0); PG8_MMA(0, 1, At, B1); PG8_BAR; PG8_SCHED;
	s_waitcnt lgkmcnt(0)
	v_mfma_f32_16x16x32_bf16 v[60:63], v[128:131], v[160:163], 0
	v_mfma_f32_16x16x32_bf16 v[56:59], v[136:139], v[160:163], 0
	v_mfma_f32_16x16x32_bf16 v[48:51], v[128:131], v[168:171], 0
	v_mfma_f32_16x16x32_bf16 v[40:43], v[136:139], v[168:171], 0
	v_mfma_f32_16x16x32_bf16 v[32:35], v[128:131], v[176:179], 0
	v_mfma_f32_16x16x32_bf16 v[24:27], v[136:139], v[176:179], 0
	v_mfma_f32_16x16x32_bf16 v[16:19], v[128:131], v[196:199], 0
	v_mfma_f32_16x16x32_bf16 v[8:11], v[136:139], v[196:199], 0
	v_mfma_f32_16x16x32_bf16 v[60:63], v[132:135], v[164:167], v[60:63]
	v_mfma_f32_16x16x32_bf16 v[56:59], v[140:143], v[164:167], v[56:59]
	v_mfma_f32_16x16x32_bf16 v[48:51], v[132:135], v[172:175], v[48:51]
	v_mfma_f32_16x16x32_bf16 v[40:43], v[140:143], v[172:175], v[40:43]
	v_mfma_f32_16x16x32_bf16 v[32:35], v[132:135], v[180:183], v[32:35]
	v_mfma_f32_16x16x32_bf16 v[24:27], v[140:143], v[180:183], v[24:27]
	v_mfma_f32_16x16x32_bf16 v[16:19], v[132:135], v[200:203], v[16:19]
	v_mfma_f32_16x16x32_bf16 v[8:11], v[140:143], v[200:203], v[8:11]
	v_mfma_f32_16x16x32_bf16 v[52:55], v[144:147], v[160:163], 0
	v_mfma_f32_16x16x32_bf16 v[44:47], v[152:155], v[160:163], 0
	v_mfma_f32_16x16x32_bf16 v[36:39], v[144:147], v[168:171], 0
	v_mfma_f32_16x16x32_bf16 v[28:31], v[152:155], v[168:171], 0
	v_mfma_f32_16x16x32_bf16 v[20:23], v[144:147], v[176:179], 0
	v_mfma_f32_16x16x32_bf16 v[12:15], v[152:155], v[176:179], 0
	v_mfma_f32_16x16x32_bf16 v[4:7], v[144:147], v[196:199], 0
	v_mfma_f32_16x16x32_bf16 v[0:3], v[152:155], v[196:199], 0
	v_mfma_f32_16x16x32_bf16 v[52:55], v[148:151], v[164:167], v[52:55]
	v_mfma_f32_16x16x32_bf16 v[44:47], v[156:159], v[164:167], v[44:47]
	v_mfma_f32_16x16x32_bf16 v[36:39], v[148:151], v[172:175], v[36:39]
	v_mfma_f32_16x16x32_bf16 v[28:31], v[156:159], v[172:175], v[28:31]
	v_mfma_f32_16x16x32_bf16 v[20:23], v[148:151], v[180:183], v[20:23]
	v_mfma_f32_16x16x32_bf16 v[12:15], v[156:159], v[180:183], v[12:15]
	v_mfma_f32_16x16x32_bf16 v[4:7], v[148:151], v[200:203], v[4:7]
	v_mfma_f32_16x16x32_bf16 v[0:3], v[156:159], v[200:203], v[0:3]
	s_barrier
	s_add_i32 s76, 0, 0x18000
	s_add_i32 s77, 0, 0x1c000
	v_add_u32_e32 v140, s76, v224
	v_add_u32_e32 v156, s77, v224
	ds_read_b128 v[128:131], v140
	ds_read_b128 v[132:135], v140 offset:1024
	ds_read_b128 v[136:139], v140 offset:2048
	ds_read_b128 v[140:143], v140 offset:3072
	ds_read_b128 v[144:147], v156
	ds_read_b128 v[148:151], v156 offset:1024
	ds_read_b128 v[152:155], v156 offset:2048
	ds_read_b128 v[156:159], v156 offset:3072
	s_add_u32 s36, s36, 0x20000
	s_addc_u32 s37, s37, 0
	s_mov_b32 m0, s45
	v_lshl_add_u64 v[208:209], s[36:37], 0, v[184:185]
	ds_read_b128 v[160:163], v228 offset:32768
	ds_read_b128 v[164:167], v228 offset:33792
	ds_read_b128 v[168:171], v228 offset:34816
	ds_read_b128 v[172:175], v228 offset:35840
	ds_read_b128 v[176:179], v228 offset:36864
	ds_read_b128 v[180:183], v228 offset:37888
	ds_read_b128 v[196:199], v228 offset:38912
	ds_read_b128 v[200:203], v228 offset:39936
	global_load_lds_dwordx4 v[208:209], off
	v_lshl_add_u64 v[208:209], s[36:37], 0, v[190:191]
	s_mov_b32 m0, s46
	s_nop 0
	global_load_lds_dwordx4 v[208:209], off
	s_waitcnt vmcnt(8)
	s_waitcnt lgkmcnt(0)
	s_barrier
	s_waitcnt lgkmcnt(0)
	v_mfma_f32_16x16x32_bf16 v[124:127], v[128:131], v[160:163], v[124:127]
	v_mfma_f32_16x16x32_bf16 v[120:123], v[136:139], v[160:163], v[120:123]
	v_mfma_f32_16x16x32_bf16 v[108:111], v[128:131], v[168:171], v[108:111]
	v_mfma_f32_16x16x32_bf16 v[104:107], v[136:139], v[168:171], v[104:107]
	v_mfma_f32_16x16x32_bf16 v[96:99], v[128:131], v[176:179], v[96:99]
	v_mfma_f32_16x16x32_bf16 v[88:91], v[136:139], v[176:179], v[88:91]
	v_mfma_f32_16x16x32_bf16 v[80:83], v[128:131], v[196:199], v[80:83]
	v_mfma_f32_16x16x32_bf16 v[72:75], v[136:139], v[196:199], v[72:75]
	v_mfma_f32_16x16x32_bf16 v[124:127], v[132:135], v[164:167], v[124:127]
	v_mfma_f32_16x16x32_bf16 v[120:123], v[140:143], v[164:167], v[120:123]
	v_mfma_f32_16x16x32_bf16 v[108:111], v[132:135], v[172:175], v[108:111]
	v_mfma_f32_16x16x32_bf16 v[104:107], v[140:143], v[172:175], v[104:107]
	v_mfma_f32_16x16x32_bf16 v[96:99], v[132:135], v[180:183], v[96:99]
	v_mfma_f32_16x16x32_bf16 v[88:91], v[140:143], v[180:183], v[88:91]
	v_mfma_f32_16x16x32_bf16 v[80:83], v[132:135], v[200:203], v[80:83]
	v_mfma_f32_16x16x32_bf16 v[72:75], v[140:143], v[200:203], v[72:75]
	v_mfma_f32_16x16x32_bf16 v[116:119], v[144:147], v[160:163], v[116:119]
	v_mfma_f32_16x16x32_bf16 v[112:115], v[152:155], v[160:163], v[112:115]
	v_mfma_f32_16x16x32_bf16 v[100:103], v[144:147], v[168:171], v[100:103]
	v_mfma_f32_16x16x32_bf16 v[92:95], v[152:155], v[168:171], v[92:95]
	v_mfma_f32_16x16x32_bf16 v[84:87], v[144:147], v[176:179], v[84:87]
	v_mfma_f32_16x16x32_bf16 v[76:79], v[152:155], v[176:179], v[76:79]
	v_mfma_f32_16x16x32_bf16 v[68:71], v[144:147], v[196:199], v[68:71]
	v_mfma_f32_16x16x32_bf16 v[64:67], v[152:155], v[196:199], v[64:67]
	v_mfma_f32_16x16x32_bf16 v[116:119], v[148:151], v[164:167], v[116:119]
	v_mfma_f32_16x16x32_bf16 v[112:115], v[156:159], v[164:167], v[112:115]
	v_mfma_f32_16x16x32_bf16 v[100:103], v[148:151], v[172:175], v[100:103]
	v_mfma_f32_16x16x32_bf16 v[92:95], v[156:159], v[172:175], v[92:95]
	v_mfma_f32_16x16x32_bf16 v[84:87], v[148:151], v[180:183], v[84:87]
	v_mfma_f32_16x16x32_bf16 v[76:79], v[156:159], v[180:183], v[76:79]
	v_mfma_f32_16x16x32_bf16 v[68:71], v[148:151], v[200:203], v[68:71]
	v_mfma_f32_16x16x32_bf16 v[64:67], v[156:159], v[200:203], v[64:67]
	s_barrier
; #define PG8_STAGE(bufoff, gbase, voff) do { _Pragma("unroll") for (int _i = 0; _i < 2; ++_i) \
;         __builtin_amdgcn_global_load_lds((const unsigned*)((const char*)(gbase) + (voff)[_i]), (PG8_LAS unsigned*)(lds + (bufoff) + ldsw + _i * 8192), 16, 0, 0); } while (0)
; #define PG8_LDA(dst, b, h) do { _Pragma("unroll") for (int m = 0; m < 4; ++m) _Pragma("unroll") for (int k = 0; k < 2; ++k) dst[m][k] = *(const PG8_LAS bf16x8*)(lds + PG8_SA(b, h) + aoff + m * 2048 + k * 1024); } while (0)
; #define PG8_LDB(dst, b, h) do { _Pragma("unroll") for (int n = 0; n < 2; ++n) _Pragma("unroll") for (int k = 0; k < 2; ++k) dst[n][k] = *(const PG8_LAS bf16x8*)(lds + PG8_SB(b, h) + boff + n * 2048 + k * 1024); } while (0)
; #define PG8_MMA(ai, bj, At, Bt) do { __builtin_amdgcn_s_setprio(1); _Pragma("unroll") for (int m = 0; m < 4; ++m) _Pragma("unroll") for (int n = 0; n < 2; ++n) _Pragma("unroll") for (int k = 0; k < 2; ++k) \
;         acc[ai][bj][m][n] = __builtin_amdgcn_mfma_f32_16x16x32_bf16(Bt[n][k], At[m][k], acc[ai][bj][m][n], 0, 0, 0); __builtin_amdgcn_s_setprio(0); } while (0)
; #define PG8_WAIT_V(n) asm volatile("s_waitcnt vmcnt(" #n ")" ::: "memory")
; #define PG8_WAIT_L(n) asm volatile("s_waitcnt lgkmcnt(" #n ")" ::: "memory")
; #define PG8_BAR __builtin_amdgcn_s_barrier()
; #define PG8_SCHED __builtin_amdgcn_sched_barrier(0)
; template <class Epi, class Sched, bool ALIGN_EPI = false, bool SP2 = false>
; __device__ __forceinline__ void gemm_phase(PG8_LAS unsigned char* lds, const Gemm g, const Sched& S, const Epi& E) {
;     ...
;             PG8_LDB(B0, 0, 0); PG8_LDB(B1, 0, 1); PG8_SCHED; PG8_LDA(At, 0, 0); PG8_STAGE(PG8_SA(1, 1), a1 + hstep, voffA);
;             PG8_WAIT_V(8); PG8_WAIT_L(0); PG8_BAR; PG8_MMA(0, 0, At, B0); PG8_MMA(0, 1, At, B1); PG8_BAR; PG8_SCHED;
;     ...
;             PG8_LDA(At, 1, 1); PG8_STAGE(PG8_SB(1, 0), b3, voffB); PG8_STAGE(PG8_SB(1, 1), b3 + hstep, voffB); PG8_STAGE(PG8_SA(1, 0), a3, voffA);
;             PG8_WAIT_V(8); PG8_WAIT_L(0); PG8_BAR; PG8_MMA(1, 0, At, B0); PG8_MMA(1, 1, At, B1); PG8_BAR; PG8_SCHED;
	s_add_i32 s36, s76, s42
	v_lshl_add_u64 v[186:187], v[186:187], 0, s[30:31]
	s_mov_b32 m0, s36
	ds_read_b128 v[160:163], v228 offset:49152
	ds_read_b128 v[164:167], v228 offset:50176
	ds_read_b128 v[168:171], v228 offset:51200
	ds_read_b128 v[172:175], v228 offset:52224
	ds_read_b128 v[176:179], v228 offset:53248
	ds_read_b128 v[180:183], v228 offset:54272
	ds_read_b128 v[196:199], v228 offset:55296
	ds_read_b128 v[200:203], v228 offset:56320
	global_load_lds_dwordx4 v[186:187], off
	s_add_i32 m0, s36, 0x2000
	s_add_u32 s24, s24, 0x20080
	v_lshl_add_u64 v[186:187], v[188:189], 0, s[30:31]
	s_addc_u32 s25, s25, 0
	s_add_i32 s36, s77, s42
	global_load_lds_dwordx4 v[186:187], off
	v_lshl_add_u64 v[186:187], s[24:25], 0, v[184:185]
	s_mov_b32 m0, s36
	s_nop 0
	global_load_lds_dwordx4 v[186:187], off
	v_lshl_add_u64 v[186:187], s[24:25], 0, v[190:191]
	s_add_i32 m0, s36, 0x2000
	s_nop 0
	global_load_lds_dwordx4 v[186:187], off
	v_lshl_add_u64 v[186:187], v[204:205], 0, s[30:31]
	s_mov_b32 m0, s47
	s_nop 0
	global_load_lds_dwordx4 v[186:187], off
	v_lshl_add_u64 v[186:187], v[206:207], 0, s[30:31]
	s_mov_b32 m0, s48
	s_nop 0
	global_load_lds_dwordx4 v[186:187], off
	s_waitcnt vmcnt(8)
	s_waitcnt lgkmcnt(0)
	s_barrier
	s_waitcnt lgkmcnt(0)
	v_mfma_f32_16x16x32_bf16 v[60:63], v[128:131], v[160:163], v[60:63]
	v_mfma_f32_16x16x32_bf16 v[56:59], v[136:139], v[160:163], v[56:59]
	v_mfma_f32_16x16x32_bf16 v[48:51], v[128:131], v[168:171], v[48:51]
	v_mfma_f32_16x16x32_bf16 v[40:43], v[136:139], v[168:171], v[40:43]
	v_mfma_f32_16x16x32_bf16 v[32:35], v[128:131], v[176:179], v[32:35]
	v_mfma_f32_16x16x32_bf16 v[24:27], v[136:139], v[176:179], v[24:27]
	v_mfma_f32_16x16x32_bf16 v[16:19], v[128:131], v[196:199], v[16:19]
	v_mfma_f32_16x16x32_bf16 v[8:11], v[136:139], v[196:199], v[8:11]
	v_mfma_f32_16x16x32_bf16 v[60:63], v[132:135], v[164:167], v[60:63]
	v_mfma_f32_16x16x32_bf16 v[56:59], v[140:143], v[164:167], v[56:59]
	v_mfma_f32_16x16x32_bf16 v[48:51], v[132:135], v[172:175], v[48:51]
	v_mfma_f32_16x16x32_bf16 v[40:43], v[140:143], v[172:175], v[40:43]
	v_mfma_f32_16x16x32_bf16 v[32:35], v[132:135], v[180:183], v[32:35]
	v_mfma_f32_16x16x32_bf16 v[24:27], v[140:143], v[180:183], v[24:27]
	v_mfma_f32_16x16x32_bf16 v[16:19], v[132:135], v[200:203], v[16:19]
	v_mfma_f32_16x16x32_bf16 v[8:11], v[140:143], v[200:203], v[8:11]
	v_mfma_f32_16x16x32_bf16 v[52:55], v[144:147], v[160:163], v[52:55]
	v_mfma_f32_16x16x32_bf16 v[44:47], v[152:155], v[160:163], v[44:47]
	v_mfma_f32_16x16x32_bf16 v[36:39], v[144:147], v[168:171], v[36:39]
	v_mfma_f32_16x16x32_bf16 v[28:31], v[152:155], v[168:171], v[28:31]
	v_mfma_f32_16x16x32_bf16 v[20:23], v[144:147], v[176:179], v[20:23]
	v_mfma_f32_16x16x32_bf16 v[12:15], v[152:155], v[176:179], v[12:15]
	v_mfma_f32_16x16x32_bf16 v[4:7], v[144:147], v[196:199], v[4:7]
	v_mfma_f32_16x16x32_bf16 v[0:3], v[152:155], v[196:199], v[0:3]
	v_mfma_f32_16x16x32_bf16 v[52:55], v[148:151], v[164:167], v[52:55]
	v_mfma_f32_16x16x32_bf16 v[44:47], v[156:159], v[164:167], v[44:47]
	v_mfma_f32_16x16x32_bf16 v[36:39], v[148:151], v[172:175], v[36:39]
	v_mfma_f32_16x16x32_bf16 v[28:31], v[156:159], v[172:175], v[28:31]
	v_mfma_f32_16x16x32_bf16 v[20:23], v[148:151], v[180:183], v[20:23]
	v_mfma_f32_16x16x32_bf16 v[12:15], v[156:159], v[180:183], v[12:15]
	v_mfma_f32_16x16x32_bf16 v[4:7], v[148:151], v[200:203], v[4:7]
	v_mfma_f32_16x16x32_bf16 v[0:3], v[156:159], v[200:203], v[0:3]
	s_barrier
	s_add_i32 s73, s73, 2
	s_add_u32 s22, s22, 0x100
	s_addc_u32 s23, s23, 0
	s_add_u32 s71, s71, 0x100
	s_addc_u32 s72, s72, 0
	s_cmp_gt_u32 s73, 5
	s_cbranch_scc0 .LBB0_395
	s_branch .Lgzero2_done
.LBB0_395:
	s_add_u32 s24, s22, 0xfffe0080
	s_addc_u32 s25, s23, -1
	s_add_i32 s76, 0, 0x10000
	s_cmp_eq_u32 s73, 4
	s_cselect_b32 s37, s15, s25
	s_cselect_b32 s36, s69, s24
	s_cselect_b32 s25, s17, s72
	s_cselect_b32 s24, s70, s71
	s_add_i32 s78, 0, 0x14000
	v_add_u32_e32 v140, s76, v224
	v_add_u32_e32 v156, s78, v224
	ds_read_b128 v[128:131], v140
	ds_read_b128 v[132:135], v140 offset:1024
	ds_read_b128 v[136:139], v140 offset:2048
	ds_read_b128 v[140:143], v140 offset:3072
	ds_read_b128 v[144:147], v156
	ds_read_b128 v[148:151], v156 offset:1024
	ds_read_b128 v[152:155], v156 offset:2048
	ds_read_b128 v[156:159], v156 offset:3072
	v_lshl_add_u64 v[186:187], s[22:23], 0, v[192:193]
	s_add_i32 m0, s43, 0xc000
	ds_read_b128 v[160:163], v228
	ds_read_b128 v[164:167], v228 offset:1024
	ds_read_b128 v[168:171], v228 offset:2048
	ds_read_b128 v[172:175], v228 offset:3072
	ds_read_b128 v[176:179], v228 offset:4096
	ds_read_b128 v[180:183], v228 offset:5120
	ds_read_b128 v[196:199], v228 offset:6144
	ds_read_b128 v[200:203], v228 offset:7168
	global_load_lds_dwordx4 v[186:187], off
	v_lshl_add_u64 v[186:187], s[22:23], 0, v[194:195]
	s_add_i32 m0, s43, 0xe000
	s_nop 0
	global_load_lds_dwordx4 v[186:187], off
	s_waitcnt vmcnt(8)
	s_waitcnt lgkmcnt(0)
	s_barrier
; #define PG8_STAGE(bufoff, gbase, voff) do { _Pragma("unroll") for (int _i = 0; _i < 2; ++_i) \
;         __builtin_amdgcn_global_load_lds((const unsigned*)((const char*)(gbase) + (voff)[_i]), (PG8_LAS unsigned*)(lds + (bufoff) + ldsw + _i * 8192), 16, 0, 0); } while (0)
; #define PG8_LDA(dst, b, h) do { _Pragma("unroll") for (int m = 0; m < 4; ++m) _Pragma("unroll") for (int k = 0; k < 2; ++k) dst[m][k] = *(const PG8_LAS bf16x8*)(lds + PG8_SA(b, h) + aoff + m * 2048 + k * 1024); } while (0)
; #define PG8_LDB(dst, b, h) do { _Pragma("unroll") for (int n = 0; n < 2; ++n) _Pragma("unroll") for (int k = 0; k < 2; ++k) dst[n][k] = *(const PG8_LAS bf16x8*)(lds + PG8_SB(b, h) + boff + n * 2048 + k * 1024); } while (0)
; #define PG8_MMA(ai, bj, At, Bt) do { __builtin_amdgcn_s_setprio(1); _Pragma("unroll") for (int m = 0; m < 4; ++m) _Pragma("unroll") for (int n = 0; n < 2; ++n) _Pragma("unroll") for (int k = 0; k < 2; ++k) \
;         acc[ai][bj][m][n] = __builtin_amdgcn_mfma_f32_16x16x32_bf16(Bt[n][k], At[m][k], acc[ai][bj][m][n], 0, 0, 0); __builtin_amdgcn_s_setprio(0); } while (0)
; #define PG8_WAIT_V(n) asm volatile("s_waitcnt vmcnt(" #n ")" ::: "memory")
; #define PG8_WAIT_L(n) asm volatile("s_waitcnt lgkmcnt(" #n ")" ::: "memory")
; #define PG8_BAR __builtin_amdgcn_s_barrier()
; #define PG8_SCHED __builtin_amdgcn_sched_barrier(0)
; template <class Epi, class Sched, bool ALIGN_EPI = false, bool SP2 = false>
; __device__ __forceinline__ void gemm_phase(PG8_LAS unsigned char* lds, const Gemm g, const Sched& S, const Epi& E) {
;     ...
;             if constexpr (SP2) {
;             PG8_LDB(B0, 0, 0); PG8_LDB(B1, 0, 1); PG8_SCHED; PG8_LDA(At, 0, 0); PG8_STAGE(PG8_SA(1, 1), a1 + hstep, voffA);
;             PG8_WAIT_V(8); PG8_WAIT_L(0); PG8_BAR; PG8_MMA(0, 0, At, B0); PG8_MMA(0, 1, At, B1); PG8_BAR; PG8_SCHED;
;             PG8_LDA(At, 0, 1); PG8_STAGE(PG8_SB(0, 0), b2, voffB); PG8_STAGE(PG8_SB(0, 1), b2 + hstep, voffB); PG8_STAGE(PG8_SA(0, 0), a2, voffA);
;             PG8_WAIT_V(8); PG8_WAIT_L(0); PG8_BAR; PG8_MMA(1, 0, At, B0); PG8_MMA(1, 1, At, B1); PG8_BAR; PG8_SCHED;
	s_waitcnt lgkmcnt(0)
	v_mfma_f32_16x16x32_bf16 v[124:127], v[128:131], v[160:163], v[124:127]
	v_mfma_f32_16x16x32_bf16 v[120:123], v[136:139], v[160:163], v[120:123]
	v_mfma_f32_16x16x32_bf16 v[108:111], v[128:131], v[168:171], v[108:111]
	v_mfma_f32_16x16x32_bf16 v[104:107], v[136:139], v[168:171], v[104:107]
	v_mfma_f32_16x16x32_bf16 v[96:99], v[128:131], v[176:179], v[96:99]
	v_mfma_f32_16x16x32_bf16 v[88:91], v[136:139], v[176:179], v[88:91]
	v_mfma_f32_16x16x32_bf16 v[80:83], v[128:131], v[196:199], v[80:83]
	v_mfma_f32_16x16x32_bf16 v[72:75], v[136:139], v[196:199], v[72:75]
	v_mfma_f32_16x16x32_bf16 v[124:127], v[132:135], v[164:167], v[124:127]
	v_mfma_f32_16x16x32_bf16 v[120:123], v[140:143], v[164:167], v[120:123]
	v_mfma_f32_16x16x32_bf16 v[108:111], v[132:135], v[172:175], v[108:111]
	v_mfma_f32_16x16x32_bf16 v[104:107], v[140:143], v[172:175], v[104:107]
	v_mfma_f32_16x16x32_bf16 v[96:99], v[132:135], v[180:183], v[96:99]
	v_mfma_f32_16x16x32_bf16 v[88:91], v[140:143], v[180:183], v[88:91]
	v_mfma_f32_16x16x32_bf16 v[80:83], v[132:135], v[200:203], v[80:83]
	v_mfma_f32_16x16x32_bf16 v[72:75], v[140:143], v[200:203], v[72:75]
	v_mfma_f32_16x16x32_bf16 v[116:119], v[144:147], v[160:163], v[116:119]
	v_mfma_f32_16x16x32_bf16 v[112:115], v[152:155], v[160:163], v[112:115]
	v_mfma_f32_16x16x32_bf16 v[100:103], v[144:147], v[168:171], v[100:103]
	v_mfma_f32_16x16x32_bf16 v[92:95], v[152:155], v[168:171], v[92:95]
	v_mfma_f32_16x16x32_bf16 v[84:87], v[144:147], v[176:179], v[84:87]
	v_mfma_f32_16x16x32_bf16 v[76:79], v[152:155], v[176:179], v[76:79]
	v_mfma_f32_16x16x32_bf16 v[68:71], v[144:147], v[196:199], v[68:71]
	v_mfma_f32_16x16x32_bf16 v[64:67], v[152:155], v[196:199], v[64:67]
	v_mfma_f32_16x16x32_bf16 v[116:119], v[148:151], v[164:167], v[116:119]
	v_mfma_f32_16x16x32_bf16 v[112:115], v[156:159], v[164:167], v[112:115]
	v_mfma_f32_16x16x32_bf16 v[100:103], v[148:151], v[172:175], v[100:103]
	v_mfma_f32_16x16x32_bf16 v[92:95], v[156:159], v[172:175], v[92:95]
	v_mfma_f32_16x16x32_bf16 v[84:87], v[148:151], v[180:183], v[84:87]
	v_mfma_f32_16x16x32_bf16 v[76:79], v[156:159], v[180:183], v[76:79]
	v_mfma_f32_16x16x32_bf16 v[68:71], v[148:151], v[200:203], v[68:71]
	v_mfma_f32_16x16x32_bf16 v[64:67], v[156:159], v[200:203], v[64:67]
	s_barrier
	s_add_i32 s76, s76, s42
	v_lshl_add_u64 v[186:187], s[24:25], 0, v[184:185]
	s_mov_b32 m0, s76
	ds_read_b128 v[160:163], v228 offset:16384
	ds_read_b128 v[164:167], v228 offset:17408
	ds_read_b128 v[168:171], v228 offset:18432
	ds_read_b128 v[172:175], v228 offset:19456
	ds_read_b128 v[176:179], v228 offset:20480
	ds_read_b128 v[180:183], v228 offset:21504
	ds_read_b128 v[196:199], v228 offset:22528
	ds_read_b128 v[200:203], v228 offset:23552
	global_load_lds_dwordx4 v[186:187], off
	s_add_i32 m0, s76, 0x2000
	s_add_u32 s76, s24, 0x20000
	v_lshl_add_u64 v[188:189], s[24:25], 0, v[190:191]
	s_addc_u32 s77, s25, 0
	s_add_i32 s78, s78, s42
	global_load_lds_dwordx4 v[188:189], off
	v_lshl_add_u64 v[204:205], s[76:77], 0, v[184:185]
	s_mov_b32 m0, s78
	v_lshl_add_u64 v[206:207], s[36:37], 0, v[190:191]
	global_load_lds_dwordx4 v[204:205], off
	v_lshl_add_u64 v[204:205], s[76:77], 0, v[190:191]
	s_add_i32 m0, s78, 0x2000
	s_nop 0
	global_load_lds_dwordx4 v[204:205], off
	v_lshl_add_u64 v[204:205], s[36:37], 0, v[184:185]
	s_mov_b32 m0, s43
	s_nop 0
	global_load_lds_dwordx4 v[204:205], off
	s_mov_b32 m0, s44
	s_nop 0
	global_load_lds_dwordx4 v[206:207], off
	s_waitcnt vmcnt(8)
	s_waitcnt lgkmcnt(0)
	s_barrier
	s_waitcnt lgkmcnt(0)
	v_mfma_f32_16x16x32_bf16 v[60:63], v[128:131], v[160:163], v[60:63]
	v_mfma_f32_16x16x32_bf16 v[56:59], v[136:139], v[160:163], v[56:59]
	v_mfma_f32_16x16x32_bf16 v[48:51], v[128:131], v[168:171], v[48:51]
	v_mfma_f32_16x16x32_bf16 v[40:43], v[136:139], v[168:171], v[40:43]
	v_mfma_f32_16x16x32_bf16 v[32:35], v[128:131], v[176:179], v[32:35]
	v_mfma_f32_16x16x32_bf16 v[24:27], v[136:139], v[176:179], v[24:27]
	v_mfma_f32_16x16x32_bf16 v[16:19], v[128:131], v[196:199], v[16:19]
	v_mfma_f32_16x16x32_bf16 v[8:11], v[136:139], v[196:199], v[8:11]
	v_mfma_f32_16x16x32_bf16 v[60:63], v[132:135], v[164:167], v[60:63]
	v_mfma_f32_16x16x32_bf16 v[56:59], v[140:143], v[164:167], v[56:59]
	v_mfma_f32_16x16x32_bf16 v[48:51], v[132:135], v[172:175], v[48:51]
	v_mfma_f32_16x16x32_bf16 v[40:43], v[140:143], v[172:175], v[40:43]
	v_mfma_f32_16x16x32_bf16 v[32:35], v[132:135], v[180:183], v[32:35]
	v_mfma_f32_16x16x32_bf16 v[24:27], v[140:143], v[180:183], v[24:27]
	v_mfma_f32_16x16x32_bf16 v[16:19], v[132:135], v[200:203], v[16:19]
	v_mfma_f32_16x16x32_bf16 v[8:11], v[140:143], v[200:203], v[8:11]
	v_mfma_f32_16x16x32_bf16 v[52:55], v[144:147], v[160:163], v[52:55]
	v_mfma_f32_16x16x32_bf16 v[44:47], v[152:155], v[160:163], v[44:47]
	v_mfma_f32_16x16x32_bf16 v[36:39], v[144:147], v[168:171], v[36:39]
	v_mfma_f32_16x16x32_bf16 v[28:31], v[152:155], v[168:171], v[28:31]
	v_mfma_f32_16x16x32_bf16 v[20:23], v[144:147], v[176:179], v[20:23]
	v_mfma_f32_16x16x32_bf16 v[12:15], v[152:155], v[176:179], v[12:15]
	v_mfma_f32_16x16x32_bf16 v[4:7], v[144:147], v[196:199], v[4:7]
	v_mfma_f32_16x16x32_bf16 v[0:3], v[152:155], v[196:199], v[0:3]
	v_mfma_f32_16x16x32_bf16 v[52:55], v[148:151], v[164:167], v[52:55]
	v_mfma_f32_16x16x32_bf16 v[44:47], v[156:159], v[164:167], v[44:47]
	v_mfma_f32_16x16x32_bf16 v[36:39], v[148:151], v[172:175], v[36:39]
	v_mfma_f32_16x16x32_bf16 v[28:31], v[156:159], v[172:175], v[28:31]
	v_mfma_f32_16x16x32_bf16 v[20:23], v[148:151], v[180:183], v[20:23]
	v_mfma_f32_16x16x32_bf16 v[12:15], v[156:159], v[180:183], v[12:15]
	v_mfma_f32_16x16x32_bf16 v[4:7], v[148:151], v[200:203], v[4:7]
	v_mfma_f32_16x16x32_bf16 v[0:3], v[156:159], v[200:203], v[0:3]
	s_barrier
; #define PG8_STAGE(bufoff, gbase, voff) do { _Pragma("unroll") for (int _i = 0; _i < 2; ++_i) \
;         __builtin_amdgcn_global_load_lds((const unsigned*)((const char*)(gbase) + (voff)[_i]), (PG8_LAS unsigned*)(lds + (bufoff) + ldsw + _i * 8192), 16, 0, 0); } while (0)
; #define PG8_LDA(dst, b, h) do { _Pragma("unroll") for (int m = 0; m < 4; ++m) _Pragma("unroll") for (int k = 0; k < 2; ++k) dst[m][k] = *(const PG8_LAS bf16x8*)(lds + PG8_SA(b, h) + aoff + m * 2048 + k * 1024); } while (0)
; #define PG8_LDB(dst, b, h) do { _Pragma("unroll") for (int n = 0; n < 2; ++n) _Pragma("unroll") for (int k = 0; k < 2; ++k) dst[n][k] = *(const PG8_LAS bf16x8*)(lds + PG8_SB(b, h) + boff + n * 2048 + k * 1024); } while (0)
; #define PG8_MMA(ai, bj, At, Bt) do { __builtin_amdgcn_s_setprio(1); _Pragma("unroll") for (int m = 0; m < 4; ++m) _Pragma("unroll") for (int n = 0; n < 2; ++n) _Pragma("unroll") for (int k = 0; k < 2; ++k) \
;         acc[ai][bj][m][n] = __builtin_amdgcn_mfma_f32_16x16x32_bf16(Bt[n][k], At[m][k], acc[ai][bj][m][n], 0, 0, 0); __builtin_amdgcn_s_setprio(0); } while (0)
; #define PG8_WAIT_V(n) asm volatile("s_waitcnt vmcnt(" #n ")" ::: "memory")
; #define PG8_WAIT_L(n) asm volatile("s_waitcnt lgkmcnt(" #n ")" ::: "memory")
; #define PG8_BAR __builtin_amdgcn_s_barrier()
; template <class Epi, class Sched, bool ALIGN_EPI = false, bool SP2 = false>
; __device__ __forceinline__ void gemm_phase(PG8_LAS unsigned char* lds, const Gemm g, const Sched& S, const Epi& E) {
;     ...
;         for (int t = 0; t < nt; t += 2) {
;             const bool last = (t == nt - 2);
;             const char* a1 = cA + (size_t)(t + 1) * kstep;
;             const char* a2 = last ? nA : cA + (size_t)(t + 2) * kstep; const char* b2 = last ? nB : cB + (size_t)(t + 2) * kstep;
;             const char* a3 = a2 + kstep; const char* b3 = b2 + kstep;
;     ...
;             PG8_LDB(B0, 1, 0); PG8_LDB(B1, 1, 1); PG8_SCHED; PG8_LDA(At, 1, 0); PG8_STAGE(PG8_SA(0, 1), a2 + hstep, voffA);
;             PG8_WAIT_V(8); PG8_WAIT_L(0); PG8_BAR; PG8_MMA(0, 0, At, B0); PG8_MMA(0, 1, At, B1); PG8_BAR; PG8_SCHED;
;             PG8_LDA(At, 1, 1); PG8_STAGE(PG8_SB(1, 0), b3, voffB); PG8_STAGE(PG8_SB(1, 1), b3 + hstep, voffB); PG8_STAGE(PG8_SA(1, 0), a3, voffA);
;             PG8_WAIT_V(8); PG8_WAIT_L(0); PG8_BAR; PG8_MMA(1, 0, At, B0); PG8_MMA(1, 1, At, B1); PG8_BAR; PG8_SCHED;
	s_add_i32 s76, 0, 0x18000
	s_add_i32 s77, 0, 0x1c000
	v_add_u32_e32 v140, s76, v224
	v_add_u32_e32 v156, s77, v224
	ds_read_b128 v[128:131], v140
	ds_read_b128 v[132:135], v140 offset:1024
	ds_read_b128 v[136:139], v140 offset:2048
	ds_read_b128 v[140:143], v140 offset:3072
	ds_read_b128 v[144:147], v156
	ds_read_b128 v[148:151], v156 offset:1024
	ds_read_b128 v[152:155], v156 offset:2048
	ds_read_b128 v[156:159], v156 offset:3072
	s_add_u32 s36, s36, 0x20000
	s_addc_u32 s37, s37, 0
	s_mov_b32 m0, s45
	v_lshl_add_u64 v[208:209], s[36:37], 0, v[184:185]
	ds_read_b128 v[160:163], v228 offset:32768
	ds_read_b128 v[164:167], v228 offset:33792
	ds_read_b128 v[168:171], v228 offset:34816
	ds_read_b128 v[172:175], v228 offset:35840
	ds_read_b128 v[176:179], v228 offset:36864
	ds_read_b128 v[180:183], v228 offset:37888
	ds_read_b128 v[196:199], v228 offset:38912
	ds_read_b128 v[200:203], v228 offset:39936
	global_load_lds_dwordx4 v[208:209], off
	v_lshl_add_u64 v[208:209], s[36:37], 0, v[190:191]
	s_mov_b32 m0, s46
	s_nop 0
	global_load_lds_dwordx4 v[208:209], off
	s_waitcnt vmcnt(8)
	s_waitcnt lgkmcnt(0)
	s_barrier
	s_waitcnt lgkmcnt(0)
	v_mfma_f32_16x16x32_bf16 v[124:127], v[128:131], v[160:163], v[124:127]
	v_mfma_f32_16x16x32_bf16 v[120:123], v[136:139], v[160:163], v[120:123]
	v_mfma_f32_16x16x32_bf16 v[108:111], v[128:131], v[168:171], v[108:111]
	v_mfma_f32_16x16x32_bf16 v[104:107], v[136:139], v[168:171], v[104:107]
	v_mfma_f32_16x16x32_bf16 v[96:99], v[128:131], v[176:179], v[96:99]
	v_mfma_f32_16x16x32_bf16 v[88:91], v[136:139], v[176:179], v[88:91]
	v_mfma_f32_16x16x32_bf16 v[80:83], v[128:131], v[196:199], v[80:83]
	v_mfma_f32_16x16x32_bf16 v[72:75], v[136:139], v[196:199], v[72:75]
	v_mfma_f32_16x16x32_bf16 v[124:127], v[132:135], v[164:167], v[124:127]
	v_mfma_f32_16x16x32_bf16 v[120:123], v[140:143], v[164:167], v[120:123]
	v_mfma_f32_16x16x32_bf16 v[108:111], v[132:135], v[172:175], v[108:111]
	v_mfma_f32_16x16x32_bf16 v[104:107], v[140:143], v[172:175], v[104:107]
	v_mfma_f32_16x16x32_bf16 v[96:99], v[132:135], v[180:183], v[96:99]
	v_mfma_f32_16x16x32_bf16 v[88:91], v[140:143], v[180:183], v[88:91]
	v_mfma_f32_16x16x32_bf16 v[80:83], v[132:135], v[200:203], v[80:83]
	v_mfma_f32_16x16x32_bf16 v[72:75], v[140:143], v[200:203], v[72:75]
	v_mfma_f32_16x16x32_bf16 v[116:119], v[144:147], v[160:163], v[116:119]
	v_mfma_f32_16x16x32_bf16 v[112:115], v[152:155], v[160:163], v[112:115]
	v_mfma_f32_16x16x32_bf16 v[100:103], v[144:147], v[168:171], v[100:103]
	v_mfma_f32_16x16x32_bf16 v[92:95], v[152:155], v[168:171], v[92:95]
	v_mfma_f32_16x16x32_bf16 v[84:87], v[144:147], v[176:179], v[84:87]
	v_mfma_f32_16x16x32_bf16 v[76:79], v[152:155], v[176:179], v[76:79]
	v_mfma_f32_16x16x32_bf16 v[68:71], v[144:147], v[196:199], v[68:71]
	v_mfma_f32_16x16x32_bf16 v[64:67], v[152:155], v[196:199], v[64:67]
	v_mfma_f32_16x16x32_bf16 v[116:119], v[148:151], v[164:167], v[116:119]
	v_mfma_f32_16x16x32_bf16 v[112:115], v[156:159], v[164:167], v[112:115]
	v_mfma_f32_16x16x32_bf16 v[100:103], v[148:151], v[172:175], v[100:103]
	v_mfma_f32_16x16x32_bf16 v[92:95], v[156:159], v[172:175], v[92:95]
	v_mfma_f32_16x16x32_bf16 v[84:87], v[148:151], v[180:183], v[84:87]
	v_mfma_f32_16x16x32_bf16 v[76:79], v[156:159], v[180:183], v[76:79]
	v_mfma_f32_16x16x32_bf16 v[68:71], v[148:151], v[200:203], v[68:71]
	v_mfma_f32_16x16x32_bf16 v[64:67], v[156:159], v[200:203], v[64:67]
	s_barrier
	s_add_i32 s36, s76, s42
	v_lshl_add_u64 v[186:187], v[186:187], 0, s[30:31]
	s_mov_b32 m0, s36
	ds_read_b128 v[160:163], v228 offset:49152
	ds_read_b128 v[164:167], v228 offset:50176
	ds_read_b128 v[168:171], v228 offset:51200
	ds_read_b128 v[172:175], v228 offset:52224
	ds_read_b128 v[176:179], v228 offset:53248
	ds_read_b128 v[180:183], v228 offset:54272
	ds_read_b128 v[196:199], v228 offset:55296
	ds_read_b128 v[200:203], v228 offset:56320
	global_load_lds_dwordx4 v[186:187], off
	s_add_i32 m0, s36, 0x2000
	s_add_u32 s24, s24, 0x20080
	v_lshl_add_u64 v[186:187], v[188:189], 0, s[30:31]
	s_addc_u32 s25, s25, 0
	s_add_i32 s36, s77, s42
	global_load_lds_dwordx4 v[186:187], off
	v_lshl_add_u64 v[186:187], s[24:25], 0, v[184:185]
	s_mov_b32 m0, s36
	s_nop 0
	global_load_lds_dwordx4 v[186:187], off
	v_lshl_add_u64 v[186:187], s[24:25], 0, v[190:191]
	s_add_i32 m0, s36, 0x2000
	s_nop 0
	global_load_lds_dwordx4 v[186:187], off
	v_lshl_add_u64 v[186:187], v[204:205], 0, s[30:31]
	s_mov_b32 m0, s47
	s_nop 0
	global_load_lds_dwordx4 v[186:187], off
	v_lshl_add_u64 v[186:187], v[206:207], 0, s[30:31]
	s_mov_b32 m0, s48
	s_nop 0
	global_load_lds_dwordx4 v[186:187], off
	s_waitcnt vmcnt(8)
	s_waitcnt lgkmcnt(0)
	s_barrier
	s_waitcnt lgkmcnt(0)
	v_mfma_f32_16x16x32_bf16 v[60:63], v[128:131], v[160:163], v[60:63]
	v_mfma_f32_16x16x32_bf16 v[56:59], v[136:139], v[160:163], v[56:59]
	v_mfma_f32_16x16x32_bf16 v[48:51], v[128:131], v[168:171], v[48:51]
	v_mfma_f32_16x16x32_bf16 v[40:43], v[136:139], v[168:171], v[40:43]
	v_mfma_f32_16x16x32_bf16 v[32:35], v[128:131], v[176:179], v[32:35]
	v_mfma_f32_16x16x32_bf16 v[24:27], v[136:139], v[176:179], v[24:27]
	v_mfma_f32_16x16x32_bf16 v[16:19], v[128:131], v[196:199], v[16:19]
	v_mfma_f32_16x16x32_bf16 v[8:11], v[136:139], v[196:199], v[8:11]
	v_mfma_f32_16x16x32_bf16 v[60:63], v[132:135], v[164:167], v[60:63]
	v_mfma_f32_16x16x32_bf16 v[56:59], v[140:143], v[164:167], v[56:59]
	v_mfma_f32_16x16x32_bf16 v[48:51], v[132:135], v[172:175], v[48:51]
	v_mfma_f32_16x16x32_bf16 v[40:43], v[140:143], v[172:175], v[40:43]
	v_mfma_f32_16x16x32_bf16 v[32:35], v[132:135], v[180:183], v[32:35]
	v_mfma_f32_16x16x32_bf16 v[24:27], v[140:143], v[180:183], v[24:27]
	v_mfma_f32_16x16x32_bf16 v[16:19], v[132:135], v[200:203], v[16:19]
	v_mfma_f32_16x16x32_bf16 v[8:11], v[140:143], v[200:203], v[8:11]
	v_mfma_f32_16x16x32_bf16 v[52:55], v[144:147], v[160:163], v[52:55]
	v_mfma_f32_16x16x32_bf16 v[44:47], v[152:155], v[160:163], v[44:47]
	v_mfma_f32_16x16x32_bf16 v[36:39], v[144:147], v[168:171], v[36:39]
	v_mfma_f32_16x16x32_bf16 v[28:31], v[152:155], v[168:171], v[28:31]
	v_mfma_f32_16x16x32_bf16 v[20:23], v[144:147], v[176:179], v[20:23]
	v_mfma_f32_16x16x32_bf16 v[12:15], v[152:155], v[176:179], v[12:15]
	v_mfma_f32_16x16x32_bf16 v[4:7], v[144:147], v[196:199], v[4:7]
	v_mfma_f32_16x16x32_bf16 v[0:3], v[152:155], v[196:199], v[0:3]
	v_mfma_f32_16x16x32_bf16 v[52:55], v[148:151], v[164:167], v[52:55]
	v_mfma_f32_16x16x32_bf16 v[44:47], v[156:159], v[164:167], v[44:47]
	v_mfma_f32_16x16x32_bf16 v[36:39], v[148:151], v[172:175], v[36:39]
	v_mfma_f32_16x16x32_bf16 v[28:31], v[156:159], v[172:175], v[28:31]
	v_mfma_f32_16x16x32_bf16 v[20:23], v[148:151], v[180:183], v[20:23]
	v_mfma_f32_16x16x32_bf16 v[12:15], v[156:159], v[180:183], v[12:15]
	v_mfma_f32_16x16x32_bf16 v[4:7], v[148:151], v[200:203], v[4:7]
	v_mfma_f32_16x16x32_bf16 v[0:3], v[156:159], v[200:203], v[0:3]
	s_barrier
	s_add_i32 s73, s73, 2
	s_add_u32 s22, s22, 0x100
	s_addc_u32 s23, s23, 0
	s_add_u32 s71, s71, 0x100
	s_addc_u32 s72, s72, 0
	s_cmp_gt_u32 s73, 5
	s_cbranch_scc0 .LBB0_395

;     __host__ __device__ bool next(int i, Unit& u) const { Unit m; if (!S.next(i >> 1, m)) return false; u.pm = m.pm; u.pn = m.pn + 4 * (i & 1); return true; }
;     __host__ __device__ bool next(int i, Unit& u) const { Unit m; if (!S.next(i >> 1, m)) return false; u.pm = m.pm + (i & 1) * dpm; u.pn = m.pn + (i & 1) * dpn; return true; }
; #define PG8_STAGE(bufoff, gbase, voff) do { _Pragma("unroll") for (int _i = 0; _i < 2; ++_i) \
;         __builtin_amdgcn_global_load_lds((const unsigned*)((const char*)(gbase) + (voff)[_i]), (PG8_LAS unsigned*)(lds + (bufoff) + ldsw + _i * 8192), 16, 0, 0); } while (0)
; #define PG8_LDA(dst, b, h) do { _Pragma("unroll") for (int m = 0; m < 4; ++m) _Pragma("unroll") for (int k = 0; k < 2; ++k) dst[m][k] = *(const PG8_LAS bf16x8*)(lds + PG8_SA(b, h) + aoff + m * 2048 + k * 1024); } while (0)
; #define PG8_LDB(dst, b, h) do { _Pragma("unroll") for (int n = 0; n < 2; ++n) _Pragma("unroll") for (int k = 0; k < 2; ++k) dst[n][k] = *(const PG8_LAS bf16x8*)(lds + PG8_SB(b, h) + boff + n * 2048 + k * 1024); } while (0)
; #define PG8_WAIT_V(n) asm volatile("s_waitcnt vmcnt(" #n ")" ::: "memory")
; template <class Epi, class Sched, bool ALIGN_EPI = false, bool SP2 = false>
; __device__ __forceinline__ void gemm_phase(PG8_LAS unsigned char* lds, const Gemm g, const Sched& S, const Epi& E) {
;     ...
;         const bool has_next = S.next(ui + 1, nxt);
;         const char* nA = has_next ? (const char*)g.A + (size_t)nxt.pm * tstep : cA; const char* nB = has_next ? (const char*)g.Bt + (size_t)nxt.pn * tstep : cB;
;         for (int t = 0; t < nt; t += 2) {
;             const bool last = (t == nt - 2);
;             const char* a1 = cA + (size_t)(t + 1) * kstep;
;             const char* a2 = last ? nA : cA + (size_t)(t + 2) * kstep; const char* b2 = last ? nB : cB + (size_t)(t + 2) * kstep;
;             const char* a3 = a2 + kstep; const char* b3 = b2 + kstep;
;             if (last && has_next) S.a_ready(nxt);
;             if constexpr (SP2) {
;             PG8_LDB(B0, 0, 0); PG8_LDB(B1, 0, 1); PG8_SCHED; PG8_LDA(At, 0, 0); PG8_STAGE(PG8_SA(1, 1), a1 + hstep, voffA);
;             PG8_WAIT_V(8); PG8_WAIT_L(0); PG8_BAR; PG8_MMA(0, 0, At, B0); PG8_MMA(0, 1, At, B1); PG8_BAR; PG8_SCHED;
;             PG8_LDA(At, 0, 1); PG8_STAGE(PG8_SB(0, 0), b2, voffB); PG8_STAGE(PG8_SB(0, 1), b2 + hstep, voffB); PG8_STAGE(PG8_SA(0, 0), a2, voffA);
.LBB0_455:
	s_ashr_i32 s15, s14, 31
	s_lshl_b64 s[16:17], s[14:15], 19
	s_add_u32 s16, s74, s16
	s_addc_u32 s17, s75, s17
	s_and_b64 s[18:19], s[4:5], exec
	s_cselect_b32 s15, s17, s21
	s_cselect_b32 s69, s16, s20
	s_ashr_i32 s13, s12, 31
	s_lshl_b64 s[18:19], s[12:13], 19
	s_add_u32 s18, s28, s18
	s_addc_u32 s19, s29, s19
	s_and_b64 s[24:25], s[4:5], exec
	s_cselect_b32 s13, s19, s73
	s_cselect_b32 s70, s18, s72
	s_add_u32 s20, s20, 0x40080
	s_addc_u32 s21, s21, 0
	s_add_u32 s71, s72, 0x100
	s_addc_u32 s72, s73, 0
	s_mov_b32 s73, -2
	v_cmp_lt_u32_e32 vcc, 0xff, v212
	s_cbranch_vccz .Lgprio3
	s_setprio 1
.Lgprio3:
	s_add_u32 s22, s20, 0xfffc0080
	s_addc_u32 s23, s21, -1
	s_add_i32 s76, 0, 0x10000
	s_cmp_eq_u32 s73, 12
	s_cselect_b32 s25, s15, s23
	s_cselect_b32 s24, s69, s22
	s_cselect_b32 s23, s13, s72
	s_cselect_b32 s22, s70, s71
	s_add_i32 s78, 0, 0x14000
	v_add_u32_e32 v140, s76, v158
	v_add_u32_e32 v154, s78, v158
	ds_read_b128 v[128:131], v140
	ds_read_b128 v[132:135], v140 offset:1024
	ds_read_b128 v[136:139], v140 offset:2048
	ds_read_b128 v[140:143], v140 offset:3072
	ds_read_b128 v[150:153], v154
	ds_read_b128 v[162:165], v154 offset:1024
	ds_read_b128 v[166:169], v154 offset:2048
	ds_read_b128 v[170:173], v154 offset:3072
	v_lshl_add_u64 v[154:155], s[20:21], 0, v[146:147]
	s_add_i32 m0, s37, 0xc000
	ds_read_b128 v[174:177], v160
	ds_read_b128 v[178:181], v160 offset:1024
	ds_read_b128 v[190:193], v160 offset:2048
	ds_read_b128 v[194:197], v160 offset:3072
	ds_read_b128 v[198:201], v160 offset:4096
	ds_read_b128 v[202:205], v160 offset:5120
	ds_read_b128 v[206:209], v160 offset:6144
	ds_read_b128 v[222:225], v160 offset:7168
	global_load_lds_dwordx4 v[154:155], off
	v_lshl_add_u64 v[154:155], s[20:21], 0, v[148:149]
	s_add_i32 m0, s37, 0xe000
	s_nop 0
	global_load_lds_dwordx4 v[154:155], off
	s_waitcnt vmcnt(8)
	s_waitcnt lgkmcnt(0)
	s_barrier
	s_waitcnt lgkmcnt(0)
	v_mfma_f32_16x16x32_bf16 v[124:127], v[128:131], v[174:177], 0
	v_mfma_f32_16x16x32_bf16 v[120:123], v[136:139], v[174:177], 0
	v_mfma_f32_16x16x32_bf16 v[116:119], v[128:131], v[190:193], 0
	v_mfma_f32_16x16x32_bf16 v[112:115], v[136:139], v[190:193], 0
	v_mfma_f32_16x16x32_bf16 v[100:103], v[128:131], v[198:201], 0
	v_mfma_f32_16x16x32_bf16 v[88:91], v[136:139], v[198:201], 0
	v_mfma_f32_16x16x32_bf16 v[80:83], v[128:131], v[206:209], 0
	v_mfma_f32_16x16x32_bf16 v[72:75], v[136:139], v[206:209], 0
	v_mfma_f32_16x16x32_bf16 v[124:127], v[132:135], v[178:181], v[124:127]
	v_mfma_f32_16x16x32_bf16 v[120:123], v[140:143], v[178:181], v[120:123]
	v_mfma_f32_16x16x32_bf16 v[116:119], v[132:135], v[194:197], v[116:119]
	v_mfma_f32_16x16x32_bf16 v[112:115], v[140:143], v[194:197], v[112:115]
	v_mfma_f32_16x16x32_bf16 v[100:103], v[132:135], v[202:205], v[100:103]
	v_mfma_f32_16x16x32_bf16 v[88:91], v[140:143], v[202:205], v[88:91]
	v_mfma_f32_16x16x32_bf16 v[80:83], v[132:135], v[222:225], v[80:83]
	v_mfma_f32_16x16x32_bf16 v[72:75], v[140:143], v[222:225], v[72:75]
	v_mfma_f32_16x16x32_bf16 v[108:111], v[150:153], v[174:177], 0
	v_mfma_f32_16x16x32_bf16 v[104:107], v[166:169], v[174:177], 0
	v_mfma_f32_16x16x32_bf16 v[96:99], v[150:153], v[190:193], 0
	v_mfma_f32_16x16x32_bf16 v[92:95], v[166:169], v[190:193], 0
	v_mfma_f32_16x16x32_bf16 v[84:87], v[150:153], v[198:201], 0
	v_mfma_f32_16x16x32_bf16 v[76:79], v[166:169], v[198:201], 0
	v_mfma_f32_16x16x32_bf16 v[68:71], v[150:153], v[206:209], 0
	v_mfma_f32_16x16x32_bf16 v[64:67], v[166:169], v[206:209], 0
	v_mfma_f32_16x16x32_bf16 v[108:111], v[162:165], v[178:181], v[108:111]
	v_mfma_f32_16x16x32_bf16 v[104:107], v[170:173], v[178:181], v[104:107]
	v_mfma_f32_16x16x32_bf16 v[96:99], v[162:165], v[194:197], v[96:99]
	v_mfma_f32_16x16x32_bf16 v[92:95], v[170:173], v[194:197], v[92:95]
	v_mfma_f32_16x16x32_bf16 v[84:87], v[162:165], v[202:205], v[84:87]
	v_mfma_f32_16x16x32_bf16 v[76:79], v[170:173], v[202:205], v[76:79]
	v_mfma_f32_16x16x32_bf16 v[68:71], v[162:165], v[222:225], v[68:71]
	v_mfma_f32_16x16x32_bf16 v[64:67], v[170:173], v[222:225], v[64:67]
	s_barrier
	s_add_i32 s76, s76, s36
	v_lshl_add_u64 v[154:155], s[22:23], 0, v[184:185]
	s_mov_b32 m0, s76
	ds_read_b128 v[174:177], v160 offset:16384
	ds_read_b128 v[178:181], v160 offset:17408
	ds_read_b128 v[190:193], v160 offset:18432
	ds_read_b128 v[194:197], v160 offset:19456
	ds_read_b128 v[198:201], v160 offset:20480
	ds_read_b128 v[202:205], v160 offset:21504
	ds_read_b128 v[206:209], v160 offset:22528
	ds_read_b128 v[222:225], v160 offset:23552
	global_load_lds_dwordx4 v[154:155], off
	s_add_i32 m0, s76, 0x2000
	s_add_u32 s76, s22, 0x40000
	v_lshl_add_u64 v[182:183], s[22:23], 0, v[144:145]
	s_addc_u32 s77, s23, 0
	s_add_i32 s78, s78, s36
	global_load_lds_dwordx4 v[182:183], off
	v_lshl_add_u64 v[186:187], s[76:77], 0, v[184:185]
	s_mov_b32 m0, s78
	v_lshl_add_u64 v[188:189], s[24:25], 0, v[144:145]
	global_load_lds_dwordx4 v[186:187], off
	v_lshl_add_u64 v[186:187], s[76:77], 0, v[144:145]
	s_add_i32 m0, s78, 0x2000
	s_nop 0
	global_load_lds_dwordx4 v[186:187], off
	v_lshl_add_u64 v[186:187], s[24:25], 0, v[184:185]
	s_mov_b32 m0, s37
	s_nop 0
	global_load_lds_dwordx4 v[186:187], off
	s_mov_b32 m0, s42
	s_nop 0
	global_load_lds_dwordx4 v[188:189], off
	s_waitcnt vmcnt(8)
	s_waitcnt lgkmcnt(0)
	s_barrier
; #define PG8_STAGE(bufoff, gbase, voff) do { _Pragma("unroll") for (int _i = 0; _i < 2; ++_i) \
;         __builtin_amdgcn_global_load_lds((const unsigned*)((const char*)(gbase) + (voff)[_i]), (PG8_LAS unsigned*)(lds + (bufoff) + ldsw + _i * 8192), 16, 0, 0); } while (0)
; #define PG8_LDA(dst, b, h) do { _Pragma("unroll") for (int m = 0; m < 4; ++m) _Pragma("unroll") for (int k = 0; k < 2; ++k) dst[m][k] = *(const PG8_LAS bf16x8*)(lds + PG8_SA(b, h) + aoff + m * 2048 + k * 1024); } while (0)
; #define PG8_LDB(dst, b, h) do { _Pragma("unroll") for (int n = 0; n < 2; ++n) _Pragma("unroll") for (int k = 0; k < 2; ++k) dst[n][k] = *(const PG8_LAS bf16x8*)(lds + PG8_SB(b, h) + boff + n * 2048 + k * 1024); } while (0)
; #define PG8_MMA(ai, bj, At, Bt) do { __builtin_amdgcn_s_setprio(1); _Pragma("unroll") for (int m = 0; m < 4; ++m) _Pragma("unroll") for (int n = 0; n < 2; ++n) _Pragma("unroll") for (int k = 0; k < 2; ++k) \
;         acc[ai][bj][m][n] = __builtin_amdgcn_mfma_f32_16x16x32_bf16(Bt[n][k], At[m][k], acc[ai][bj][m][n], 0, 0, 0); __builtin_amdgcn_s_setprio(0); } while (0)
; #define PG8_WAIT_V(n) asm volatile("s_waitcnt vmcnt(" #n ")" ::: "memory")
; #define PG8_WAIT_L(n) asm volatile("s_waitcnt lgkmcnt(" #n ")" ::: "memory")
; #define PG8_BAR __builtin_amdgcn_s_barrier()
; #define PG8_SCHED __builtin_amdgcn_sched_barrier(0)
; template <class Epi, class Sched, bool ALIGN_EPI = false, bool SP2 = false>
; __device__ __forceinline__ void gemm_phase(PG8_LAS unsigned char* lds, const Gemm g, const Sched& S, const Epi& E) {
;     ...
;             PG8_WAIT_V(8); PG8_WAIT_L(0); PG8_BAR; PG8_MMA(0, 0, At, B0); PG8_MMA(0, 1, At, B1); PG8_BAR; PG8_SCHED;
;             PG8_LDA(At, 0, 1); PG8_STAGE(PG8_SB(0, 0), b2, voffB); PG8_STAGE(PG8_SB(0, 1), b2 + hstep, voffB); PG8_STAGE(PG8_SA(0, 0), a2, voffA);
;             PG8_WAIT_V(8); PG8_WAIT_L(0); PG8_BAR; PG8_MMA(1, 0, At, B0); PG8_MMA(1, 1, At, B1); PG8_BAR; PG8_SCHED;
;             PG8_LDB(B0, 1, 0); PG8_LDB(B1, 1, 1); PG8_SCHED; PG8_LDA(At, 1, 0); PG8_STAGE(PG8_SA(0, 1), a2 + hstep, voffA);
;             PG8_WAIT_V(8); PG8_WAIT_L(0); PG8_BAR; PG8_MMA(0, 0, At, B0); PG8_MMA(0, 1, At, B1); PG8_BAR; PG8_SCHED;
	s_waitcnt lgkmcnt(0)
	v_mfma_f32_16x16x32_bf16 v[60:63], v[128:131], v[174:177], 0
	v_mfma_f32_16x16x32_bf16 v[56:59], v[136:139], v[174:177], 0
	v_mfma_f32_16x16x32_bf16 v[48:51], v[128:131], v[190:193], 0
	v_mfma_f32_16x16x32_bf16 v[40:43], v[136:139], v[190:193], 0
	v_mfma_f32_16x16x32_bf16 v[32:35], v[128:131], v[198:201], 0
	v_mfma_f32_16x16x32_bf16 v[24:27], v[136:139], v[198:201], 0
	v_mfma_f32_16x16x32_bf16 v[16:19], v[128:131], v[206:209], 0
	v_mfma_f32_16x16x32_bf16 v[8:11], v[136:139], v[206:209], 0
	v_mfma_f32_16x16x32_bf16 v[60:63], v[132:135], v[178:181], v[60:63]
	v_mfma_f32_16x16x32_bf16 v[56:59], v[140:143], v[178:181], v[56:59]
	v_mfma_f32_16x16x32_bf16 v[48:51], v[132:135], v[194:197], v[48:51]
	v_mfma_f32_16x16x32_bf16 v[40:43], v[140:143], v[194:197], v[40:43]
	v_mfma_f32_16x16x32_bf16 v[32:35], v[132:135], v[202:205], v[32:35]
	v_mfma_f32_16x16x32_bf16 v[24:27], v[140:143], v[202:205], v[24:27]
	v_mfma_f32_16x16x32_bf16 v[16:19], v[132:135], v[222:225], v[16:19]
	v_mfma_f32_16x16x32_bf16 v[8:11], v[140:143], v[222:225], v[8:11]
	v_mfma_f32_16x16x32_bf16 v[52:55], v[150:153], v[174:177], 0
	v_mfma_f32_16x16x32_bf16 v[44:47], v[166:169], v[174:177], 0
	v_mfma_f32_16x16x32_bf16 v[36:39], v[150:153], v[190:193], 0
	v_mfma_f32_16x16x32_bf16 v[28:31], v[166:169], v[190:193], 0
	v_mfma_f32_16x16x32_bf16 v[20:23], v[150:153], v[198:201], 0
	v_mfma_f32_16x16x32_bf16 v[12:15], v[166:169], v[198:201], 0
	v_mfma_f32_16x16x32_bf16 v[4:7], v[150:153], v[206:209], 0
	v_mfma_f32_16x16x32_bf16 v[0:3], v[166:169], v[206:209], 0
	v_mfma_f32_16x16x32_bf16 v[52:55], v[162:165], v[178:181], v[52:55]
	v_mfma_f32_16x16x32_bf16 v[44:47], v[170:173], v[178:181], v[44:47]
	v_mfma_f32_16x16x32_bf16 v[36:39], v[162:165], v[194:197], v[36:39]
	v_mfma_f32_16x16x32_bf16 v[28:31], v[170:173], v[194:197], v[28:31]
	v_mfma_f32_16x16x32_bf16 v[20:23], v[162:165], v[202:205], v[20:23]
	v_mfma_f32_16x16x32_bf16 v[12:15], v[170:173], v[202:205], v[12:15]
	v_mfma_f32_16x16x32_bf16 v[4:7], v[162:165], v[222:225], v[4:7]
	v_mfma_f32_16x16x32_bf16 v[0:3], v[170:173], v[222:225], v[0:3]
	s_barrier
	s_add_i32 s76, 0, 0x18000
	s_add_i32 s77, 0, 0x1c000
	v_add_u32_e32 v140, s76, v158
	v_add_u32_e32 v161, s77, v158
	ds_read_b128 v[128:131], v140
	ds_read_b128 v[132:135], v140 offset:1024
	ds_read_b128 v[136:139], v140 offset:2048
	ds_read_b128 v[140:143], v140 offset:3072
	ds_read_b128 v[150:153], v161
	ds_read_b128 v[162:165], v161 offset:1024
	ds_read_b128 v[166:169], v161 offset:2048
	ds_read_b128 v[170:173], v161 offset:3072
	s_add_u32 s24, s24, 0x40000
	s_addc_u32 s25, s25, 0
	s_mov_b32 m0, s43
	v_lshl_add_u64 v[210:211], s[24:25], 0, v[184:185]
	ds_read_b128 v[174:177], v160 offset:32768
	ds_read_b128 v[178:181], v160 offset:33792
	ds_read_b128 v[190:193], v160 offset:34816
	ds_read_b128 v[194:197], v160 offset:35840
	ds_read_b128 v[198:201], v160 offset:36864
	ds_read_b128 v[202:205], v160 offset:37888
	ds_read_b128 v[206:209], v160 offset:38912
	ds_read_b128 v[222:225], v160 offset:39936
	global_load_lds_dwordx4 v[210:211], off
	v_lshl_add_u64 v[210:211], s[24:25], 0, v[144:145]
	s_mov_b32 m0, s44
	s_nop 0
	global_load_lds_dwordx4 v[210:211], off
	s_waitcnt vmcnt(8)
	s_waitcnt lgkmcnt(0)
	s_barrier
	s_waitcnt lgkmcnt(0)
	v_mfma_f32_16x16x32_bf16 v[124:127], v[128:131], v[174:177], v[124:127]
	v_mfma_f32_16x16x32_bf16 v[120:123], v[136:139], v[174:177], v[120:123]
	v_mfma_f32_16x16x32_bf16 v[116:119], v[128:131], v[190:193], v[116:119]
	v_mfma_f32_16x16x32_bf16 v[112:115], v[136:139], v[190:193], v[112:115]
	v_mfma_f32_16x16x32_bf16 v[100:103], v[128:131], v[198:201], v[100:103]
	v_mfma_f32_16x16x32_bf16 v[88:91], v[136:139], v[198:201], v[88:91]
	v_mfma_f32_16x16x32_bf16 v[80:83], v[128:131], v[206:209], v[80:83]
	v_mfma_f32_16x16x32_bf16 v[72:75], v[136:139], v[206:209], v[72:75]
	v_mfma_f32_16x16x32_bf16 v[124:127], v[132:135], v[178:181], v[124:127]
	v_mfma_f32_16x16x32_bf16 v[120:123], v[140:143], v[178:181], v[120:123]
	v_mfma_f32_16x16x32_bf16 v[116:119], v[132:135], v[194:197], v[116:119]
	v_mfma_f32_16x16x32_bf16 v[112:115], v[140:143], v[194:197], v[112:115]
	v_mfma_f32_16x16x32_bf16 v[100:103], v[132:135], v[202:205], v[100:103]
	v_mfma_f32_16x16x32_bf16 v[88:91], v[140:143], v[202:205], v[88:91]
	v_mfma_f32_16x16x32_bf16 v[80:83], v[132:135], v[222:225], v[80:83]
	v_mfma_f32_16x16x32_bf16 v[72:75], v[140:143], v[222:225], v[72:75]
	v_mfma_f32_16x16x32_bf16 v[108:111], v[150:153], v[174:177], v[108:111]
	v_mfma_f32_16x16x32_bf16 v[104:107], v[166:169], v[174:177], v[104:107]
	v_mfma_f32_16x16x32_bf16 v[96:99], v[150:153], v[190:193], v[96:99]
	v_mfma_f32_16x16x32_bf16 v[92:95], v[166:169], v[190:193], v[92:95]
	v_mfma_f32_16x16x32_bf16 v[84:87], v[150:153], v[198:201], v[84:87]
	v_mfma_f32_16x16x32_bf16 v[76:79], v[166:169], v[198:201], v[76:79]
	v_mfma_f32_16x16x32_bf16 v[68:71], v[150:153], v[206:209], v[68:71]
	v_mfma_f32_16x16x32_bf16 v[64:67], v[166:169], v[206:209], v[64:67]
	v_mfma_f32_16x16x32_bf16 v[108:111], v[162:165], v[178:181], v[108:111]
	v_mfma_f32_16x16x32_bf16 v[104:107], v[170:173], v[178:181], v[104:107]
	v_mfma_f32_16x16x32_bf16 v[96:99], v[162:165], v[194:197], v[96:99]
	v_mfma_f32_16x16x32_bf16 v[92:95], v[170:173], v[194:197], v[92:95]
	v_mfma_f32_16x16x32_bf16 v[84:87], v[162:165], v[202:205], v[84:87]
	v_mfma_f32_16x16x32_bf16 v[76:79], v[170:173], v[202:205], v[76:79]
	v_mfma_f32_16x16x32_bf16 v[68:71], v[162:165], v[222:225], v[68:71]
	v_mfma_f32_16x16x32_bf16 v[64:67], v[170:173], v[222:225], v[64:67]
	s_barrier
; #define PG8_STAGE(bufoff, gbase, voff) do { _Pragma("unroll") for (int _i = 0; _i < 2; ++_i) \
;         __builtin_amdgcn_global_load_lds((const unsigned*)((const char*)(gbase) + (voff)[_i]), (PG8_LAS unsigned*)(lds + (bufoff) + ldsw + _i * 8192), 16, 0, 0); } while (0)
; #define PG8_LDA(dst, b, h) do { _Pragma("unroll") for (int m = 0; m < 4; ++m) _Pragma("unroll") for (int k = 0; k < 2; ++k) dst[m][k] = *(const PG8_LAS bf16x8*)(lds + PG8_SA(b, h) + aoff + m * 2048 + k * 1024); } while (0)
; #define PG8_LDB(dst, b, h) do { _Pragma("unroll") for (int n = 0; n < 2; ++n) _Pragma("unroll") for (int k = 0; k < 2; ++k) dst[n][k] = *(const PG8_LAS bf16x8*)(lds + PG8_SB(b, h) + boff + n * 2048 + k * 1024); } while (0)
; #define PG8_MMA(ai, bj, At, Bt) do { __builtin_amdgcn_s_setprio(1); _Pragma("unroll") for (int m = 0; m < 4; ++m) _Pragma("unroll") for (int n = 0; n < 2; ++n) _Pragma("unroll") for (int k = 0; k < 2; ++k) \
;         acc[ai][bj][m][n] = __builtin_amdgcn_mfma_f32_16x16x32_bf16(Bt[n][k], At[m][k], acc[ai][bj][m][n], 0, 0, 0); __builtin_amdgcn_s_setprio(0); } while (0)
; #define PG8_WAIT_V(n) asm volatile("s_waitcnt vmcnt(" #n ")" ::: "memory")
; #define PG8_WAIT_L(n) asm volatile("s_waitcnt lgkmcnt(" #n ")" ::: "memory")
; #define PG8_BAR __builtin_amdgcn_s_barrier()
; #define PG8_SCHED __builtin_amdgcn_sched_barrier(0)
; template <class Epi, class Sched, bool ALIGN_EPI = false, bool SP2 = false>
; __device__ __forceinline__ void gemm_phase(PG8_LAS unsigned char* lds, const Gemm g, const Sched& S, const Epi& E) {
;     ...
;             PG8_LDB(B0, 0, 0); PG8_LDB(B1, 0, 1); PG8_SCHED; PG8_LDA(At, 0, 0); PG8_STAGE(PG8_SA(1, 1), a1 + hstep, voffA);
;             PG8_WAIT_V(8); PG8_WAIT_L(0); PG8_BAR; PG8_MMA(0, 0, At, B0); PG8_MMA(0, 1, At, B1); PG8_BAR; PG8_SCHED;
;     ...
;             PG8_LDB(B0, 1, 0); PG8_LDB(B1, 1, 1); PG8_SCHED; PG8_LDA(At, 1, 0); PG8_STAGE(PG8_SA(0, 1), a2 + hstep, voffA);
;             PG8_WAIT_V(8); PG8_WAIT_L(0); PG8_BAR; PG8_MMA(0, 0, At, B0); PG8_MMA(0, 1, At, B1); PG8_BAR; PG8_SCHED;
;             PG8_LDA(At, 1, 1); PG8_STAGE(PG8_SB(1, 0), b3, voffB); PG8_STAGE(PG8_SB(1, 1), b3 + hstep, voffB); PG8_STAGE(PG8_SA(1, 0), a3, voffA);
;             PG8_WAIT_V(8); PG8_WAIT_L(0); PG8_BAR; PG8_MMA(1, 0, At, B0); PG8_MMA(1, 1, At, B1); PG8_BAR; PG8_SCHED;
	s_add_i32 s24, s76, s36
	v_lshl_add_u64 v[154:155], v[154:155], 0, s[30:31]
	s_mov_b32 m0, s24
	ds_read_b128 v[174:177], v160 offset:49152
	ds_read_b128 v[178:181], v160 offset:50176
	ds_read_b128 v[190:193], v160 offset:51200
	ds_read_b128 v[194:197], v160 offset:52224
	ds_read_b128 v[198:201], v160 offset:53248
	ds_read_b128 v[202:205], v160 offset:54272
	ds_read_b128 v[206:209], v160 offset:55296
	ds_read_b128 v[222:225], v160 offset:56320
	global_load_lds_dwordx4 v[154:155], off
	s_add_i32 m0, s24, 0x2000
	s_add_u32 s22, s22, 0x40080
	v_lshl_add_u64 v[154:155], v[182:183], 0, s[30:31]
	s_addc_u32 s23, s23, 0
	s_add_i32 s24, s77, s36
	global_load_lds_dwordx4 v[154:155], off
	v_lshl_add_u64 v[154:155], s[22:23], 0, v[184:185]
	s_mov_b32 m0, s24
	s_nop 0
	global_load_lds_dwordx4 v[154:155], off
	v_lshl_add_u64 v[154:155], s[22:23], 0, v[144:145]
	s_add_i32 m0, s24, 0x2000
	s_nop 0
	global_load_lds_dwordx4 v[154:155], off
	v_lshl_add_u64 v[154:155], v[186:187], 0, s[30:31]
	s_mov_b32 m0, s47
	s_nop 0
	global_load_lds_dwordx4 v[154:155], off
	v_lshl_add_u64 v[154:155], v[188:189], 0, s[30:31]
	s_mov_b32 m0, s48
	s_nop 0
	global_load_lds_dwordx4 v[154:155], off
	s_waitcnt vmcnt(8)
	s_waitcnt lgkmcnt(0)
	s_barrier
	s_waitcnt lgkmcnt(0)
	v_mfma_f32_16x16x32_bf16 v[60:63], v[128:131], v[174:177], v[60:63]
	v_mfma_f32_16x16x32_bf16 v[56:59], v[136:139], v[174:177], v[56:59]
	v_mfma_f32_16x16x32_bf16 v[48:51], v[128:131], v[190:193], v[48:51]
	v_mfma_f32_16x16x32_bf16 v[40:43], v[136:139], v[190:193], v[40:43]
	v_mfma_f32_16x16x32_bf16 v[32:35], v[128:131], v[198:201], v[32:35]
	v_mfma_f32_16x16x32_bf16 v[24:27], v[136:139], v[198:201], v[24:27]
	v_mfma_f32_16x16x32_bf16 v[16:19], v[128:131], v[206:209], v[16:19]
	v_mfma_f32_16x16x32_bf16 v[8:11], v[136:139], v[206:209], v[8:11]
	v_mfma_f32_16x16x32_bf16 v[60:63], v[132:135], v[178:181], v[60:63]
	v_mfma_f32_16x16x32_bf16 v[56:59], v[140:143], v[178:181], v[56:59]
	v_mfma_f32_16x16x32_bf16 v[48:51], v[132:135], v[194:197], v[48:51]
	v_mfma_f32_16x16x32_bf16 v[40:43], v[140:143], v[194:197], v[40:43]
	v_mfma_f32_16x16x32_bf16 v[32:35], v[132:135], v[202:205], v[32:35]
	v_mfma_f32_16x16x32_bf16 v[24:27], v[140:143], v[202:205], v[24:27]
	v_mfma_f32_16x16x32_bf16 v[16:19], v[132:135], v[222:225], v[16:19]
	v_mfma_f32_16x16x32_bf16 v[8:11], v[140:143], v[222:225], v[8:11]
	v_mfma_f32_16x16x32_bf16 v[52:55], v[150:153], v[174:177], v[52:55]
	v_mfma_f32_16x16x32_bf16 v[44:47], v[166:169], v[174:177], v[44:47]
	v_mfma_f32_16x16x32_bf16 v[36:39], v[150:153], v[190:193], v[36:39]
	v_mfma_f32_16x16x32_bf16 v[28:31], v[166:169], v[190:193], v[28:31]
	v_mfma_f32_16x16x32_bf16 v[20:23], v[150:153], v[198:201], v[20:23]
	v_mfma_f32_16x16x32_bf16 v[12:15], v[166:169], v[198:201], v[12:15]
	v_mfma_f32_16x16x32_bf16 v[4:7], v[150:153], v[206:209], v[4:7]
	v_mfma_f32_16x16x32_bf16 v[0:3], v[166:169], v[206:209], v[0:3]
	v_mfma_f32_16x16x32_bf16 v[52:55], v[162:165], v[178:181], v[52:55]
	v_mfma_f32_16x16x32_bf16 v[44:47], v[170:173], v[178:181], v[44:47]
	v_mfma_f32_16x16x32_bf16 v[36:39], v[162:165], v[194:197], v[36:39]
	v_mfma_f32_16x16x32_bf16 v[28:31], v[170:173], v[194:197], v[28:31]
	v_mfma_f32_16x16x32_bf16 v[20:23], v[162:165], v[202:205], v[20:23]
	v_mfma_f32_16x16x32_bf16 v[12:15], v[170:173], v[202:205], v[12:15]
	v_mfma_f32_16x16x32_bf16 v[4:7], v[162:165], v[222:225], v[4:7]
	v_mfma_f32_16x16x32_bf16 v[0:3], v[170:173], v[222:225], v[0:3]
	s_barrier
	s_add_i32 s73, s73, 2
	s_add_u32 s20, s20, 0x100
	s_addc_u32 s21, s21, 0
	s_add_u32 s71, s71, 0x100
	s_addc_u32 s72, s72, 0
	s_cmp_gt_u32 s73, 13
	s_cbranch_scc0 .LBB0_456
	s_branch .Lgzero3_done
.LBB0_456:
	s_add_u32 s22, s20, 0xfffc0080
	s_addc_u32 s23, s21, -1
	s_add_i32 s76, 0, 0x10000
	s_cmp_eq_u32 s73, 12
	s_cselect_b32 s25, s15, s23
	s_cselect_b32 s24, s69, s22
	s_cselect_b32 s23, s13, s72
	s_cselect_b32 s22, s70, s71
	s_add_i32 s78, 0, 0x14000
	v_add_u32_e32 v140, s76, v158
	v_add_u32_e32 v154, s78, v158
	ds_read_b128 v[128:131], v140
	ds_read_b128 v[132:135], v140 offset:1024
	ds_read_b128 v[136:139], v140 offset:2048
	ds_read_b128 v[140:143], v140 offset:3072
	ds_read_b128 v[150:153], v154
	ds_read_b128 v[162:165], v154 offset:1024
	ds_read_b128 v[166:169], v154 offset:2048
	ds_read_b128 v[170:173], v154 offset:3072
	v_lshl_add_u64 v[154:155], s[20:21], 0, v[146:147]
	s_add_i32 m0, s37, 0xc000
	ds_read_b128 v[174:177], v160
	ds_read_b128 v[178:181], v160 offset:1024
	ds_read_b128 v[190:193], v160 offset:2048
	ds_read_b128 v[194:197], v160 offset:3072
	ds_read_b128 v[198:201], v160 offset:4096
	ds_read_b128 v[202:205], v160 offset:5120
	ds_read_b128 v[206:209], v160 offset:6144
	ds_read_b128 v[222:225], v160 offset:7168
	global_load_lds_dwordx4 v[154:155], off
	v_lshl_add_u64 v[154:155], s[20:21], 0, v[148:149]
	s_add_i32 m0, s37, 0xe000
	s_nop 0
	global_load_lds_dwordx4 v[154:155], off
	s_waitcnt vmcnt(8)
	s_waitcnt lgkmcnt(0)
	s_barrier
; #define PG8_STAGE(bufoff, gbase, voff) do { _Pragma("unroll") for (int _i = 0; _i < 2; ++_i) \
;         __builtin_amdgcn_global_load_lds((const unsigned*)((const char*)(gbase) + (voff)[_i]), (PG8_LAS unsigned*)(lds + (bufoff) + ldsw + _i * 8192), 16, 0, 0); } while (0)
; #define PG8_LDA(dst, b, h) do { _Pragma("unroll") for (int m = 0; m < 4; ++m) _Pragma("unroll") for (int k = 0; k < 2; ++k) dst[m][k] = *(const PG8_LAS bf16x8*)(lds + PG8_SA(b, h) + aoff + m * 2048 + k * 1024); } while (0)
; #define PG8_LDB(dst, b, h) do { _Pragma("unroll") for (int n = 0; n < 2; ++n) _Pragma("unroll") for (int k = 0; k < 2; ++k) dst[n][k] = *(const PG8_LAS bf16x8*)(lds + PG8_SB(b, h) + boff + n * 2048 + k * 1024); } while (0)
; #define PG8_MMA(ai, bj, At, Bt) do { __builtin_amdgcn_s_setprio(1); _Pragma("unroll") for (int m = 0; m < 4; ++m) _Pragma("unroll") for (int n = 0; n < 2; ++n) _Pragma("unroll") for (int k = 0; k < 2; ++k) \
;         acc[ai][bj][m][n] = __builtin_amdgcn_mfma_f32_16x16x32_bf16(Bt[n][k], At[m][k], acc[ai][bj][m][n], 0, 0, 0); __builtin_amdgcn_s_setprio(0); } while (0)
; #define PG8_WAIT_V(n) asm volatile("s_waitcnt vmcnt(" #n ")" ::: "memory")
; #define PG8_WAIT_L(n) asm volatile("s_waitcnt lgkmcnt(" #n ")" ::: "memory")
; #define PG8_BAR __builtin_amdgcn_s_barrier()
; #define PG8_SCHED __builtin_amdgcn_sched_barrier(0)
; template <class Epi, class Sched, bool ALIGN_EPI = false, bool SP2 = false>
; __device__ __forceinline__ void gemm_phase(PG8_LAS unsigned char* lds, const Gemm g, const Sched& S, const Epi& E) {
;     ...
;             PG8_LDB(B0, 0, 0); PG8_LDB(B1, 0, 1); PG8_SCHED; PG8_LDA(At, 0, 0); PG8_STAGE(PG8_SA(1, 1), a1 + hstep, voffA);
;             PG8_WAIT_V(8); PG8_WAIT_L(0); PG8_BAR; PG8_MMA(0, 0, At, B0); PG8_MMA(0, 1, At, B1); PG8_BAR; PG8_SCHED;
;             PG8_LDA(At, 0, 1); PG8_STAGE(PG8_SB(0, 0), b2, voffB); PG8_STAGE(PG8_SB(0, 1), b2 + hstep, voffB); PG8_STAGE(PG8_SA(0, 0), a2, voffA);
;             PG8_WAIT_V(8); PG8_WAIT_L(0); PG8_BAR; PG8_MMA(1, 0, At, B0); PG8_MMA(1, 1, At, B1); PG8_BAR; PG8_SCHED;
;             PG8_LDB(B0, 1, 0); PG8_LDB(B1, 1, 1); PG8_SCHED; PG8_LDA(At, 1, 0); PG8_STAGE(PG8_SA(0, 1), a2 + hstep, voffA);
;             PG8_WAIT_V(8); PG8_WAIT_L(0); PG8_BAR; PG8_MMA(0, 0, At, B0); PG8_MMA(0, 1, At, B1); PG8_BAR; PG8_SCHED;
	s_waitcnt lgkmcnt(0)
	v_mfma_f32_16x16x32_bf16 v[124:127], v[128:131], v[174:177], v[124:127]
	v_mfma_f32_16x16x32_bf16 v[120:123], v[136:139], v[174:177], v[120:123]
	v_mfma_f32_16x16x32_bf16 v[116:119], v[128:131], v[190:193], v[116:119]
	v_mfma_f32_16x16x32_bf16 v[112:115], v[136:139], v[190:193], v[112:115]
	v_mfma_f32_16x16x32_bf16 v[100:103], v[128:131], v[198:201], v[100:103]
	v_mfma_f32_16x16x32_bf16 v[88:91], v[136:139], v[198:201], v[88:91]
	v_mfma_f32_16x16x32_bf16 v[80:83], v[128:131], v[206:209], v[80:83]
	v_mfma_f32_16x16x32_bf16 v[72:75], v[136:139], v[206:209], v[72:75]
	v_mfma_f32_16x16x32_bf16 v[124:127], v[132:135], v[178:181], v[124:127]
	v_mfma_f32_16x16x32_bf16 v[120:123], v[140:143], v[178:181], v[120:123]
	v_mfma_f32_16x16x32_bf16 v[116:119], v[132:135], v[194:197], v[116:119]
	v_mfma_f32_16x16x32_bf16 v[112:115], v[140:143], v[194:197], v[112:115]
	v_mfma_f32_16x16x32_bf16 v[100:103], v[132:135], v[202:205], v[100:103]
	v_mfma_f32_16x16x32_bf16 v[88:91], v[140:143], v[202:205], v[88:91]
	v_mfma_f32_16x16x32_bf16 v[80:83], v[132:135], v[222:225], v[80:83]
	v_mfma_f32_16x16x32_bf16 v[72:75], v[140:143], v[222:225], v[72:75]
	v_mfma_f32_16x16x32_bf16 v[108:111], v[150:153], v[174:177], v[108:111]
	v_mfma_f32_16x16x32_bf16 v[104:107], v[166:169], v[174:177], v[104:107]
	v_mfma_f32_16x16x32_bf16 v[96:99], v[150:153], v[190:193], v[96:99]
	v_mfma_f32_16x16x32_bf16 v[92:95], v[166:169], v[190:193], v[92:95]
	v_mfma_f32_16x16x32_bf16 v[84:87], v[150:153], v[198:201], v[84:87]
	v_mfma_f32_16x16x32_bf16 v[76:79], v[166:169], v[198:201], v[76:79]
	v_mfma_f32_16x16x32_bf16 v[68:71], v[150:153], v[206:209], v[68:71]
	v_mfma_f32_16x16x32_bf16 v[64:67], v[166:169], v[206:209], v[64:67]
	v_mfma_f32_16x16x32_bf16 v[108:111], v[162:165], v[178:181], v[108:111]
	v_mfma_f32_16x16x32_bf16 v[104:107], v[170:173], v[178:181], v[104:107]
	v_mfma_f32_16x16x32_bf16 v[96:99], v[162:165], v[194:197], v[96:99]
	v_mfma_f32_16x16x32_bf16 v[92:95], v[170:173], v[194:197], v[92:95]
	v_mfma_f32_16x16x32_bf16 v[84:87], v[162:165], v[202:205], v[84:87]
	v_mfma_f32_16x16x32_bf16 v[76:79], v[170:173], v[202:205], v[76:79]
	v_mfma_f32_16x16x32_bf16 v[68:71], v[162:165], v[222:225], v[68:71]
	v_mfma_f32_16x16x32_bf16 v[64:67], v[170:173], v[222:225], v[64:67]
	s_barrier
	s_add_i32 s76, s76, s36
	v_lshl_add_u64 v[154:155], s[22:23], 0, v[184:185]
	s_mov_b32 m0, s76
	ds_read_b128 v[174:177], v160 offset:16384
	ds_read_b128 v[178:181], v160 offset:17408
	ds_read_b128 v[190:193], v160 offset:18432
	ds_read_b128 v[194:197], v160 offset:19456
	ds_read_b128 v[198:201], v160 offset:20480
	ds_read_b128 v[202:205], v160 offset:21504
	ds_read_b128 v[206:209], v160 offset:22528
	ds_read_b128 v[222:225], v160 offset:23552
	global_load_lds_dwordx4 v[154:155], off
	s_add_i32 m0, s76, 0x2000
	s_add_u32 s76, s22, 0x40000
	v_lshl_add_u64 v[182:183], s[22:23], 0, v[144:145]
	s_addc_u32 s77, s23, 0
	s_add_i32 s78, s78, s36
	global_load_lds_dwordx4 v[182:183], off
	v_lshl_add_u64 v[186:187], s[76:77], 0, v[184:185]
	s_mov_b32 m0, s78
	v_lshl_add_u64 v[188:189], s[24:25], 0, v[144:145]
	global_load_lds_dwordx4 v[186:187], off
	v_lshl_add_u64 v[186:187], s[76:77], 0, v[144:145]
	s_add_i32 m0, s78, 0x2000
	s_nop 0
	global_load_lds_dwordx4 v[186:187], off
	v_lshl_add_u64 v[186:187], s[24:25], 0, v[184:185]
	s_mov_b32 m0, s37
	s_nop 0
	global_load_lds_dwordx4 v[186:187], off
	s_mov_b32 m0, s42
	s_nop 0
	global_load_lds_dwordx4 v[188:189], off
	s_waitcnt vmcnt(8)
	s_waitcnt lgkmcnt(0)
	s_barrier
	s_waitcnt lgkmcnt(0)
	v_mfma_f32_16x16x32_bf16 v[60:63], v[128:131], v[174:177], v[60:63]
	v_mfma_f32_16x16x32_bf16 v[56:59], v[136:139], v[174:177], v[56:59]
	v_mfma_f32_16x16x32_bf16 v[48:51], v[128:131], v[190:193], v[48:51]
	v_mfma_f32_16x16x32_bf16 v[40:43], v[136:139], v[190:193], v[40:43]
	v_mfma_f32_16x16x32_bf16 v[32:35], v[128:131], v[198:201], v[32:35]
	v_mfma_f32_16x16x32_bf16 v[24:27], v[136:139], v[198:201], v[24:27]
	v_mfma_f32_16x16x32_bf16 v[16:19], v[128:131], v[206:209], v[16:19]
	v_mfma_f32_16x16x32_bf16 v[8:11], v[136:139], v[206:209], v[8:11]
	v_mfma_f32_16x16x32_bf16 v[60:63], v[132:135], v[178:181], v[60:63]
	v_mfma_f32_16x16x32_bf16 v[56:59], v[140:143], v[178:181], v[56:59]
	v_mfma_f32_16x16x32_bf16 v[48:51], v[132:135], v[194:197], v[48:51]
	v_mfma_f32_16x16x32_bf16 v[40:43], v[140:143], v[194:197], v[40:43]
	v_mfma_f32_16x16x32_bf16 v[32:35], v[132:135], v[202:205], v[32:35]
	v_mfma_f32_16x16x32_bf16 v[24:27], v[140:143], v[202:205], v[24:27]
	v_mfma_f32_16x16x32_bf16 v[16:19], v[132:135], v[222:225], v[16:19]
	v_mfma_f32_16x16x32_bf16 v[8:11], v[140:143], v[222:225], v[8:11]
	v_mfma_f32_16x16x32_bf16 v[52:55], v[150:153], v[174:177], v[52:55]
	v_mfma_f32_16x16x32_bf16 v[44:47], v[166:169], v[174:177], v[44:47]
	v_mfma_f32_16x16x32_bf16 v[36:39], v[150:153], v[190:193], v[36:39]
	v_mfma_f32_16x16x32_bf16 v[28:31], v[166:169], v[190:193], v[28:31]
	v_mfma_f32_16x16x32_bf16 v[20:23], v[150:153], v[198:201], v[20:23]
	v_mfma_f32_16x16x32_bf16 v[12:15], v[166:169], v[198:201], v[12:15]
	v_mfma_f32_16x16x32_bf16 v[4:7], v[150:153], v[206:209], v[4:7]
	v_mfma_f32_16x16x32_bf16 v[0:3], v[166:169], v[206:209], v[0:3]
	v_mfma_f32_16x16x32_bf16 v[52:55], v[162:165], v[178:181], v[52:55]
	v_mfma_f32_16x16x32_bf16 v[44:47], v[170:173], v[178:181], v[44:47]
	v_mfma_f32_16x16x32_bf16 v[36:39], v[162:165], v[194:197], v[36:39]
	v_mfma_f32_16x16x32_bf16 v[28:31], v[170:173], v[194:197], v[28:31]
	v_mfma_f32_16x16x32_bf16 v[20:23], v[162:165], v[202:205], v[20:23]
	v_mfma_f32_16x16x32_bf16 v[12:15], v[170:173], v[202:205], v[12:15]
	v_mfma_f32_16x16x32_bf16 v[4:7], v[162:165], v[222:225], v[4:7]
	v_mfma_f32_16x16x32_bf16 v[0:3], v[170:173], v[222:225], v[0:3]
	s_barrier
; #define PG8_STAGE(bufoff, gbase, voff) do { _Pragma("unroll") for (int _i = 0; _i < 2; ++_i) \
;         __builtin_amdgcn_global_load_lds((const unsigned*)((const char*)(gbase) + (voff)[_i]), (PG8_LAS unsigned*)(lds + (bufoff) + ldsw + _i * 8192), 16, 0, 0); } while (0)
; #define PG8_LDA(dst, b, h) do { _Pragma("unroll") for (int m = 0; m < 4; ++m) _Pragma("unroll") for (int k = 0; k < 2; ++k) dst[m][k] = *(const PG8_LAS bf16x8*)(lds + PG8_SA(b, h) + aoff + m * 2048 + k * 1024); } while (0)
; #define PG8_LDB(dst, b, h) do { _Pragma("unroll") for (int n = 0; n < 2; ++n) _Pragma("unroll") for (int k = 0; k < 2; ++k) dst[n][k] = *(const PG8_LAS bf16x8*)(lds + PG8_SB(b, h) + boff + n * 2048 + k * 1024); } while (0)
; #define PG8_MMA(ai, bj, At, Bt) do { __builtin_amdgcn_s_setprio(1); _Pragma("unroll") for (int m = 0; m < 4; ++m) _Pragma("unroll") for (int n = 0; n < 2; ++n) _Pragma("unroll") for (int k = 0; k < 2; ++k) \
;         acc[ai][bj][m][n] = __builtin_amdgcn_mfma_f32_16x16x32_bf16(Bt[n][k], At[m][k], acc[ai][bj][m][n], 0, 0, 0); __builtin_amdgcn_s_setprio(0); } while (0)
; #define PG8_WAIT_V(n) asm volatile("s_waitcnt vmcnt(" #n ")" ::: "memory")
; #define PG8_WAIT_L(n) asm volatile("s_waitcnt lgkmcnt(" #n ")" ::: "memory")
; #define PG8_BAR __builtin_amdgcn_s_barrier()
; template <class Epi, class Sched, bool ALIGN_EPI = false, bool SP2 = false>
; __device__ __forceinline__ void gemm_phase(PG8_LAS unsigned char* lds, const Gemm g, const Sched& S, const Epi& E) {
;     ...
;         for (int t = 0; t < nt; t += 2) {
;             const bool last = (t == nt - 2);
;             const char* a1 = cA + (size_t)(t + 1) * kstep;
;             const char* a2 = last ? nA : cA + (size_t)(t + 2) * kstep; const char* b2 = last ? nB : cB + (size_t)(t + 2) * kstep;
;             const char* a3 = a2 + kstep; const char* b3 = b2 + kstep;
;     ...
;             PG8_LDB(B0, 1, 0); PG8_LDB(B1, 1, 1); PG8_SCHED; PG8_LDA(At, 1, 0); PG8_STAGE(PG8_SA(0, 1), a2 + hstep, voffA);
;             PG8_WAIT_V(8); PG8_WAIT_L(0); PG8_BAR; PG8_MMA(0, 0, At, B0); PG8_MMA(0, 1, At, B1); PG8_BAR; PG8_SCHED;
;             PG8_LDA(At, 1, 1); PG8_STAGE(PG8_SB(1, 0), b3, voffB); PG8_STAGE(PG8_SB(1, 1), b3 + hstep, voffB); PG8_STAGE(PG8_SA(1, 0), a3, voffA);
;             PG8_WAIT_V(8); PG8_WAIT_L(0); PG8_BAR; PG8_MMA(1, 0, At, B0); PG8_MMA(1, 1, At, B1); PG8_BAR; PG8_SCHED;
	s_add_i32 s76, 0, 0x18000
	s_add_i32 s77, 0, 0x1c000
	v_add_u32_e32 v140, s76, v158
	v_add_u32_e32 v161, s77, v158
	ds_read_b128 v[128:131], v140
	ds_read_b128 v[132:135], v140 offset:1024
	ds_read_b128 v[136:139], v140 offset:2048
	ds_read_b128 v[140:143], v140 offset:3072
	ds_read_b128 v[150:153], v161
	ds_read_b128 v[162:165], v161 offset:1024
	ds_read_b128 v[166:169], v161 offset:2048
	ds_read_b128 v[170:173], v161 offset:3072
	s_add_u32 s24, s24, 0x40000
	s_addc_u32 s25, s25, 0
	s_mov_b32 m0, s43
	v_lshl_add_u64 v[210:211], s[24:25], 0, v[184:185]
	ds_read_b128 v[174:177], v160 offset:32768
	ds_read_b128 v[178:181], v160 offset:33792
	ds_read_b128 v[190:193], v160 offset:34816
	ds_read_b128 v[194:197], v160 offset:35840
	ds_read_b128 v[198:201], v160 offset:36864
	ds_read_b128 v[202:205], v160 offset:37888
	ds_read_b128 v[206:209], v160 offset:38912
	ds_read_b128 v[222:225], v160 offset:39936
	global_load_lds_dwordx4 v[210:211], off
	v_lshl_add_u64 v[210:211], s[24:25], 0, v[144:145]
	s_mov_b32 m0, s44
	s_nop 0
	global_load_lds_dwordx4 v[210:211], off
	s_waitcnt vmcnt(8)
	s_waitcnt lgkmcnt(0)
	s_barrier
	s_waitcnt lgkmcnt(0)
	v_mfma_f32_16x16x32_bf16 v[124:127], v[128:131], v[174:177], v[124:127]
	v_mfma_f32_16x16x32_bf16 v[120:123], v[136:139], v[174:177], v[120:123]
	v_mfma_f32_16x16x32_bf16 v[116:119], v[128:131], v[190:193], v[116:119]
	v_mfma_f32_16x16x32_bf16 v[112:115], v[136:139], v[190:193], v[112:115]
	v_mfma_f32_16x16x32_bf16 v[100:103], v[128:131], v[198:201], v[100:103]
	v_mfma_f32_16x16x32_bf16 v[88:91], v[136:139], v[198:201], v[88:91]
	v_mfma_f32_16x16x32_bf16 v[80:83], v[128:131], v[206:209], v[80:83]
	v_mfma_f32_16x16x32_bf16 v[72:75], v[136:139], v[206:209], v[72:75]
	v_mfma_f32_16x16x32_bf16 v[124:127], v[132:135], v[178:181], v[124:127]
	v_mfma_f32_16x16x32_bf16 v[120:123], v[140:143], v[178:181], v[120:123]
	v_mfma_f32_16x16x32_bf16 v[116:119], v[132:135], v[194:197], v[116:119]
	v_mfma_f32_16x16x32_bf16 v[112:115], v[140:143], v[194:197], v[112:115]
	v_mfma_f32_16x16x32_bf16 v[100:103], v[132:135], v[202:205], v[100:103]
	v_mfma_f32_16x16x32_bf16 v[88:91], v[140:143], v[202:205], v[88:91]
	v_mfma_f32_16x16x32_bf16 v[80:83], v[132:135], v[222:225], v[80:83]
	v_mfma_f32_16x16x32_bf16 v[72:75], v[140:143], v[222:225], v[72:75]
	v_mfma_f32_16x16x32_bf16 v[108:111], v[150:153], v[174:177], v[108:111]
	v_mfma_f32_16x16x32_bf16 v[104:107], v[166:169], v[174:177], v[104:107]
	v_mfma_f32_16x16x32_bf16 v[96:99], v[150:153], v[190:193], v[96:99]
	v_mfma_f32_16x16x32_bf16 v[92:95], v[166:169], v[190:193], v[92:95]
	v_mfma_f32_16x16x32_bf16 v[84:87], v[150:153], v[198:201], v[84:87]
	v_mfma_f32_16x16x32_bf16 v[76:79], v[166:169], v[198:201], v[76:79]
	v_mfma_f32_16x16x32_bf16 v[68:71], v[150:153], v[206:209], v[68:71]
	v_mfma_f32_16x16x32_bf16 v[64:67], v[166:169], v[206:209], v[64:67]
	v_mfma_f32_16x16x32_bf16 v[108:111], v[162:165], v[178:181], v[108:111]
	v_mfma_f32_16x16x32_bf16 v[104:107], v[170:173], v[178:181], v[104:107]
	v_mfma_f32_16x16x32_bf16 v[96:99], v[162:165], v[194:197], v[96:99]
	v_mfma_f32_16x16x32_bf16 v[92:95], v[170:173], v[194:197], v[92:95]
	v_mfma_f32_16x16x32_bf16 v[84:87], v[162:165], v[202:205], v[84:87]
	v_mfma_f32_16x16x32_bf16 v[76:79], v[170:173], v[202:205], v[76:79]
	v_mfma_f32_16x16x32_bf16 v[68:71], v[162:165], v[222:225], v[68:71]
	v_mfma_f32_16x16x32_bf16 v[64:67], v[170:173], v[222:225], v[64:67]
	s_barrier
	s_add_i32 s24, s76, s36
	v_lshl_add_u64 v[154:155], v[154:155], 0, s[30:31]
	s_mov_b32 m0, s24
	ds_read_b128 v[174:177], v160 offset:49152
	ds_read_b128 v[178:181], v160 offset:50176
	ds_read_b128 v[190:193], v160 offset:51200
	ds_read_b128 v[194:197], v160 offset:52224
	ds_read_b128 v[198:201], v160 offset:53248
	ds_read_b128 v[202:205], v160 offset:54272
	ds_read_b128 v[206:209], v160 offset:55296
	ds_read_b128 v[222:225], v160 offset:56320
	global_load_lds_dwordx4 v[154:155], off
	s_add_i32 m0, s24, 0x2000
	s_add_u32 s22, s22, 0x40080
	v_lshl_add_u64 v[154:155], v[182:183], 0, s[30:31]
	s_addc_u32 s23, s23, 0
	s_add_i32 s24, s77, s36
	global_load_lds_dwordx4 v[154:155], off
	v_lshl_add_u64 v[154:155], s[22:23], 0, v[184:185]
	s_mov_b32 m0, s24
	s_nop 0
	global_load_lds_dwordx4 v[154:155], off
	v_lshl_add_u64 v[154:155], s[22:23], 0, v[144:145]
	s_add_i32 m0, s24, 0x2000
	s_nop 0
	global_load_lds_dwordx4 v[154:155], off
	v_lshl_add_u64 v[154:155], v[186:187], 0, s[30:31]
	s_mov_b32 m0, s47
	s_nop 0
	global_load_lds_dwordx4 v[154:155], off
	v_lshl_add_u64 v[154:155], v[188:189], 0, s[30:31]
	s_mov_b32 m0, s48
	s_nop 0
	global_load_lds_dwordx4 v[154:155], off
	s_waitcnt vmcnt(8)
	s_waitcnt lgkmcnt(0)
	s_barrier
	s_waitcnt lgkmcnt(0)
	v_mfma_f32_16x16x32_bf16 v[60:63], v[128:131], v[174:177], v[60:63]
	v_mfma_f32_16x16x32_bf16 v[56:59], v[136:139], v[174:177], v[56:59]
	v_mfma_f32_16x16x32_bf16 v[48:51], v[128:131], v[190:193], v[48:51]
	v_mfma_f32_16x16x32_bf16 v[40:43], v[136:139], v[190:193], v[40:43]
	v_mfma_f32_16x16x32_bf16 v[32:35], v[128:131], v[198:201], v[32:35]
	v_mfma_f32_16x16x32_bf16 v[24:27], v[136:139], v[198:201], v[24:27]
	v_mfma_f32_16x16x32_bf16 v[16:19], v[128:131], v[206:209], v[16:19]
	v_mfma_f32_16x16x32_bf16 v[8:11], v[136:139], v[206:209], v[8:11]
	v_mfma_f32_16x16x32_bf16 v[60:63], v[132:135], v[178:181], v[60:63]
	v_mfma_f32_16x16x32_bf16 v[56:59], v[140:143], v[178:181], v[56:59]
	v_mfma_f32_16x16x32_bf16 v[48:51], v[132:135], v[194:197], v[48:51]
	v_mfma_f32_16x16x32_bf16 v[40:43], v[140:143], v[194:197], v[40:43]
	v_mfma_f32_16x16x32_bf16 v[32:35], v[132:135], v[202:205], v[32:35]
	v_mfma_f32_16x16x32_bf16 v[24:27], v[140:143], v[202:205], v[24:27]
	v_mfma_f32_16x16x32_bf16 v[16:19], v[132:135], v[222:225], v[16:19]
	v_mfma_f32_16x16x32_bf16 v[8:11], v[140:143], v[222:225], v[8:11]
	v_mfma_f32_16x16x32_bf16 v[52:55], v[150:153], v[174:177], v[52:55]
	v_mfma_f32_16x16x32_bf16 v[44:47], v[166:169], v[174:177], v[44:47]
	v_mfma_f32_16x16x32_bf16 v[36:39], v[150:153], v[190:193], v[36:39]
	v_mfma_f32_16x16x32_bf16 v[28:31], v[166:169], v[190:193], v[28:31]
	v_mfma_f32_16x16x32_bf16 v[20:23], v[150:153], v[198:201], v[20:23]
	v_mfma_f32_16x16x32_bf16 v[12:15], v[166:169], v[198:201], v[12:15]
	v_mfma_f32_16x16x32_bf16 v[4:7], v[150:153], v[206:209], v[4:7]
	v_mfma_f32_16x16x32_bf16 v[0:3], v[166:169], v[206:209], v[0:3]
	v_mfma_f32_16x16x32_bf16 v[52:55], v[162:165], v[178:181], v[52:55]
	v_mfma_f32_16x16x32_bf16 v[44:47], v[170:173], v[178:181], v[44:47]
	v_mfma_f32_16x16x32_bf16 v[36:39], v[162:165], v[194:197], v[36:39]
	v_mfma_f32_16x16x32_bf16 v[28:31], v[170:173], v[194:197], v[28:31]
	v_mfma_f32_16x16x32_bf16 v[20:23], v[162:165], v[202:205], v[20:23]
	v_mfma_f32_16x16x32_bf16 v[12:15], v[170:173], v[202:205], v[12:15]
	v_mfma_f32_16x16x32_bf16 v[4:7], v[162:165], v[222:225], v[4:7]
	v_mfma_f32_16x16x32_bf16 v[0:3], v[170:173], v[222:225], v[0:3]
	s_barrier
	s_add_i32 s73, s73, 2
	s_add_u32 s20, s20, 0x100
	s_addc_u32 s21, s21, 0
	s_add_u32 s71, s71, 0x100
	s_addc_u32 s72, s72, 0
	s_cmp_gt_u32 s73, 13
	s_cbranch_scc0 .LBB0_456
; #define PG8_BAR __builtin_amdgcn_s_barrier()
; template <class Epi, class Sched, bool ALIGN_EPI = false, bool SP2 = false>
; __device__ __forceinline__ void gemm_phase(PG8_LAS unsigned char* lds, const Gemm g, const Sched& S, const Epi& E) {
;     ...
;         }
;         if constexpr (ALIGN_EPI) { if (wr == 0) PG8_BAR; }
.Lgzero3_done:
	s_setprio 0
	s_and_b64 vcc, exec, s[10:11]
	s_cbranch_vccz .LBB0_459
	s_barrier
